# EpiResid epilogues: x tile loads issued 5 groups ahead into free fragment registers, counted vmcnt
# baseline (speedup 1.0000x reference)
.LBB11_929:
	v_mov_b32_e32 v148, v158
	v_mov_b32_e32 v130, v160
	s_lshl_b32 s22, s7, 8
	v_mul_f32_e32 v122, 0xbfb8aa3b, v122
	v_add_u32_e32 v150, s22, v148
	v_lshl_add_u32 v130, s6, 7, v130
	v_ashrrev_i32_e32 v151, 31, v150
	v_ashrrev_i32_e32 v131, 31, v130
	v_lshlrev_b64 v[132:133], 11, v[150:151]
	v_lshl_add_u64 v[134:135], s[66:67], 0, v[132:133]
	v_lshlrev_b64 v[152:153], 1, v[130:131]
	v_lshl_add_u64 v[156:157], v[134:135], 0, v[152:153]
	v_lshl_add_u64 v[130:131], s[64:65], 0, v[132:133]
	v_lshl_add_u64 v[154:155], v[130:131], 0, v[152:153]
	v_lshl_add_u32 v249, v150, 11, v152
	global_load_dwordx4 v[170:173], v249, s[66:67]
	global_load_dwordx4 v[174:177], v249, s[64:65]
	v_add_u32_e32 v250, 0x8000, v249
	global_load_dwordx4 v[178:181], v250, s[66:67]
	global_load_dwordx4 v[190:193], v250, s[64:65]
	v_add_u32_e32 v251, 0x10000, v249
	global_load_dwordx4 v[194:197], v251, s[66:67]
	global_load_dwordx4 v[214:217], v251, s[64:65]
	v_add_u32_e32 v250, 0x18000, v249
	global_load_dwordx4 v[218:221], v250, s[66:67]
	global_load_dwordx4 v[222:225], v250, s[64:65]
	v_add_u32_e32 v251, 0x40000, v249
	global_load_dwordx4 v[226:229], v251, s[66:67]
	global_load_dwordx4 v[230:233], v251, s[64:65]
	v_mul_f32_e32 v123, 0xbfb8aa3b, v123
	v_exp_f32_e32 v122, v122
	v_exp_f32_e32 v123, v123
	v_mul_f32_e32 v118, 0xbfb8aa3b, v118
	v_mul_f32_e32 v119, 0xbfb8aa3b, v119
	v_exp_f32_e32 v118, v118
	v_exp_f32_e32 v119, v119
	v_add_f32_e32 v122, 1.0, v122
	v_add_f32_e32 v123, 1.0, v123
	v_rcp_f32_e32 v122, v122
	v_rcp_f32_e32 v123, v123
	v_add_f32_e32 v118, 1.0, v118
	v_add_f32_e32 v119, 1.0, v119
	v_rcp_f32_e32 v118, v118
	v_rcp_f32_e32 v119, v119
	v_mul_f32_e32 v121, 0xbfb8aa3b, v121
	v_exp_f32_e32 v121, v121
	v_mul_f32_e32 v106, 0xbfb8aa3b, v106
	v_mul_f32_e32 v107, 0xbfb8aa3b, v107
	v_exp_f32_e32 v106, v106
	v_add_f32_e32 v121, 1.0, v121
	v_rcp_f32_e32 v121, v121
	v_exp_f32_e32 v107, v107
	v_mul_f32_e32 v102, 0xbfb8aa3b, v102
	v_mul_f32_e32 v103, 0xbfb8aa3b, v103
	v_exp_f32_e32 v102, v102
	v_exp_f32_e32 v103, v103
	v_add_f32_e32 v106, 1.0, v106
	v_add_f32_e32 v107, 1.0, v107
	v_rcp_f32_e32 v106, v106
	v_rcp_f32_e32 v107, v107
	v_add_f32_e32 v102, 1.0, v102
	v_add_f32_e32 v103, 1.0, v103
	v_rcp_f32_e32 v102, v102
	v_rcp_f32_e32 v103, v103
	v_mul_f32_e32 v105, 0xbfb8aa3b, v105
	v_exp_f32_e32 v105, v105
	v_mul_f32_e32 v90, 0xbfb8aa3b, v90
	v_mul_f32_e32 v91, 0xbfb8aa3b, v91
	v_exp_f32_e32 v90, v90
	v_add_f32_e32 v105, 1.0, v105
	v_rcp_f32_e32 v105, v105
	v_exp_f32_e32 v91, v91
	v_mul_f32_e32 v86, 0xbfb8aa3b, v86
	v_mul_f32_e32 v87, 0xbfb8aa3b, v87
	v_exp_f32_e32 v86, v86
	v_exp_f32_e32 v87, v87
	v_add_f32_e32 v90, 1.0, v90
	v_add_f32_e32 v91, 1.0, v91
	v_rcp_f32_e32 v90, v90
	v_rcp_f32_e32 v91, v91
	v_add_f32_e32 v86, 1.0, v86
	v_add_f32_e32 v87, 1.0, v87
	v_rcp_f32_e32 v86, v86
	v_rcp_f32_e32 v87, v87
	v_mul_f32_e32 v89, 0xbfb8aa3b, v89
	v_exp_f32_e32 v89, v89
	v_mul_f32_e32 v74, 0xbfb8aa3b, v74
	v_mul_f32_e32 v75, 0xbfb8aa3b, v75
	v_exp_f32_e32 v74, v74
	v_add_f32_e32 v89, 1.0, v89
	v_rcp_f32_e32 v89, v89
	v_exp_f32_e32 v75, v75
	v_mul_f32_e32 v70, 0xbfb8aa3b, v70
	v_mul_f32_e32 v71, 0xbfb8aa3b, v71
	v_exp_f32_e32 v70, v70
	v_exp_f32_e32 v71, v71
	v_add_f32_e32 v74, 1.0, v74
	v_add_f32_e32 v75, 1.0, v75
	v_rcp_f32_e32 v74, v74
	v_rcp_f32_e32 v75, v75
	v_add_f32_e32 v70, 1.0, v70
	v_add_f32_e32 v71, 1.0, v71
	v_rcp_f32_e32 v70, v70
	v_rcp_f32_e32 v71, v71
	v_mul_f32_e32 v73, 0xbfb8aa3b, v73
	v_exp_f32_e32 v73, v73
	v_mul_f32_e32 v58, 0xbfb8aa3b, v58
	s_waitcnt vmcnt(8)
	v_lshlrev_b32_e32 v162, 16, v170
	v_and_b32_e32 v163, 0xffff0000, v170
	v_lshlrev_b32_e32 v164, 16, v174
	v_and_b32_e32 v165, 0xffff0000, v174
	v_pk_add_f32 v[162:163], v[162:163], v[164:165]
	v_add_f32_e32 v73, 1.0, v73
	v_pk_fma_f32 v[122:123], v[126:127], v[122:123], v[162:163]
	v_lshlrev_b32_e32 v126, 16, v172
	v_and_b32_e32 v127, 0xffff0000, v172
	v_lshlrev_b32_e32 v162, 16, v176
	v_and_b32_e32 v163, 0xffff0000, v176
	v_pk_add_f32 v[126:127], v[126:127], v[162:163]
	v_rcp_f32_e32 v73, v73
	v_pk_fma_f32 v[114:115], v[114:115], v[118:119], v[126:127]
	v_mul_f32_e32 v119, 0xbfb8aa3b, v120
	v_exp_f32_e32 v119, v119
	v_mul_f32_e32 v118, 0xbfb8aa3b, v124
	v_exp_f32_e32 v118, v118
	v_lshlrev_b32_e32 v124, 16, v171
	v_add_f32_e32 v119, 1.0, v119
	v_rcp_f32_e32 v120, v119
	v_mul_f32_e32 v119, 0xbfb8aa3b, v125
	v_exp_f32_e32 v119, v119
	v_add_f32_e32 v118, 1.0, v118
	v_rcp_f32_e32 v118, v118
	v_and_b32_e32 v125, 0xffff0000, v171
	v_add_f32_e32 v119, 1.0, v119
	v_rcp_f32_e32 v119, v119
	v_lshlrev_b32_e32 v126, 16, v175
	v_and_b32_e32 v127, 0xffff0000, v175
	v_pk_add_f32 v[124:125], v[124:125], v[126:127]
	v_lshlrev_b32_e32 v126, 16, v177
	v_pk_fma_f32 v[118:119], v[128:129], v[118:119], v[124:125]
	v_lshlrev_b32_e32 v124, 16, v173
	v_and_b32_e32 v125, 0xffff0000, v173
	v_and_b32_e32 v127, 0xffff0000, v177
	v_add_u32_e32 v250, 0x48000, v249
	global_load_dwordx4 v[170:173], v250, s[66:67]
	global_load_dwordx4 v[174:177], v250, s[64:65]
	v_pk_add_f32 v[124:125], v[124:125], v[126:127]
	v_mul_f32_e32 v59, 0xbfb8aa3b, v59
	v_pk_fma_f32 v[124:125], v[116:117], v[120:121], v[124:125]
	v_cvt_pk_bf16_f32 v116, v122, v123
	v_cvt_pk_bf16_f32 v117, v118, v119
	v_exp_f32_e32 v58, v58
	v_lshlrev_b32_e32 v126, 16, v116
	v_and_b32_e32 v127, 0xffff0000, v116
	v_lshlrev_b32_e32 v128, 16, v117
	v_and_b32_e32 v129, 0xffff0000, v117
	v_sub_f32_e32 v118, v118, v128
	v_sub_f32_e32 v119, v119, v129
	v_sub_f32_e32 v120, v122, v126
	v_sub_f32_e32 v121, v123, v127
	v_cvt_pk_bf16_f32 v120, v120, v121
	v_cvt_pk_bf16_f32 v121, v118, v119
	v_exp_f32_e32 v59, v59
	v_lshlrev_b32_e32 v118, 16, v120
	v_and_b32_e32 v119, 0xffff0000, v120
	v_pk_add_f32 v[126:127], v[126:127], v[118:119]
	v_cvt_pk_bf16_f32 v118, v114, v115
	v_lshlrev_b32_e32 v122, 16, v121
	v_lshlrev_b32_e32 v130, 16, v118
	v_and_b32_e32 v131, 0xffff0000, v118
	v_and_b32_e32 v123, 0xffff0000, v121
	v_cvt_pk_bf16_f32 v119, v124, v125
	v_sub_f32_e32 v114, v114, v130
	v_lshlrev_b32_e32 v132, 16, v119
	v_sub_f32_e32 v115, v115, v131
	v_pk_add_f32 v[128:129], v[128:129], v[122:123]
	v_and_b32_e32 v133, 0xffff0000, v119
	v_sub_f32_e32 v123, v124, v132
	v_cvt_pk_bf16_f32 v122, v114, v115
	v_sub_f32_e32 v124, v125, v133
	v_lshlrev_b32_e32 v114, 16, v122
	v_and_b32_e32 v115, 0xffff0000, v122
	v_cvt_pk_bf16_f32 v123, v123, v124
	v_pk_add_f32 v[114:115], v[130:131], v[114:115]
	global_store_dwordx4 v[156:157], v[116:119], off
	global_store_dwordx4 v[154:155], v[120:123], off
	v_lshlrev_b32_e32 v124, 16, v123
	v_mul_f32_e32 v116, v127, v127
	v_mul_f32_e32 v117, v129, v129
	v_and_b32_e32 v125, 0xffff0000, v123
	v_fmac_f32_e32 v116, v126, v126
	v_fmac_f32_e32 v117, v128, v128
	v_mul_f32_e32 v115, v115, v115
	v_pk_add_f32 v[124:125], v[132:133], v[124:125]
	v_add_f32_e32 v116, v116, v117
	v_fmac_f32_e32 v115, v114, v114
	v_add_f32_e32 v114, v116, v115
	v_mul_f32_e32 v115, v125, v125
	v_fmac_f32_e32 v115, v124, v124
	v_add_f32_e32 v114, v115, v114
	ds_bpermute_b32 v115, v204, v114
	v_mul_f32_e32 v54, 0xbfb8aa3b, v54
	v_mul_f32_e32 v55, 0xbfb8aa3b, v55
	v_exp_f32_e32 v54, v54
	s_waitcnt lgkmcnt(0)
	v_add_f32_e32 v126, v114, v115
	v_add_u32_e32 v114, 16, v150
	v_ashrrev_i32_e32 v115, 31, v114
	v_lshlrev_b64 v[114:115], 11, v[114:115]
	v_lshl_add_u64 v[116:117], s[66:67], 0, v[114:115]
	v_lshl_add_u64 v[124:125], v[116:117], 0, v[152:153]
	v_lshl_add_u64 v[114:115], s[64:65], 0, v[114:115]
	v_lshl_add_u64 v[122:123], v[114:115], 0, v[152:153]
	v_exp_f32_e32 v55, v55
	v_add_f32_e32 v58, 1.0, v58
	v_add_f32_e32 v59, 1.0, v59
	v_rcp_f32_e32 v58, v58
	v_rcp_f32_e32 v59, v59
	v_add_f32_e32 v54, 1.0, v54
	v_add_f32_e32 v55, 1.0, v55
	v_rcp_f32_e32 v54, v54
	v_rcp_f32_e32 v55, v55
	v_mul_f32_e32 v57, 0xbfb8aa3b, v57
	v_exp_f32_e32 v57, v57
	v_mul_f32_e32 v42, 0xbfb8aa3b, v42
	v_mul_f32_e32 v43, 0xbfb8aa3b, v43
	v_exp_f32_e32 v42, v42
	v_add_f32_e32 v57, 1.0, v57
	v_rcp_f32_e32 v57, v57
	v_exp_f32_e32 v43, v43
	v_mul_f32_e32 v34, 0xbfb8aa3b, v34
	v_mul_f32_e32 v35, 0xbfb8aa3b, v35
	v_exp_f32_e32 v34, v34
	v_exp_f32_e32 v35, v35
	v_add_f32_e32 v42, 1.0, v42
	v_add_f32_e32 v43, 1.0, v43
	v_rcp_f32_e32 v42, v42
	v_rcp_f32_e32 v43, v43
	v_add_f32_e32 v34, 1.0, v34
	v_add_f32_e32 v35, 1.0, v35
	v_rcp_f32_e32 v34, v34
	v_rcp_f32_e32 v35, v35
	v_mul_f32_e32 v26, 0xbfb8aa3b, v26
	v_mul_f32_e32 v27, 0xbfb8aa3b, v27
	v_exp_f32_e32 v26, v26
	v_exp_f32_e32 v27, v27
	v_mul_f32_e32 v18, 0xbfb8aa3b, v18
	v_mul_f32_e32 v19, 0xbfb8aa3b, v19
	v_exp_f32_e32 v18, v18
	v_exp_f32_e32 v19, v19
	v_add_f32_e32 v26, 1.0, v26
	v_add_f32_e32 v27, 1.0, v27
	v_rcp_f32_e32 v26, v26
	v_rcp_f32_e32 v27, v27
	v_add_f32_e32 v18, 1.0, v18
	v_add_f32_e32 v19, 1.0, v19
	v_rcp_f32_e32 v18, v18
	v_rcp_f32_e32 v19, v19
	v_mul_f32_e32 v10, 0xbfb8aa3b, v10
	v_mul_f32_e32 v11, 0xbfb8aa3b, v11
	v_exp_f32_e32 v10, v10
	v_exp_f32_e32 v11, v11
	v_mul_f32_e32 v2, 0xbfb8aa3b, v2
	v_mul_f32_e32 v3, 0xbfb8aa3b, v3
	v_exp_f32_e32 v2, v2
	v_exp_f32_e32 v3, v3
	v_add_f32_e32 v10, 1.0, v10
	v_add_f32_e32 v11, 1.0, v11
	v_rcp_f32_e32 v10, v10
	v_rcp_f32_e32 v11, v11
	v_add_f32_e32 v2, 1.0, v2
	v_add_f32_e32 v3, 1.0, v3
	v_rcp_f32_e32 v2, v2
	v_rcp_f32_e32 v3, v3
	ds_bpermute_b32 v127, v205, v126
	s_waitcnt vmcnt(10)
	v_lshlrev_b32_e32 v128, 16, v178
	v_and_b32_e32 v129, 0xffff0000, v178
	v_lshlrev_b32_e32 v130, 16, v190
	v_and_b32_e32 v131, 0xffff0000, v190
	v_pk_add_f32 v[128:129], v[128:129], v[130:131]
	s_nop 0
	v_pk_fma_f32 v[106:107], v[110:111], v[106:107], v[128:129]
	v_lshlrev_b32_e32 v110, 16, v180
	v_and_b32_e32 v111, 0xffff0000, v180
	v_lshlrev_b32_e32 v128, 16, v192
	v_and_b32_e32 v129, 0xffff0000, v192
	v_pk_add_f32 v[110:111], v[110:111], v[128:129]
	s_nop 0
	v_pk_fma_f32 v[98:99], v[98:99], v[102:103], v[110:111]
	v_mul_f32_e32 v103, 0xbfb8aa3b, v104
	v_exp_f32_e32 v103, v103
	v_mul_f32_e32 v102, 0xbfb8aa3b, v108
	v_exp_f32_e32 v102, v102
	v_lshlrev_b32_e32 v108, 16, v179
	v_add_f32_e32 v103, 1.0, v103
	v_rcp_f32_e32 v104, v103
	v_mul_f32_e32 v103, 0xbfb8aa3b, v109
	v_exp_f32_e32 v103, v103
	v_add_f32_e32 v102, 1.0, v102
	v_rcp_f32_e32 v102, v102
	v_and_b32_e32 v109, 0xffff0000, v179
	v_add_f32_e32 v103, 1.0, v103
	v_rcp_f32_e32 v103, v103
	v_lshlrev_b32_e32 v110, 16, v191
	v_and_b32_e32 v111, 0xffff0000, v191
	v_pk_add_f32 v[108:109], v[108:109], v[110:111]
	v_lshlrev_b32_e32 v110, 16, v193
	v_pk_fma_f32 v[102:103], v[112:113], v[102:103], v[108:109]
	v_lshlrev_b32_e32 v108, 16, v181
	v_and_b32_e32 v109, 0xffff0000, v181
	v_and_b32_e32 v111, 0xffff0000, v193
	v_add_u32_e32 v251, 0x50000, v249
	global_load_dwordx4 v[178:181], v251, s[66:67]
	global_load_dwordx4 v[190:193], v251, s[64:65]
	v_pk_add_f32 v[108:109], v[108:109], v[110:111]
	s_nop 0
	v_pk_fma_f32 v[108:109], v[100:101], v[104:105], v[108:109]
	v_cvt_pk_bf16_f32 v100, v106, v107
	v_cvt_pk_bf16_f32 v101, v102, v103
	s_nop 0
	v_lshlrev_b32_e32 v110, 16, v100
	v_and_b32_e32 v111, 0xffff0000, v100
	v_lshlrev_b32_e32 v112, 16, v101
	v_and_b32_e32 v113, 0xffff0000, v101
	v_sub_f32_e32 v102, v102, v112
	v_sub_f32_e32 v103, v103, v113
	v_sub_f32_e32 v104, v106, v110
	v_sub_f32_e32 v105, v107, v111
	v_cvt_pk_bf16_f32 v104, v104, v105
	v_cvt_pk_bf16_f32 v105, v102, v103
	s_nop 0
	v_lshlrev_b32_e32 v102, 16, v104
	v_and_b32_e32 v103, 0xffff0000, v104
	v_pk_add_f32 v[110:111], v[110:111], v[102:103]
	v_cvt_pk_bf16_f32 v102, v98, v99
	v_lshlrev_b32_e32 v106, 16, v105
	v_lshlrev_b32_e32 v114, 16, v102
	v_and_b32_e32 v115, 0xffff0000, v102
	v_and_b32_e32 v107, 0xffff0000, v105
	v_cvt_pk_bf16_f32 v103, v108, v109
	v_sub_f32_e32 v98, v98, v114
	v_lshlrev_b32_e32 v116, 16, v103
	v_sub_f32_e32 v99, v99, v115
	v_pk_add_f32 v[112:113], v[112:113], v[106:107]
	v_and_b32_e32 v117, 0xffff0000, v103
	v_sub_f32_e32 v107, v108, v116
	v_cvt_pk_bf16_f32 v106, v98, v99
	v_sub_f32_e32 v108, v109, v117
	v_lshlrev_b32_e32 v98, 16, v106
	v_and_b32_e32 v99, 0xffff0000, v106
	v_cvt_pk_bf16_f32 v107, v107, v108
	v_pk_add_f32 v[98:99], v[114:115], v[98:99]
	global_store_dwordx4 v[124:125], v[100:103], off
	global_store_dwordx4 v[122:123], v[104:107], off
	v_lshlrev_b32_e32 v108, 16, v107
	v_mul_f32_e32 v100, v111, v111
	v_mul_f32_e32 v101, v113, v113
	v_and_b32_e32 v109, 0xffff0000, v107
	v_fmac_f32_e32 v100, v110, v110
	v_fmac_f32_e32 v101, v112, v112
	v_mul_f32_e32 v99, v99, v99
	v_pk_add_f32 v[108:109], v[116:117], v[108:109]
	v_add_f32_e32 v100, v100, v101
	v_fmac_f32_e32 v99, v98, v98
	v_add_f32_e32 v98, v100, v99
	v_mul_f32_e32 v99, v109, v109
	v_fmac_f32_e32 v99, v108, v108
	v_add_f32_e32 v98, v99, v98
	ds_bpermute_b32 v99, v204, v98
	s_waitcnt lgkmcnt(0)
	v_add_f32_e32 v110, v98, v99
	v_add_u32_e32 v98, 32, v150
	v_ashrrev_i32_e32 v99, 31, v98
	v_lshlrev_b64 v[98:99], 11, v[98:99]
	v_lshl_add_u64 v[100:101], s[66:67], 0, v[98:99]
	v_lshl_add_u64 v[108:109], v[100:101], 0, v[152:153]
	v_lshl_add_u64 v[98:99], s[64:65], 0, v[98:99]
	v_lshl_add_u64 v[106:107], v[98:99], 0, v[152:153]
	ds_bpermute_b32 v111, v205, v110
	s_waitcnt vmcnt(12)
	v_lshlrev_b32_e32 v112, 16, v194
	v_and_b32_e32 v113, 0xffff0000, v194
	v_lshlrev_b32_e32 v114, 16, v214
	v_and_b32_e32 v115, 0xffff0000, v214
	v_pk_add_f32 v[112:113], v[112:113], v[114:115]
	s_nop 0
	v_pk_fma_f32 v[90:91], v[94:95], v[90:91], v[112:113]
	v_lshlrev_b32_e32 v94, 16, v196
	v_and_b32_e32 v95, 0xffff0000, v196
	v_lshlrev_b32_e32 v112, 16, v216
	v_and_b32_e32 v113, 0xffff0000, v216
	v_pk_add_f32 v[94:95], v[94:95], v[112:113]
	s_nop 0
	v_pk_fma_f32 v[82:83], v[82:83], v[86:87], v[94:95]
	v_mul_f32_e32 v87, 0xbfb8aa3b, v88
	v_exp_f32_e32 v87, v87
	v_mul_f32_e32 v86, 0xbfb8aa3b, v92
	v_exp_f32_e32 v86, v86
	v_lshlrev_b32_e32 v92, 16, v195
	v_add_f32_e32 v87, 1.0, v87
	v_rcp_f32_e32 v88, v87
	v_mul_f32_e32 v87, 0xbfb8aa3b, v93
	v_exp_f32_e32 v87, v87
	v_add_f32_e32 v86, 1.0, v86
	v_rcp_f32_e32 v86, v86
	v_and_b32_e32 v93, 0xffff0000, v195
	v_add_f32_e32 v87, 1.0, v87
	v_rcp_f32_e32 v87, v87
	v_lshlrev_b32_e32 v94, 16, v215
	v_and_b32_e32 v95, 0xffff0000, v215
	v_pk_add_f32 v[92:93], v[92:93], v[94:95]
	v_lshlrev_b32_e32 v94, 16, v217
	v_pk_fma_f32 v[86:87], v[96:97], v[86:87], v[92:93]
	v_lshlrev_b32_e32 v92, 16, v197
	v_and_b32_e32 v93, 0xffff0000, v197
	v_and_b32_e32 v95, 0xffff0000, v217
	v_add_u32_e32 v250, 0x58000, v249
	global_load_dwordx4 v[194:197], v250, s[66:67]
	global_load_dwordx4 v[214:217], v250, s[64:65]
	v_pk_add_f32 v[92:93], v[92:93], v[94:95]
	s_nop 0
	v_pk_fma_f32 v[92:93], v[84:85], v[88:89], v[92:93]
	v_cvt_pk_bf16_f32 v84, v90, v91
	v_cvt_pk_bf16_f32 v85, v86, v87
	s_nop 0
	v_lshlrev_b32_e32 v94, 16, v84
	v_and_b32_e32 v95, 0xffff0000, v84
	v_lshlrev_b32_e32 v96, 16, v85
	v_and_b32_e32 v97, 0xffff0000, v85
	v_sub_f32_e32 v86, v86, v96
	v_sub_f32_e32 v87, v87, v97
	v_sub_f32_e32 v88, v90, v94
	v_sub_f32_e32 v89, v91, v95
	v_cvt_pk_bf16_f32 v88, v88, v89
	v_cvt_pk_bf16_f32 v89, v86, v87
	s_nop 0
	v_lshlrev_b32_e32 v86, 16, v88
	v_and_b32_e32 v87, 0xffff0000, v88
	v_pk_add_f32 v[94:95], v[94:95], v[86:87]
	v_cvt_pk_bf16_f32 v86, v82, v83
	v_lshlrev_b32_e32 v90, 16, v89
	v_lshlrev_b32_e32 v98, 16, v86
	v_and_b32_e32 v99, 0xffff0000, v86
	v_and_b32_e32 v91, 0xffff0000, v89
	v_cvt_pk_bf16_f32 v87, v92, v93
	v_sub_f32_e32 v82, v82, v98
	v_lshlrev_b32_e32 v100, 16, v87
	v_sub_f32_e32 v83, v83, v99
	v_pk_add_f32 v[96:97], v[96:97], v[90:91]
	v_and_b32_e32 v101, 0xffff0000, v87
	v_sub_f32_e32 v91, v92, v100
	v_cvt_pk_bf16_f32 v90, v82, v83
	v_sub_f32_e32 v92, v93, v101
	v_lshlrev_b32_e32 v82, 16, v90
	v_and_b32_e32 v83, 0xffff0000, v90
	v_cvt_pk_bf16_f32 v91, v91, v92
	v_pk_add_f32 v[82:83], v[98:99], v[82:83]
	global_store_dwordx4 v[108:109], v[84:87], off
	global_store_dwordx4 v[106:107], v[88:91], off
	v_lshlrev_b32_e32 v92, 16, v91
	v_mul_f32_e32 v84, v95, v95
	v_mul_f32_e32 v85, v97, v97
	v_and_b32_e32 v93, 0xffff0000, v91
	v_fmac_f32_e32 v84, v94, v94
	v_fmac_f32_e32 v85, v96, v96
	v_mul_f32_e32 v83, v83, v83
	v_pk_add_f32 v[92:93], v[100:101], v[92:93]
	v_add_f32_e32 v84, v84, v85
	v_fmac_f32_e32 v83, v82, v82
	v_add_f32_e32 v82, v84, v83
	v_mul_f32_e32 v83, v93, v93
	v_fmac_f32_e32 v83, v92, v92
	v_add_f32_e32 v82, v83, v82
	ds_bpermute_b32 v83, v204, v82
	s_waitcnt lgkmcnt(0)
	v_add_f32_e32 v94, v82, v83
	v_add_u32_e32 v82, 48, v150
	v_ashrrev_i32_e32 v83, 31, v82
	v_lshlrev_b64 v[82:83], 11, v[82:83]
	v_lshl_add_u64 v[84:85], s[66:67], 0, v[82:83]
	v_lshl_add_u64 v[92:93], v[84:85], 0, v[152:153]
	v_lshl_add_u64 v[82:83], s[64:65], 0, v[82:83]
	v_lshl_add_u64 v[90:91], v[82:83], 0, v[152:153]
	ds_bpermute_b32 v95, v205, v94
	s_waitcnt vmcnt(14)
	v_lshlrev_b32_e32 v96, 16, v218
	v_and_b32_e32 v97, 0xffff0000, v218
	v_lshlrev_b32_e32 v98, 16, v222
	v_and_b32_e32 v99, 0xffff0000, v222
	v_pk_add_f32 v[96:97], v[96:97], v[98:99]
	s_nop 0
	v_pk_fma_f32 v[74:75], v[78:79], v[74:75], v[96:97]
	v_lshlrev_b32_e32 v78, 16, v220
	v_and_b32_e32 v79, 0xffff0000, v220
	v_lshlrev_b32_e32 v96, 16, v224
	v_and_b32_e32 v97, 0xffff0000, v224
	v_pk_add_f32 v[78:79], v[78:79], v[96:97]
	s_nop 0
	v_pk_fma_f32 v[66:67], v[66:67], v[70:71], v[78:79]
	v_mul_f32_e32 v71, 0xbfb8aa3b, v72
	v_exp_f32_e32 v71, v71
	v_mul_f32_e32 v70, 0xbfb8aa3b, v76
	v_exp_f32_e32 v70, v70
	v_lshlrev_b32_e32 v76, 16, v219
	v_add_f32_e32 v71, 1.0, v71
	v_rcp_f32_e32 v72, v71
	v_mul_f32_e32 v71, 0xbfb8aa3b, v77
	v_exp_f32_e32 v71, v71
	v_add_f32_e32 v70, 1.0, v70
	v_rcp_f32_e32 v70, v70
	v_and_b32_e32 v77, 0xffff0000, v219
	v_add_f32_e32 v71, 1.0, v71
	v_rcp_f32_e32 v71, v71
	v_lshlrev_b32_e32 v78, 16, v223
	v_and_b32_e32 v79, 0xffff0000, v223
	v_pk_add_f32 v[76:77], v[76:77], v[78:79]
	v_lshlrev_b32_e32 v78, 16, v225
	v_pk_fma_f32 v[70:71], v[80:81], v[70:71], v[76:77]
	v_lshlrev_b32_e32 v76, 16, v221
	v_and_b32_e32 v77, 0xffff0000, v221
	v_and_b32_e32 v79, 0xffff0000, v225
	v_pk_add_f32 v[76:77], v[76:77], v[78:79]
	s_nop 0
	v_pk_fma_f32 v[76:77], v[68:69], v[72:73], v[76:77]
	v_cvt_pk_bf16_f32 v68, v74, v75
	v_cvt_pk_bf16_f32 v69, v70, v71
	s_nop 0
	v_lshlrev_b32_e32 v78, 16, v68
	v_and_b32_e32 v79, 0xffff0000, v68
	v_lshlrev_b32_e32 v80, 16, v69
	v_and_b32_e32 v81, 0xffff0000, v69
	v_sub_f32_e32 v70, v70, v80
	v_sub_f32_e32 v71, v71, v81
	v_sub_f32_e32 v72, v74, v78
	v_sub_f32_e32 v73, v75, v79
	v_cvt_pk_bf16_f32 v72, v72, v73
	v_cvt_pk_bf16_f32 v73, v70, v71
	s_nop 0
	v_lshlrev_b32_e32 v70, 16, v72
	v_and_b32_e32 v71, 0xffff0000, v72
	v_pk_add_f32 v[78:79], v[78:79], v[70:71]
	v_cvt_pk_bf16_f32 v70, v66, v67
	v_lshlrev_b32_e32 v74, 16, v73
	v_lshlrev_b32_e32 v82, 16, v70
	v_and_b32_e32 v83, 0xffff0000, v70
	v_and_b32_e32 v75, 0xffff0000, v73
	v_cvt_pk_bf16_f32 v71, v76, v77
	v_sub_f32_e32 v66, v66, v82
	v_lshlrev_b32_e32 v84, 16, v71
	v_sub_f32_e32 v67, v67, v83
	v_pk_add_f32 v[80:81], v[80:81], v[74:75]
	v_and_b32_e32 v85, 0xffff0000, v71
	v_sub_f32_e32 v75, v76, v84
	v_cvt_pk_bf16_f32 v74, v66, v67
	v_sub_f32_e32 v76, v77, v85
	v_lshlrev_b32_e32 v66, 16, v74
	v_and_b32_e32 v67, 0xffff0000, v74
	v_cvt_pk_bf16_f32 v75, v75, v76
	v_pk_add_f32 v[66:67], v[82:83], v[66:67]
	global_store_dwordx4 v[92:93], v[68:71], off
	global_store_dwordx4 v[90:91], v[72:75], off
	v_lshlrev_b32_e32 v76, 16, v75
	v_mul_f32_e32 v68, v79, v79
	v_mul_f32_e32 v69, v81, v81
	v_and_b32_e32 v77, 0xffff0000, v75
	v_fmac_f32_e32 v68, v78, v78
	v_fmac_f32_e32 v69, v80, v80
	v_mul_f32_e32 v67, v67, v67
	v_pk_add_f32 v[76:77], v[84:85], v[76:77]
	v_add_f32_e32 v68, v68, v69
	v_fmac_f32_e32 v67, v66, v66
	v_add_f32_e32 v66, v68, v67
	v_mul_f32_e32 v67, v77, v77
	v_fmac_f32_e32 v67, v76, v76
	v_add_f32_e32 v66, v67, v66
	ds_bpermute_b32 v67, v204, v66
	s_waitcnt lgkmcnt(0)
	v_add_f32_e32 v78, v66, v67
	v_add_u32_e32 v66, 0x80, v150
	v_ashrrev_i32_e32 v67, 31, v66
	v_lshlrev_b64 v[66:67], 11, v[66:67]
	v_lshl_add_u64 v[68:69], s[66:67], 0, v[66:67]
	v_lshl_add_u64 v[76:77], v[68:69], 0, v[152:153]
	v_lshl_add_u64 v[66:67], s[64:65], 0, v[66:67]
	v_lshl_add_u64 v[74:75], v[66:67], 0, v[152:153]
	ds_bpermute_b32 v79, v205, v78
	s_waitcnt vmcnt(14)
	v_lshlrev_b32_e32 v80, 16, v226
	v_and_b32_e32 v81, 0xffff0000, v226
	v_lshlrev_b32_e32 v82, 16, v230
	v_and_b32_e32 v83, 0xffff0000, v230
	v_pk_add_f32 v[80:81], v[80:81], v[82:83]
	s_nop 0
	v_pk_fma_f32 v[58:59], v[62:63], v[58:59], v[80:81]
	v_lshlrev_b32_e32 v62, 16, v228
	v_and_b32_e32 v63, 0xffff0000, v228
	v_lshlrev_b32_e32 v80, 16, v232
	v_and_b32_e32 v81, 0xffff0000, v232
	v_pk_add_f32 v[62:63], v[62:63], v[80:81]
	s_nop 0
	v_pk_fma_f32 v[50:51], v[50:51], v[54:55], v[62:63]
	v_mul_f32_e32 v55, 0xbfb8aa3b, v56
	v_exp_f32_e32 v55, v55
	v_mul_f32_e32 v54, 0xbfb8aa3b, v60
	v_exp_f32_e32 v54, v54
	v_lshlrev_b32_e32 v60, 16, v227
	v_add_f32_e32 v55, 1.0, v55
	v_rcp_f32_e32 v56, v55
	v_mul_f32_e32 v55, 0xbfb8aa3b, v61
	v_exp_f32_e32 v55, v55
	v_add_f32_e32 v54, 1.0, v54
	v_rcp_f32_e32 v54, v54
	v_and_b32_e32 v61, 0xffff0000, v227
	v_add_f32_e32 v55, 1.0, v55
	v_rcp_f32_e32 v55, v55
	v_lshlrev_b32_e32 v62, 16, v231
	v_and_b32_e32 v63, 0xffff0000, v231
	v_pk_add_f32 v[60:61], v[60:61], v[62:63]
	v_lshlrev_b32_e32 v62, 16, v233
	v_pk_fma_f32 v[54:55], v[64:65], v[54:55], v[60:61]
	v_lshlrev_b32_e32 v60, 16, v229
	v_and_b32_e32 v61, 0xffff0000, v229
	v_and_b32_e32 v63, 0xffff0000, v233
	v_pk_add_f32 v[60:61], v[60:61], v[62:63]
	s_nop 0
	v_pk_fma_f32 v[60:61], v[52:53], v[56:57], v[60:61]
	v_cvt_pk_bf16_f32 v52, v58, v59
	v_cvt_pk_bf16_f32 v53, v54, v55
	s_nop 0
	v_lshlrev_b32_e32 v62, 16, v52
	v_and_b32_e32 v63, 0xffff0000, v52
	v_lshlrev_b32_e32 v64, 16, v53
	v_and_b32_e32 v65, 0xffff0000, v53
	v_sub_f32_e32 v54, v54, v64
	v_sub_f32_e32 v55, v55, v65
	v_sub_f32_e32 v56, v58, v62
	v_sub_f32_e32 v57, v59, v63
	v_cvt_pk_bf16_f32 v56, v56, v57
	v_cvt_pk_bf16_f32 v57, v54, v55
	s_nop 0
	v_lshlrev_b32_e32 v54, 16, v56
	v_and_b32_e32 v55, 0xffff0000, v56
	v_pk_add_f32 v[62:63], v[62:63], v[54:55]
	v_cvt_pk_bf16_f32 v54, v50, v51
	v_lshlrev_b32_e32 v58, 16, v57
	v_lshlrev_b32_e32 v66, 16, v54
	v_and_b32_e32 v67, 0xffff0000, v54
	v_and_b32_e32 v59, 0xffff0000, v57
	v_cvt_pk_bf16_f32 v55, v60, v61
	v_sub_f32_e32 v50, v50, v66
	v_lshlrev_b32_e32 v68, 16, v55
	v_sub_f32_e32 v51, v51, v67
	v_pk_add_f32 v[64:65], v[64:65], v[58:59]
	v_and_b32_e32 v69, 0xffff0000, v55
	v_sub_f32_e32 v59, v60, v68
	v_cvt_pk_bf16_f32 v58, v50, v51
	v_sub_f32_e32 v60, v61, v69
	v_lshlrev_b32_e32 v50, 16, v58
	v_and_b32_e32 v51, 0xffff0000, v58
	v_cvt_pk_bf16_f32 v59, v59, v60
	v_pk_add_f32 v[50:51], v[66:67], v[50:51]
	global_store_dwordx4 v[76:77], v[52:55], off
	global_store_dwordx4 v[74:75], v[56:59], off
	v_lshlrev_b32_e32 v60, 16, v59
	v_mul_f32_e32 v52, v63, v63
	v_mul_f32_e32 v53, v65, v65
	v_and_b32_e32 v61, 0xffff0000, v59
	v_fmac_f32_e32 v52, v62, v62
	v_fmac_f32_e32 v53, v64, v64
	v_mul_f32_e32 v51, v51, v51
	v_pk_add_f32 v[60:61], v[68:69], v[60:61]
	v_add_f32_e32 v52, v52, v53
	v_fmac_f32_e32 v51, v50, v50
	v_add_f32_e32 v50, v52, v51
	v_mul_f32_e32 v51, v61, v61
	v_fmac_f32_e32 v51, v60, v60
	v_add_f32_e32 v50, v51, v50
	ds_bpermute_b32 v51, v204, v50
	s_waitcnt lgkmcnt(0)
	v_add_f32_e32 v62, v50, v51
	v_add_u32_e32 v50, 0x90, v150
	v_ashrrev_i32_e32 v51, 31, v50
	v_lshlrev_b64 v[50:51], 11, v[50:51]
	v_lshl_add_u64 v[52:53], s[66:67], 0, v[50:51]
	v_lshl_add_u64 v[60:61], v[52:53], 0, v[152:153]
	v_lshl_add_u64 v[50:51], s[64:65], 0, v[50:51]
	v_lshl_add_u64 v[58:59], v[50:51], 0, v[152:153]
	ds_bpermute_b32 v63, v205, v62
	s_waitcnt vmcnt(14)
	v_lshlrev_b32_e32 v64, 16, v170
	v_and_b32_e32 v65, 0xffff0000, v170
	v_lshlrev_b32_e32 v66, 16, v174
	v_and_b32_e32 v67, 0xffff0000, v174
	v_pk_add_f32 v[64:65], v[64:65], v[66:67]
	s_nop 0
	v_pk_fma_f32 v[42:43], v[46:47], v[42:43], v[64:65]
	v_lshlrev_b32_e32 v46, 16, v172
	v_and_b32_e32 v47, 0xffff0000, v172
	v_lshlrev_b32_e32 v64, 16, v176
	v_and_b32_e32 v65, 0xffff0000, v176
	v_pk_add_f32 v[46:47], v[46:47], v[64:65]
	s_nop 0
	v_pk_fma_f32 v[46:47], v[38:39], v[34:35], v[46:47]
	v_mul_f32_e32 v35, 0xbfb8aa3b, v36
	v_exp_f32_e32 v35, v35
	v_mul_f32_e32 v34, 0xbfb8aa3b, v44
	v_exp_f32_e32 v34, v34
	v_lshlrev_b32_e32 v38, 16, v171
	v_add_f32_e32 v35, 1.0, v35
	v_rcp_f32_e32 v36, v35
	v_mul_f32_e32 v35, 0xbfb8aa3b, v45
	v_exp_f32_e32 v35, v35
	v_add_f32_e32 v34, 1.0, v34
	v_rcp_f32_e32 v34, v34
	v_and_b32_e32 v39, 0xffff0000, v171
	v_add_f32_e32 v35, 1.0, v35
	v_rcp_f32_e32 v35, v35
	v_lshlrev_b32_e32 v44, 16, v175
	v_and_b32_e32 v45, 0xffff0000, v175
	v_pk_add_f32 v[38:39], v[38:39], v[44:45]
	v_lshlrev_b32_e32 v44, 16, v177
	v_pk_fma_f32 v[38:39], v[48:49], v[34:35], v[38:39]
	v_mul_f32_e32 v34, 0xbfb8aa3b, v37
	v_exp_f32_e32 v34, v34
	v_and_b32_e32 v35, 0xffff0000, v173
	v_and_b32_e32 v45, 0xffff0000, v177
	v_add_f32_e32 v34, 1.0, v34
	v_rcp_f32_e32 v37, v34
	v_lshlrev_b32_e32 v34, 16, v173
	v_pk_add_f32 v[34:35], v[34:35], v[44:45]
	s_nop 0
	v_pk_fma_f32 v[40:41], v[40:41], v[36:37], v[34:35]
	v_cvt_pk_bf16_f32 v34, v42, v43
	v_cvt_pk_bf16_f32 v35, v38, v39
	s_nop 0
	v_lshlrev_b32_e32 v36, 16, v34
	v_and_b32_e32 v37, 0xffff0000, v34
	v_lshlrev_b32_e32 v44, 16, v35
	v_and_b32_e32 v45, 0xffff0000, v35
	v_sub_f32_e32 v48, v38, v44
	v_sub_f32_e32 v39, v39, v45
	v_sub_f32_e32 v38, v42, v36
	v_sub_f32_e32 v42, v43, v37
	v_cvt_pk_bf16_f32 v38, v38, v42
	v_cvt_pk_bf16_f32 v39, v48, v39
	s_nop 0
	v_lshlrev_b32_e32 v42, 16, v38
	v_and_b32_e32 v43, 0xffff0000, v38
	v_lshlrev_b32_e32 v48, 16, v39
	v_and_b32_e32 v49, 0xffff0000, v39
	v_pk_add_f32 v[44:45], v[44:45], v[48:49]
	v_pk_add_f32 v[42:43], v[36:37], v[42:43]
	v_cvt_pk_bf16_f32 v36, v46, v47
	v_cvt_pk_bf16_f32 v37, v40, v41
	s_nop 0
	v_lshlrev_b32_e32 v48, 16, v36
	v_and_b32_e32 v49, 0xffff0000, v36
	v_lshlrev_b32_e32 v50, 16, v37
	v_and_b32_e32 v51, 0xffff0000, v37
	v_sub_f32_e32 v52, v40, v50
	v_sub_f32_e32 v41, v41, v51
	v_sub_f32_e32 v40, v46, v48
	v_sub_f32_e32 v46, v47, v49
	v_cvt_pk_bf16_f32 v40, v40, v46
	v_cvt_pk_bf16_f32 v41, v52, v41
	global_store_dwordx4 v[60:61], v[34:37], off
	global_store_dwordx4 v[58:59], v[38:41], off
	v_lshlrev_b32_e32 v46, 16, v40
	v_and_b32_e32 v47, 0xffff0000, v40
	v_mul_f32_e32 v34, v43, v43
	v_mul_f32_e32 v35, v45, v45
	v_pk_add_f32 v[46:47], v[48:49], v[46:47]
	v_fmac_f32_e32 v34, v42, v42
	v_fmac_f32_e32 v35, v44, v44
	v_lshlrev_b32_e32 v52, 16, v41
	v_and_b32_e32 v53, 0xffff0000, v41
	v_add_f32_e32 v34, v34, v35
	v_mul_f32_e32 v35, v47, v47
	v_pk_add_f32 v[50:51], v[50:51], v[52:53]
	v_fmac_f32_e32 v35, v46, v46
	v_add_f32_e32 v34, v34, v35
	v_mul_f32_e32 v35, v51, v51
	v_fmac_f32_e32 v35, v50, v50
	v_add_f32_e32 v34, v35, v34
	ds_bpermute_b32 v35, v204, v34
	s_waitcnt lgkmcnt(0)
	v_add_f32_e32 v46, v34, v35
	v_add_u32_e32 v34, 0xa0, v150
	v_ashrrev_i32_e32 v35, 31, v34
	v_lshlrev_b64 v[34:35], 11, v[34:35]
	v_lshl_add_u64 v[36:37], s[66:67], 0, v[34:35]
	v_lshl_add_u64 v[44:45], v[36:37], 0, v[152:153]
	v_lshl_add_u64 v[34:35], s[64:65], 0, v[34:35]
	v_lshl_add_u64 v[42:43], v[34:35], 0, v[152:153]
	ds_bpermute_b32 v47, v205, v46
	s_waitcnt vmcnt(12)
	v_lshlrev_b32_e32 v48, 16, v178
	v_and_b32_e32 v49, 0xffff0000, v178
	v_lshlrev_b32_e32 v50, 16, v190
	v_and_b32_e32 v51, 0xffff0000, v190
	v_pk_add_f32 v[48:49], v[48:49], v[50:51]
	s_nop 0
	v_pk_fma_f32 v[26:27], v[30:31], v[26:27], v[48:49]
	v_lshlrev_b32_e32 v30, 16, v180
	v_and_b32_e32 v31, 0xffff0000, v180
	v_lshlrev_b32_e32 v48, 16, v192
	v_and_b32_e32 v49, 0xffff0000, v192
	v_pk_add_f32 v[30:31], v[30:31], v[48:49]
	s_nop 0
	v_pk_fma_f32 v[30:31], v[22:23], v[18:19], v[30:31]
	v_mul_f32_e32 v19, 0xbfb8aa3b, v20
	v_exp_f32_e32 v19, v19
	v_mul_f32_e32 v18, 0xbfb8aa3b, v28
	v_exp_f32_e32 v18, v18
	v_lshlrev_b32_e32 v22, 16, v179
	v_add_f32_e32 v19, 1.0, v19
	v_rcp_f32_e32 v20, v19
	v_mul_f32_e32 v19, 0xbfb8aa3b, v29
	v_exp_f32_e32 v19, v19
	v_add_f32_e32 v18, 1.0, v18
	v_rcp_f32_e32 v18, v18
	v_and_b32_e32 v23, 0xffff0000, v179
	v_add_f32_e32 v19, 1.0, v19
	v_rcp_f32_e32 v19, v19
	v_lshlrev_b32_e32 v28, 16, v191
	v_and_b32_e32 v29, 0xffff0000, v191
	v_pk_add_f32 v[22:23], v[22:23], v[28:29]
	v_lshlrev_b32_e32 v28, 16, v193
	v_pk_fma_f32 v[22:23], v[32:33], v[18:19], v[22:23]
	v_mul_f32_e32 v18, 0xbfb8aa3b, v21
	v_exp_f32_e32 v18, v18
	v_and_b32_e32 v19, 0xffff0000, v181
	v_and_b32_e32 v29, 0xffff0000, v193
	v_add_f32_e32 v18, 1.0, v18
	v_rcp_f32_e32 v21, v18
	v_lshlrev_b32_e32 v18, 16, v181
	v_pk_add_f32 v[18:19], v[18:19], v[28:29]
	s_nop 0
	v_pk_fma_f32 v[24:25], v[24:25], v[20:21], v[18:19]
	v_cvt_pk_bf16_f32 v18, v26, v27
	v_cvt_pk_bf16_f32 v19, v22, v23
	s_nop 0
	v_lshlrev_b32_e32 v20, 16, v18
	v_and_b32_e32 v21, 0xffff0000, v18
	v_lshlrev_b32_e32 v28, 16, v19
	v_and_b32_e32 v29, 0xffff0000, v19
	v_sub_f32_e32 v32, v22, v28
	v_sub_f32_e32 v23, v23, v29
	v_sub_f32_e32 v22, v26, v20
	v_sub_f32_e32 v26, v27, v21
	v_cvt_pk_bf16_f32 v22, v22, v26
	v_cvt_pk_bf16_f32 v23, v32, v23
	s_nop 0
	v_lshlrev_b32_e32 v26, 16, v22
	v_and_b32_e32 v27, 0xffff0000, v22
	v_lshlrev_b32_e32 v32, 16, v23
	v_and_b32_e32 v33, 0xffff0000, v23
	v_pk_add_f32 v[28:29], v[28:29], v[32:33]
	v_pk_add_f32 v[26:27], v[20:21], v[26:27]
	v_cvt_pk_bf16_f32 v20, v30, v31
	v_cvt_pk_bf16_f32 v21, v24, v25
	s_nop 0
	v_lshlrev_b32_e32 v32, 16, v20
	v_and_b32_e32 v33, 0xffff0000, v20
	v_lshlrev_b32_e32 v34, 16, v21
	v_and_b32_e32 v35, 0xffff0000, v21
	v_sub_f32_e32 v36, v24, v34
	v_sub_f32_e32 v25, v25, v35
	v_sub_f32_e32 v24, v30, v32
	v_sub_f32_e32 v30, v31, v33
	v_cvt_pk_bf16_f32 v24, v24, v30
	v_cvt_pk_bf16_f32 v25, v36, v25
	global_store_dwordx4 v[44:45], v[18:21], off
	global_store_dwordx4 v[42:43], v[22:25], off
	v_lshlrev_b32_e32 v30, 16, v24
	v_and_b32_e32 v31, 0xffff0000, v24
	v_mul_f32_e32 v18, v27, v27
	v_mul_f32_e32 v19, v29, v29
	v_pk_add_f32 v[30:31], v[32:33], v[30:31]
	v_fmac_f32_e32 v18, v26, v26
	v_fmac_f32_e32 v19, v28, v28
	v_lshlrev_b32_e32 v36, 16, v25
	v_and_b32_e32 v37, 0xffff0000, v25
	v_add_f32_e32 v18, v18, v19
	v_mul_f32_e32 v19, v31, v31
	v_pk_add_f32 v[34:35], v[34:35], v[36:37]
	v_fmac_f32_e32 v19, v30, v30
	v_add_f32_e32 v18, v18, v19
	v_mul_f32_e32 v19, v35, v35
	v_fmac_f32_e32 v19, v34, v34
	v_add_f32_e32 v18, v19, v18
	ds_bpermute_b32 v19, v204, v18
	s_waitcnt lgkmcnt(0)
	v_add_f32_e32 v30, v18, v19
	v_add_u32_e32 v18, 0xb0, v150
	v_ashrrev_i32_e32 v19, 31, v18
	v_lshlrev_b64 v[18:19], 11, v[18:19]
	v_lshl_add_u64 v[20:21], s[66:67], 0, v[18:19]
	v_lshl_add_u64 v[26:27], v[20:21], 0, v[152:153]
	v_lshl_add_u64 v[18:19], s[64:65], 0, v[18:19]
	v_lshl_add_u64 v[28:29], v[18:19], 0, v[152:153]
	ds_bpermute_b32 v31, v205, v30
	s_waitcnt vmcnt(10)
	v_lshlrev_b32_e32 v32, 16, v194
	v_and_b32_e32 v33, 0xffff0000, v194
	v_lshlrev_b32_e32 v34, 16, v214
	v_and_b32_e32 v35, 0xffff0000, v214
	v_pk_add_f32 v[32:33], v[32:33], v[34:35]
	s_nop 0
	v_pk_fma_f32 v[10:11], v[14:15], v[10:11], v[32:33]
	v_lshlrev_b32_e32 v14, 16, v196
	v_and_b32_e32 v15, 0xffff0000, v196
	v_lshlrev_b32_e32 v32, 16, v216
	v_and_b32_e32 v33, 0xffff0000, v216
	v_pk_add_f32 v[14:15], v[14:15], v[32:33]
	s_nop 0
	v_pk_fma_f32 v[14:15], v[6:7], v[2:3], v[14:15]
	v_mul_f32_e32 v3, 0xbfb8aa3b, v4
	v_exp_f32_e32 v3, v3
	v_mul_f32_e32 v2, 0xbfb8aa3b, v12
	v_exp_f32_e32 v2, v2
	v_lshlrev_b32_e32 v6, 16, v195
	v_add_f32_e32 v3, 1.0, v3
	v_rcp_f32_e32 v4, v3
	v_mul_f32_e32 v3, 0xbfb8aa3b, v13
	v_exp_f32_e32 v3, v3
	v_add_f32_e32 v2, 1.0, v2
	v_rcp_f32_e32 v2, v2
	v_and_b32_e32 v7, 0xffff0000, v195
	v_add_f32_e32 v3, 1.0, v3
	v_rcp_f32_e32 v3, v3
	v_lshlrev_b32_e32 v12, 16, v215
	v_and_b32_e32 v13, 0xffff0000, v215
	v_pk_add_f32 v[6:7], v[6:7], v[12:13]
	v_lshlrev_b32_e32 v12, 16, v217
	v_pk_fma_f32 v[6:7], v[16:17], v[2:3], v[6:7]
	v_mul_f32_e32 v2, 0xbfb8aa3b, v5
	v_exp_f32_e32 v2, v2
	v_and_b32_e32 v3, 0xffff0000, v197
	v_and_b32_e32 v13, 0xffff0000, v217
	v_add_f32_e32 v2, 1.0, v2
	v_rcp_f32_e32 v5, v2
	v_lshlrev_b32_e32 v2, 16, v197
	v_pk_add_f32 v[2:3], v[2:3], v[12:13]
	s_nop 0
	v_pk_fma_f32 v[8:9], v[8:9], v[4:5], v[2:3]
	v_cvt_pk_bf16_f32 v2, v10, v11
	v_cvt_pk_bf16_f32 v3, v6, v7
	s_nop 0
	v_lshlrev_b32_e32 v4, 16, v2
	v_and_b32_e32 v5, 0xffff0000, v2
	v_lshlrev_b32_e32 v12, 16, v3
	v_and_b32_e32 v13, 0xffff0000, v3
	v_sub_f32_e32 v16, v6, v12
	v_sub_f32_e32 v7, v7, v13
	v_sub_f32_e32 v6, v10, v4
	v_sub_f32_e32 v10, v11, v5
	v_cvt_pk_bf16_f32 v6, v6, v10
	v_cvt_pk_bf16_f32 v7, v16, v7
	s_nop 0
	v_lshlrev_b32_e32 v10, 16, v6
	v_and_b32_e32 v11, 0xffff0000, v6
	v_lshlrev_b32_e32 v16, 16, v7
	v_and_b32_e32 v17, 0xffff0000, v7
	v_pk_add_f32 v[12:13], v[12:13], v[16:17]
	v_pk_add_f32 v[10:11], v[4:5], v[10:11]
	v_cvt_pk_bf16_f32 v4, v14, v15
	v_cvt_pk_bf16_f32 v5, v8, v9
	s_nop 0
	v_lshlrev_b32_e32 v16, 16, v4
	v_and_b32_e32 v17, 0xffff0000, v4
	v_lshlrev_b32_e32 v18, 16, v5
	v_and_b32_e32 v19, 0xffff0000, v5
	v_sub_f32_e32 v20, v8, v18
	v_sub_f32_e32 v9, v9, v19
	v_sub_f32_e32 v8, v14, v16
	v_sub_f32_e32 v14, v15, v17
	v_cvt_pk_bf16_f32 v8, v8, v14
	v_cvt_pk_bf16_f32 v9, v20, v9
	global_store_dwordx4 v[26:27], v[2:5], off
	global_store_dwordx4 v[28:29], v[6:9], off
	v_lshlrev_b32_e32 v14, 16, v8
	v_and_b32_e32 v15, 0xffff0000, v8
	v_mul_f32_e32 v2, v11, v11
	v_mul_f32_e32 v3, v13, v13
	v_pk_add_f32 v[14:15], v[16:17], v[14:15]
	v_fmac_f32_e32 v2, v10, v10
	v_fmac_f32_e32 v3, v12, v12
	v_lshlrev_b32_e32 v20, 16, v9
	v_and_b32_e32 v21, 0xffff0000, v9
	v_add_f32_e32 v2, v2, v3
	v_mul_f32_e32 v3, v15, v15
	v_pk_add_f32 v[18:19], v[18:19], v[20:21]
	v_fmac_f32_e32 v3, v14, v14
	v_add_f32_e32 v2, v2, v3
	v_mul_f32_e32 v3, v19, v19
	v_fmac_f32_e32 v3, v18, v18
	v_add_f32_e32 v2, v3, v2
	ds_bpermute_b32 v3, v204, v2
	s_waitcnt lgkmcnt(0)
	v_add_f32_e32 v2, v2, v3
	ds_bpermute_b32 v3, v205, v2
	s_and_saveexec_b64 s[24:25], s[10:11]
	s_cbranch_execz .LBB11_931
	s_ashr_i32 s23, s22, 31
	s_lshl_b64 s[0:1], s[22:23], 2
	s_add_u32 s0, s28, s0
	v_ashrrev_i32_e32 v149, 31, v148
	s_addc_u32 s1, s29, s1
	s_waitcnt lgkmcnt(0)
	v_add_f32_e32 v4, v2, v3
	v_add_f32_e32 v11, v126, v127
	v_lshl_add_u64 v[2:3], v[148:149], 2, s[0:1]
	v_add_f32_e32 v5, v30, v31
	v_add_f32_e32 v6, v46, v47
	v_add_f32_e32 v7, v62, v63
	v_add_f32_e32 v8, v78, v79
	v_add_f32_e32 v9, v94, v95
	v_add_f32_e32 v10, v110, v111
	global_atomic_add_f32 v[2:3], v11, off
	global_atomic_add_f32 v[2:3], v10, off offset:64
	global_atomic_add_f32 v[2:3], v9, off offset:128
	global_atomic_add_f32 v[2:3], v8, off offset:192
	global_atomic_add_f32 v[2:3], v7, off offset:512
	global_atomic_add_f32 v[2:3], v6, off offset:576
	global_atomic_add_f32 v[2:3], v5, off offset:640
	global_atomic_add_f32 v[2:3], v4, off offset:704

.LBB11_1632:
	v_mov_b32_e32 v141, v152
	v_mov_b32_e32 v140, v150
	s_lshl_b32 s22, s7, 8
	s_nop 0
	v_add_u32_e32 v144, s22, v140
	v_lshl_add_u32 v142, s6, 8, v141
	v_ashrrev_i32_e32 v145, 31, v144
	v_lshlrev_b64 v[148:149], 11, v[144:145]
	v_ashrrev_i32_e32 v143, 31, v142
	v_lshl_add_u64 v[146:147], s[66:67], 0, v[148:149]
	v_lshlrev_b64 v[142:143], 1, v[142:143]
	v_lshl_add_u64 v[146:147], v[146:147], 0, v[142:143]
	v_lshl_add_u64 v[148:149], s[64:65], 0, v[148:149]
	v_lshl_add_u64 v[148:149], v[148:149], 0, v[142:143]
	v_lshl_add_u32 v249, v144, 11, v142
	global_load_dwordx4 v[170:173], v249, s[66:67]
	global_load_dwordx4 v[174:177], v249, s[64:65]
	global_load_dwordx4 v[178:181], v249, s[66:67] offset:256
	global_load_dwordx4 v[190:193], v249, s[64:65] offset:256
	v_add_u32_e32 v251, 0x8000, v249
	global_load_dwordx4 v[194:197], v251, s[66:67]
	global_load_dwordx4 v[214:217], v251, s[64:65]
	v_add_u32_e32 v250, 0x8000, v249
	global_load_dwordx4 v[218:221], v250, s[66:67] offset:256
	global_load_dwordx4 v[222:225], v250, s[64:65] offset:256
	v_add_u32_e32 v251, 0x10000, v249
	global_load_dwordx4 v[226:229], v251, s[66:67]
	global_load_dwordx4 v[230:233], v251, s[64:65]
	s_waitcnt vmcnt(8)
	v_lshlrev_b32_e32 v162, 16, v170
	v_and_b32_e32 v163, 0xffff0000, v170
	v_lshlrev_b32_e32 v164, 16, v174
	v_and_b32_e32 v165, 0xffff0000, v174
	v_lshlrev_b32_e32 v154, 16, v171
	v_and_b32_e32 v155, 0xffff0000, v171
	v_lshlrev_b32_e32 v158, 16, v175
	v_and_b32_e32 v159, 0xffff0000, v175
	v_pk_add_f32 v[162:163], v[162:163], v[164:165]
	v_pk_add_f32 v[154:155], v[154:155], v[158:159]
	v_lshlrev_b32_e32 v158, 16, v172
	v_and_b32_e32 v159, 0xffff0000, v172
	v_lshlrev_b32_e32 v164, 16, v176
	v_and_b32_e32 v165, 0xffff0000, v176
	v_lshlrev_b32_e32 v156, 16, v173
	v_and_b32_e32 v157, 0xffff0000, v173
	v_lshlrev_b32_e32 v160, 16, v177
	v_and_b32_e32 v161, 0xffff0000, v177
	v_add_u32_e32 v250, 0x10000, v249
	global_load_dwordx4 v[170:173], v250, s[66:67] offset:256
	global_load_dwordx4 v[174:177], v250, s[64:65] offset:256
	v_pk_add_f32 v[158:159], v[158:159], v[164:165]
	v_pk_add_f32 v[156:157], v[156:157], v[160:161]
	v_pk_add_f32 v[128:129], v[128:129], v[154:155]
	v_pk_add_f32 v[126:127], v[126:127], v[162:163]
	v_pk_add_f32 v[154:155], v[124:125], v[156:157]
	v_pk_add_f32 v[156:157], v[122:123], v[158:159]
	v_cvt_pk_bf16_f32 v122, v126, v127
	v_cvt_pk_bf16_f32 v123, v128, v129
	s_nop 0
	v_lshlrev_b32_e32 v124, 16, v122
	v_and_b32_e32 v125, 0xffff0000, v122
	v_lshlrev_b32_e32 v158, 16, v123
	v_and_b32_e32 v159, 0xffff0000, v123
	v_sub_f32_e32 v128, v128, v158
	v_sub_f32_e32 v129, v129, v159
	v_sub_f32_e32 v126, v126, v124
	v_sub_f32_e32 v127, v127, v125
	v_cvt_pk_bf16_f32 v126, v126, v127
	v_cvt_pk_bf16_f32 v127, v128, v129
	s_nop 0
	v_lshlrev_b32_e32 v128, 16, v126
	v_and_b32_e32 v129, 0xffff0000, v126
	v_lshlrev_b32_e32 v160, 16, v127
	v_and_b32_e32 v161, 0xffff0000, v127
	v_pk_add_f32 v[158:159], v[158:159], v[160:161]
	v_pk_add_f32 v[160:161], v[124:125], v[128:129]
	v_cvt_pk_bf16_f32 v124, v156, v157
	v_cvt_pk_bf16_f32 v125, v154, v155
	s_nop 0
	v_lshlrev_b32_e32 v162, 16, v124
	v_lshlrev_b32_e32 v164, 16, v125
	v_and_b32_e32 v163, 0xffff0000, v124
	v_and_b32_e32 v165, 0xffff0000, v125
	v_sub_f32_e32 v129, v154, v164
	v_sub_f32_e32 v128, v156, v162
	v_sub_f32_e32 v141, v155, v165
	v_sub_f32_e32 v145, v157, v163
	v_cvt_pk_bf16_f32 v128, v128, v145
	v_cvt_pk_bf16_f32 v129, v129, v141
	global_store_dwordx4 v[146:147], v[122:125], off
	global_store_dwordx4 v[148:149], v[126:129], off
	v_lshlrev_b32_e32 v154, 16, v128
	v_and_b32_e32 v155, 0xffff0000, v128
	v_mul_f32_e32 v122, v161, v161
	v_mul_f32_e32 v123, v159, v159
	v_pk_add_f32 v[154:155], v[162:163], v[154:155]
	v_fmac_f32_e32 v122, v160, v160
	v_fmac_f32_e32 v123, v158, v158
	v_lshlrev_b32_e32 v156, 16, v129
	v_and_b32_e32 v157, 0xffff0000, v129
	v_add_f32_e32 v122, v122, v123
	v_mul_f32_e32 v123, v155, v155
	v_pk_add_f32 v[156:157], v[164:165], v[156:157]
	v_fmac_f32_e32 v123, v154, v154
	v_add_f32_e32 v122, v122, v123
	v_mul_f32_e32 v123, v157, v157
	v_fmac_f32_e32 v123, v156, v156
	v_add_f32_e32 v141, v123, v122
	s_waitcnt vmcnt(10)
	v_lshlrev_b32_e32 v154, 16, v178
	v_and_b32_e32 v155, 0xffff0000, v178
	v_lshlrev_b32_e32 v156, 16, v190
	v_and_b32_e32 v157, 0xffff0000, v190
	v_lshlrev_b32_e32 v122, 16, v179
	v_and_b32_e32 v123, 0xffff0000, v179
	v_lshlrev_b32_e32 v126, 16, v191
	v_and_b32_e32 v127, 0xffff0000, v191
	v_pk_add_f32 v[154:155], v[154:155], v[156:157]
	v_pk_add_f32 v[122:123], v[122:123], v[126:127]
	v_lshlrev_b32_e32 v126, 16, v180
	v_and_b32_e32 v127, 0xffff0000, v180
	v_lshlrev_b32_e32 v156, 16, v192
	v_and_b32_e32 v157, 0xffff0000, v192
	v_lshlrev_b32_e32 v124, 16, v181
	v_and_b32_e32 v125, 0xffff0000, v181
	v_lshlrev_b32_e32 v128, 16, v193
	v_and_b32_e32 v129, 0xffff0000, v193
	v_add_u32_e32 v251, 0x18000, v249
	global_load_dwordx4 v[178:181], v251, s[66:67]
	global_load_dwordx4 v[190:193], v251, s[64:65]
	v_pk_add_f32 v[126:127], v[126:127], v[156:157]
	v_pk_add_f32 v[124:125], v[124:125], v[128:129]
	v_pk_add_f32 v[120:121], v[120:121], v[122:123]
	v_pk_add_f32 v[118:119], v[118:119], v[154:155]
	v_pk_add_f32 v[122:123], v[116:117], v[124:125]
	v_pk_add_f32 v[124:125], v[114:115], v[126:127]
	v_cvt_pk_bf16_f32 v114, v118, v119
	v_cvt_pk_bf16_f32 v115, v120, v121
	s_nop 0
	v_lshlrev_b32_e32 v116, 16, v114
	v_and_b32_e32 v117, 0xffff0000, v114
	v_lshlrev_b32_e32 v126, 16, v115
	v_and_b32_e32 v127, 0xffff0000, v115
	v_sub_f32_e32 v120, v120, v126
	v_sub_f32_e32 v121, v121, v127
	v_sub_f32_e32 v118, v118, v116
	v_sub_f32_e32 v119, v119, v117
	v_cvt_pk_bf16_f32 v118, v118, v119
	v_cvt_pk_bf16_f32 v119, v120, v121
	s_nop 0
	v_lshlrev_b32_e32 v120, 16, v118
	v_and_b32_e32 v121, 0xffff0000, v118
	v_lshlrev_b32_e32 v128, 16, v119
	v_and_b32_e32 v129, 0xffff0000, v119
	v_pk_add_f32 v[126:127], v[126:127], v[128:129]
	v_pk_add_f32 v[128:129], v[116:117], v[120:121]
	v_cvt_pk_bf16_f32 v116, v124, v125
	v_cvt_pk_bf16_f32 v117, v122, v123
	s_nop 0
	v_lshlrev_b32_e32 v154, 16, v116
	v_and_b32_e32 v155, 0xffff0000, v116
	v_lshlrev_b32_e32 v156, 16, v117
	v_and_b32_e32 v157, 0xffff0000, v117
	v_sub_f32_e32 v121, v122, v156
	v_sub_f32_e32 v122, v123, v157
	v_sub_f32_e32 v120, v124, v154
	v_sub_f32_e32 v123, v125, v155
	v_cvt_pk_bf16_f32 v120, v120, v123
	v_cvt_pk_bf16_f32 v121, v121, v122
	global_store_dwordx4 v[146:147], v[114:117], off offset:256
	global_store_dwordx4 v[148:149], v[118:121], off offset:256
	v_lshlrev_b32_e32 v122, 16, v120
	v_and_b32_e32 v123, 0xffff0000, v120
	v_mul_f32_e32 v114, v129, v129
	v_mul_f32_e32 v115, v127, v127
	v_pk_add_f32 v[122:123], v[154:155], v[122:123]
	v_fmac_f32_e32 v114, v128, v128
	v_fmac_f32_e32 v115, v126, v126
	v_lshlrev_b32_e32 v124, 16, v121
	v_and_b32_e32 v125, 0xffff0000, v121
	v_add_f32_e32 v114, v114, v115
	v_mul_f32_e32 v115, v123, v123
	v_pk_add_f32 v[124:125], v[156:157], v[124:125]
	v_fmac_f32_e32 v115, v122, v122
	v_add_f32_e32 v114, v114, v115
	v_mul_f32_e32 v115, v125, v125
	v_fmac_f32_e32 v115, v124, v124
	v_add_f32_e32 v114, v115, v114
	v_add_f32_e32 v114, v141, v114
	ds_bpermute_b32 v115, v204, v114
	s_waitcnt lgkmcnt(0)
	v_add_f32_e32 v118, v114, v115
	v_add_u32_e32 v114, 16, v144
	v_ashrrev_i32_e32 v115, 31, v114
	v_lshlrev_b64 v[116:117], 11, v[114:115]
	v_lshl_add_u64 v[114:115], s[66:67], 0, v[116:117]
	v_lshl_add_u64 v[114:115], v[114:115], 0, v[142:143]
	v_lshl_add_u64 v[116:117], s[64:65], 0, v[116:117]
	v_lshl_add_u64 v[116:117], v[116:117], 0, v[142:143]
	ds_bpermute_b32 v119, v205, v118
	s_waitcnt vmcnt(12)
	v_lshlrev_b32_e32 v128, 16, v194
	v_and_b32_e32 v129, 0xffff0000, v194
	v_lshlrev_b32_e32 v146, 16, v214
	v_and_b32_e32 v147, 0xffff0000, v214
	v_lshlrev_b32_e32 v120, 16, v195
	v_and_b32_e32 v121, 0xffff0000, v195
	v_lshlrev_b32_e32 v124, 16, v215
	v_and_b32_e32 v125, 0xffff0000, v215
	v_pk_add_f32 v[128:129], v[128:129], v[146:147]
	v_pk_add_f32 v[120:121], v[120:121], v[124:125]
	v_lshlrev_b32_e32 v124, 16, v196
	v_and_b32_e32 v125, 0xffff0000, v196
	v_lshlrev_b32_e32 v146, 16, v216
	v_and_b32_e32 v147, 0xffff0000, v216
	v_lshlrev_b32_e32 v122, 16, v197
	v_and_b32_e32 v123, 0xffff0000, v197
	v_lshlrev_b32_e32 v126, 16, v217
	v_and_b32_e32 v127, 0xffff0000, v217
	v_add_u32_e32 v250, 0x18000, v249
	global_load_dwordx4 v[194:197], v250, s[66:67] offset:256
	global_load_dwordx4 v[214:217], v250, s[64:65] offset:256
	v_pk_add_f32 v[124:125], v[124:125], v[146:147]
	v_pk_add_f32 v[122:123], v[122:123], v[126:127]
	v_pk_add_f32 v[112:113], v[112:113], v[120:121]
	v_pk_add_f32 v[110:111], v[110:111], v[128:129]
	v_pk_add_f32 v[120:121], v[108:109], v[122:123]
	v_pk_add_f32 v[122:123], v[106:107], v[124:125]
	v_cvt_pk_bf16_f32 v106, v110, v111
	v_cvt_pk_bf16_f32 v107, v112, v113
	s_nop 0
	v_lshlrev_b32_e32 v108, 16, v106
	v_and_b32_e32 v109, 0xffff0000, v106
	v_lshlrev_b32_e32 v124, 16, v107
	v_and_b32_e32 v125, 0xffff0000, v107
	v_sub_f32_e32 v112, v112, v124
	v_sub_f32_e32 v113, v113, v125
	v_sub_f32_e32 v110, v110, v108
	v_sub_f32_e32 v111, v111, v109
	v_cvt_pk_bf16_f32 v110, v110, v111
	v_cvt_pk_bf16_f32 v111, v112, v113
	s_nop 0
	v_lshlrev_b32_e32 v112, 16, v110
	v_and_b32_e32 v113, 0xffff0000, v110
	v_lshlrev_b32_e32 v126, 16, v111
	v_and_b32_e32 v127, 0xffff0000, v111
	v_pk_add_f32 v[124:125], v[124:125], v[126:127]
	v_pk_add_f32 v[126:127], v[108:109], v[112:113]
	v_cvt_pk_bf16_f32 v108, v122, v123
	v_cvt_pk_bf16_f32 v109, v120, v121
	s_nop 0
	v_lshlrev_b32_e32 v128, 16, v108
	v_and_b32_e32 v129, 0xffff0000, v108
	v_lshlrev_b32_e32 v146, 16, v109
	v_and_b32_e32 v147, 0xffff0000, v109
	v_sub_f32_e32 v113, v120, v146
	v_sub_f32_e32 v120, v121, v147
	v_sub_f32_e32 v112, v122, v128
	v_sub_f32_e32 v121, v123, v129
	v_cvt_pk_bf16_f32 v112, v112, v121
	v_cvt_pk_bf16_f32 v113, v113, v120
	global_store_dwordx4 v[114:115], v[106:109], off
	global_store_dwordx4 v[116:117], v[110:113], off
	v_lshlrev_b32_e32 v120, 16, v112
	v_and_b32_e32 v121, 0xffff0000, v112
	v_mul_f32_e32 v106, v127, v127
	v_mul_f32_e32 v107, v125, v125
	v_pk_add_f32 v[120:121], v[128:129], v[120:121]
	v_fmac_f32_e32 v106, v126, v126
	v_fmac_f32_e32 v107, v124, v124
	v_lshlrev_b32_e32 v122, 16, v113
	v_and_b32_e32 v123, 0xffff0000, v113
	v_add_f32_e32 v106, v106, v107
	v_mul_f32_e32 v107, v121, v121
	v_pk_add_f32 v[122:123], v[146:147], v[122:123]
	v_fmac_f32_e32 v107, v120, v120
	v_add_f32_e32 v106, v106, v107
	v_mul_f32_e32 v107, v123, v123
	v_fmac_f32_e32 v107, v122, v122
	v_add_f32_e32 v124, v107, v106
	s_waitcnt vmcnt(14)
	v_lshlrev_b32_e32 v120, 16, v218
	v_and_b32_e32 v121, 0xffff0000, v218
	v_lshlrev_b32_e32 v122, 16, v222
	v_and_b32_e32 v123, 0xffff0000, v222
	v_lshlrev_b32_e32 v106, 16, v219
	v_and_b32_e32 v107, 0xffff0000, v219
	v_lshlrev_b32_e32 v110, 16, v223
	v_and_b32_e32 v111, 0xffff0000, v223
	v_pk_add_f32 v[120:121], v[120:121], v[122:123]
	v_pk_add_f32 v[106:107], v[106:107], v[110:111]
	v_lshlrev_b32_e32 v110, 16, v220
	v_and_b32_e32 v111, 0xffff0000, v220
	v_lshlrev_b32_e32 v122, 16, v224
	v_and_b32_e32 v123, 0xffff0000, v224
	v_lshlrev_b32_e32 v108, 16, v221
	v_and_b32_e32 v109, 0xffff0000, v221
	v_lshlrev_b32_e32 v112, 16, v225
	v_and_b32_e32 v113, 0xffff0000, v225
	v_add_u32_e32 v251, 0x40000, v249
	global_load_dwordx4 v[218:221], v251, s[66:67]
	global_load_dwordx4 v[222:225], v251, s[64:65]
	v_pk_add_f32 v[110:111], v[110:111], v[122:123]
	v_pk_add_f32 v[108:109], v[108:109], v[112:113]
	v_pk_add_f32 v[104:105], v[104:105], v[106:107]
	v_pk_add_f32 v[102:103], v[102:103], v[120:121]
	v_pk_add_f32 v[106:107], v[100:101], v[108:109]
	v_pk_add_f32 v[108:109], v[98:99], v[110:111]
	v_cvt_pk_bf16_f32 v98, v102, v103
	v_cvt_pk_bf16_f32 v99, v104, v105
	s_nop 0
	v_lshlrev_b32_e32 v100, 16, v98
	v_and_b32_e32 v101, 0xffff0000, v98
	v_lshlrev_b32_e32 v110, 16, v99
	v_and_b32_e32 v111, 0xffff0000, v99
	v_sub_f32_e32 v104, v104, v110
	v_sub_f32_e32 v105, v105, v111
	v_sub_f32_e32 v102, v102, v100
	v_sub_f32_e32 v103, v103, v101
	v_cvt_pk_bf16_f32 v102, v102, v103
	v_cvt_pk_bf16_f32 v103, v104, v105
	s_nop 0
	v_lshlrev_b32_e32 v104, 16, v102
	v_and_b32_e32 v105, 0xffff0000, v102
	v_lshlrev_b32_e32 v112, 16, v103
	v_and_b32_e32 v113, 0xffff0000, v103
	v_pk_add_f32 v[110:111], v[110:111], v[112:113]
	v_pk_add_f32 v[112:113], v[100:101], v[104:105]
	v_cvt_pk_bf16_f32 v100, v108, v109
	v_cvt_pk_bf16_f32 v101, v106, v107
	s_nop 0
	v_lshlrev_b32_e32 v120, 16, v100
	v_and_b32_e32 v121, 0xffff0000, v100
	v_lshlrev_b32_e32 v122, 16, v101
	v_and_b32_e32 v123, 0xffff0000, v101
	v_sub_f32_e32 v105, v106, v122
	v_sub_f32_e32 v106, v107, v123
	v_sub_f32_e32 v104, v108, v120
	v_sub_f32_e32 v107, v109, v121
	v_cvt_pk_bf16_f32 v104, v104, v107
	v_cvt_pk_bf16_f32 v105, v105, v106
	global_store_dwordx4 v[114:115], v[98:101], off offset:256
	global_store_dwordx4 v[116:117], v[102:105], off offset:256
	v_lshlrev_b32_e32 v106, 16, v104
	v_and_b32_e32 v107, 0xffff0000, v104
	v_mul_f32_e32 v98, v113, v113
	v_mul_f32_e32 v99, v111, v111
	v_pk_add_f32 v[106:107], v[120:121], v[106:107]
	v_fmac_f32_e32 v98, v112, v112
	v_fmac_f32_e32 v99, v110, v110
	v_lshlrev_b32_e32 v108, 16, v105
	v_and_b32_e32 v109, 0xffff0000, v105
	v_add_f32_e32 v98, v98, v99
	v_mul_f32_e32 v99, v107, v107
	v_pk_add_f32 v[108:109], v[122:123], v[108:109]
	v_fmac_f32_e32 v99, v106, v106
	v_add_f32_e32 v98, v98, v99
	v_mul_f32_e32 v99, v109, v109
	v_fmac_f32_e32 v99, v108, v108
	v_add_f32_e32 v98, v99, v98
	v_add_f32_e32 v98, v124, v98
	ds_bpermute_b32 v99, v204, v98
	s_waitcnt lgkmcnt(0)
	v_add_f32_e32 v102, v98, v99
	v_add_u32_e32 v98, 32, v144
	v_ashrrev_i32_e32 v99, 31, v98
	v_lshlrev_b64 v[100:101], 11, v[98:99]
	v_lshl_add_u64 v[98:99], s[66:67], 0, v[100:101]
	v_lshl_add_u64 v[98:99], v[98:99], 0, v[142:143]
	v_lshl_add_u64 v[100:101], s[64:65], 0, v[100:101]
	v_lshl_add_u64 v[100:101], v[100:101], 0, v[142:143]
	ds_bpermute_b32 v103, v205, v102
	s_waitcnt vmcnt(16)
	v_lshlrev_b32_e32 v112, 16, v226
	v_and_b32_e32 v113, 0xffff0000, v226
	v_lshlrev_b32_e32 v114, 16, v230
	v_and_b32_e32 v115, 0xffff0000, v230
	v_lshlrev_b32_e32 v104, 16, v227
	v_and_b32_e32 v105, 0xffff0000, v227
	v_lshlrev_b32_e32 v108, 16, v231
	v_and_b32_e32 v109, 0xffff0000, v231
	v_pk_add_f32 v[112:113], v[112:113], v[114:115]
	v_pk_add_f32 v[104:105], v[104:105], v[108:109]
	v_lshlrev_b32_e32 v108, 16, v228
	v_and_b32_e32 v109, 0xffff0000, v228
	v_lshlrev_b32_e32 v114, 16, v232
	v_and_b32_e32 v115, 0xffff0000, v232
	v_lshlrev_b32_e32 v106, 16, v229
	v_and_b32_e32 v107, 0xffff0000, v229
	v_lshlrev_b32_e32 v110, 16, v233
	v_and_b32_e32 v111, 0xffff0000, v233
	v_add_u32_e32 v250, 0x40000, v249
	global_load_dwordx4 v[226:229], v250, s[66:67] offset:256
	global_load_dwordx4 v[230:233], v250, s[64:65] offset:256
	v_pk_add_f32 v[108:109], v[108:109], v[114:115]
	v_pk_add_f32 v[106:107], v[106:107], v[110:111]
	v_pk_add_f32 v[96:97], v[96:97], v[104:105]
	v_pk_add_f32 v[94:95], v[94:95], v[112:113]
	v_pk_add_f32 v[104:105], v[92:93], v[106:107]
	v_pk_add_f32 v[106:107], v[90:91], v[108:109]
	v_cvt_pk_bf16_f32 v90, v94, v95
	v_cvt_pk_bf16_f32 v91, v96, v97
	s_nop 0
	v_lshlrev_b32_e32 v92, 16, v90
	v_and_b32_e32 v93, 0xffff0000, v90
	v_lshlrev_b32_e32 v108, 16, v91
	v_and_b32_e32 v109, 0xffff0000, v91
	v_sub_f32_e32 v96, v96, v108
	v_sub_f32_e32 v97, v97, v109
	v_sub_f32_e32 v94, v94, v92
	v_sub_f32_e32 v95, v95, v93
	v_cvt_pk_bf16_f32 v94, v94, v95
	v_cvt_pk_bf16_f32 v95, v96, v97
	s_nop 0
	v_lshlrev_b32_e32 v96, 16, v94
	v_and_b32_e32 v97, 0xffff0000, v94
	v_lshlrev_b32_e32 v110, 16, v95
	v_and_b32_e32 v111, 0xffff0000, v95
	v_pk_add_f32 v[108:109], v[108:109], v[110:111]
	v_pk_add_f32 v[110:111], v[92:93], v[96:97]
	v_cvt_pk_bf16_f32 v92, v106, v107
	v_cvt_pk_bf16_f32 v93, v104, v105
	s_nop 0
	v_lshlrev_b32_e32 v112, 16, v92
	v_and_b32_e32 v113, 0xffff0000, v92
	v_lshlrev_b32_e32 v114, 16, v93
	v_and_b32_e32 v115, 0xffff0000, v93
	v_sub_f32_e32 v97, v104, v114
	v_sub_f32_e32 v104, v105, v115
	v_sub_f32_e32 v96, v106, v112
	v_sub_f32_e32 v105, v107, v113
	v_cvt_pk_bf16_f32 v96, v96, v105
	v_cvt_pk_bf16_f32 v97, v97, v104
	global_store_dwordx4 v[98:99], v[90:93], off
	global_store_dwordx4 v[100:101], v[94:97], off
	v_lshlrev_b32_e32 v104, 16, v96
	v_and_b32_e32 v105, 0xffff0000, v96
	v_mul_f32_e32 v90, v111, v111
	v_mul_f32_e32 v91, v109, v109
	v_pk_add_f32 v[104:105], v[112:113], v[104:105]
	v_fmac_f32_e32 v90, v110, v110
	v_fmac_f32_e32 v91, v108, v108
	v_lshlrev_b32_e32 v106, 16, v97
	v_and_b32_e32 v107, 0xffff0000, v97
	v_add_f32_e32 v90, v90, v91
	v_mul_f32_e32 v91, v105, v105
	v_pk_add_f32 v[106:107], v[114:115], v[106:107]
	v_fmac_f32_e32 v91, v104, v104
	v_add_f32_e32 v90, v90, v91
	v_mul_f32_e32 v91, v107, v107
	v_fmac_f32_e32 v91, v106, v106
	v_add_f32_e32 v108, v91, v90
	s_waitcnt vmcnt(18)
	v_lshlrev_b32_e32 v104, 16, v170
	v_and_b32_e32 v105, 0xffff0000, v170
	v_lshlrev_b32_e32 v106, 16, v174
	v_and_b32_e32 v107, 0xffff0000, v174
	v_lshlrev_b32_e32 v90, 16, v171
	v_and_b32_e32 v91, 0xffff0000, v171
	v_lshlrev_b32_e32 v94, 16, v175
	v_and_b32_e32 v95, 0xffff0000, v175
	v_pk_add_f32 v[104:105], v[104:105], v[106:107]
	v_pk_add_f32 v[90:91], v[90:91], v[94:95]
	v_lshlrev_b32_e32 v94, 16, v172
	v_and_b32_e32 v95, 0xffff0000, v172
	v_lshlrev_b32_e32 v106, 16, v176
	v_and_b32_e32 v107, 0xffff0000, v176
	v_lshlrev_b32_e32 v92, 16, v173
	v_and_b32_e32 v93, 0xffff0000, v173
	v_lshlrev_b32_e32 v96, 16, v177
	v_and_b32_e32 v97, 0xffff0000, v177
	v_add_u32_e32 v251, 0x48000, v249
	global_load_dwordx4 v[170:173], v251, s[66:67]
	global_load_dwordx4 v[174:177], v251, s[64:65]
	v_pk_add_f32 v[94:95], v[94:95], v[106:107]
	v_pk_add_f32 v[92:93], v[92:93], v[96:97]
	v_pk_add_f32 v[88:89], v[88:89], v[90:91]
	v_pk_add_f32 v[86:87], v[86:87], v[104:105]
	v_pk_add_f32 v[90:91], v[84:85], v[92:93]
	v_pk_add_f32 v[92:93], v[82:83], v[94:95]
	v_cvt_pk_bf16_f32 v82, v86, v87
	v_cvt_pk_bf16_f32 v83, v88, v89
	s_nop 0
	v_lshlrev_b32_e32 v84, 16, v82
	v_and_b32_e32 v85, 0xffff0000, v82
	v_lshlrev_b32_e32 v94, 16, v83
	v_and_b32_e32 v95, 0xffff0000, v83
	v_sub_f32_e32 v88, v88, v94
	v_sub_f32_e32 v89, v89, v95
	v_sub_f32_e32 v86, v86, v84
	v_sub_f32_e32 v87, v87, v85
	v_cvt_pk_bf16_f32 v86, v86, v87
	v_cvt_pk_bf16_f32 v87, v88, v89
	s_nop 0
	v_lshlrev_b32_e32 v88, 16, v86
	v_and_b32_e32 v89, 0xffff0000, v86
	v_lshlrev_b32_e32 v96, 16, v87
	v_and_b32_e32 v97, 0xffff0000, v87
	v_pk_add_f32 v[94:95], v[94:95], v[96:97]
	v_pk_add_f32 v[96:97], v[84:85], v[88:89]
	v_cvt_pk_bf16_f32 v84, v92, v93
	v_cvt_pk_bf16_f32 v85, v90, v91
	s_nop 0
	v_lshlrev_b32_e32 v104, 16, v84
	v_and_b32_e32 v105, 0xffff0000, v84
	v_lshlrev_b32_e32 v106, 16, v85
	v_and_b32_e32 v107, 0xffff0000, v85
	v_sub_f32_e32 v89, v90, v106
	v_sub_f32_e32 v90, v91, v107
	v_sub_f32_e32 v88, v92, v104
	v_sub_f32_e32 v91, v93, v105
	v_cvt_pk_bf16_f32 v88, v88, v91
	v_cvt_pk_bf16_f32 v89, v89, v90
	global_store_dwordx4 v[98:99], v[82:85], off offset:256
	global_store_dwordx4 v[100:101], v[86:89], off offset:256
	v_lshlrev_b32_e32 v90, 16, v88
	v_and_b32_e32 v91, 0xffff0000, v88
	v_mul_f32_e32 v82, v97, v97
	v_mul_f32_e32 v83, v95, v95
	v_pk_add_f32 v[90:91], v[104:105], v[90:91]
	v_fmac_f32_e32 v82, v96, v96
	v_fmac_f32_e32 v83, v94, v94
	v_lshlrev_b32_e32 v92, 16, v89
	v_and_b32_e32 v93, 0xffff0000, v89
	v_add_f32_e32 v82, v82, v83
	v_mul_f32_e32 v83, v91, v91
	v_pk_add_f32 v[92:93], v[106:107], v[92:93]
	v_fmac_f32_e32 v83, v90, v90
	v_add_f32_e32 v82, v82, v83
	v_mul_f32_e32 v83, v93, v93
	v_fmac_f32_e32 v83, v92, v92
	v_add_f32_e32 v82, v83, v82
	v_add_f32_e32 v82, v108, v82
	ds_bpermute_b32 v83, v204, v82
	s_waitcnt lgkmcnt(0)
	v_add_f32_e32 v86, v82, v83
	v_add_u32_e32 v82, 48, v144
	v_ashrrev_i32_e32 v83, 31, v82
	v_lshlrev_b64 v[84:85], 11, v[82:83]
	v_lshl_add_u64 v[82:83], s[66:67], 0, v[84:85]
	v_lshl_add_u64 v[82:83], v[82:83], 0, v[142:143]
	v_lshl_add_u64 v[84:85], s[64:65], 0, v[84:85]
	v_lshl_add_u64 v[84:85], v[84:85], 0, v[142:143]
	ds_bpermute_b32 v87, v205, v86
	s_waitcnt vmcnt(18)
	v_lshlrev_b32_e32 v96, 16, v178
	v_and_b32_e32 v97, 0xffff0000, v178
	v_lshlrev_b32_e32 v98, 16, v190
	v_and_b32_e32 v99, 0xffff0000, v190
	v_lshlrev_b32_e32 v88, 16, v179
	v_and_b32_e32 v89, 0xffff0000, v179
	v_lshlrev_b32_e32 v92, 16, v191
	v_and_b32_e32 v93, 0xffff0000, v191
	v_pk_add_f32 v[96:97], v[96:97], v[98:99]
	v_pk_add_f32 v[88:89], v[88:89], v[92:93]
	v_lshlrev_b32_e32 v92, 16, v180
	v_and_b32_e32 v93, 0xffff0000, v180
	v_lshlrev_b32_e32 v98, 16, v192
	v_and_b32_e32 v99, 0xffff0000, v192
	v_lshlrev_b32_e32 v90, 16, v181
	v_and_b32_e32 v91, 0xffff0000, v181
	v_lshlrev_b32_e32 v94, 16, v193
	v_and_b32_e32 v95, 0xffff0000, v193
	v_add_u32_e32 v250, 0x48000, v249
	global_load_dwordx4 v[178:181], v250, s[66:67] offset:256
	global_load_dwordx4 v[190:193], v250, s[64:65] offset:256
	v_pk_add_f32 v[92:93], v[92:93], v[98:99]
	v_pk_add_f32 v[90:91], v[90:91], v[94:95]
	v_pk_add_f32 v[80:81], v[80:81], v[88:89]
	v_pk_add_f32 v[78:79], v[78:79], v[96:97]
	v_pk_add_f32 v[88:89], v[76:77], v[90:91]
	v_pk_add_f32 v[90:91], v[74:75], v[92:93]
	v_cvt_pk_bf16_f32 v74, v78, v79
	v_cvt_pk_bf16_f32 v75, v80, v81
	s_nop 0
	v_lshlrev_b32_e32 v76, 16, v74
	v_and_b32_e32 v77, 0xffff0000, v74
	v_lshlrev_b32_e32 v92, 16, v75
	v_and_b32_e32 v93, 0xffff0000, v75
	v_sub_f32_e32 v80, v80, v92
	v_sub_f32_e32 v81, v81, v93
	v_sub_f32_e32 v78, v78, v76
	v_sub_f32_e32 v79, v79, v77
	v_cvt_pk_bf16_f32 v78, v78, v79
	v_cvt_pk_bf16_f32 v79, v80, v81
	s_nop 0
	v_lshlrev_b32_e32 v80, 16, v78
	v_and_b32_e32 v81, 0xffff0000, v78
	v_lshlrev_b32_e32 v94, 16, v79
	v_and_b32_e32 v95, 0xffff0000, v79
	v_pk_add_f32 v[92:93], v[92:93], v[94:95]
	v_pk_add_f32 v[94:95], v[76:77], v[80:81]
	v_cvt_pk_bf16_f32 v76, v90, v91
	v_cvt_pk_bf16_f32 v77, v88, v89
	s_nop 0
	v_lshlrev_b32_e32 v96, 16, v76
	v_and_b32_e32 v97, 0xffff0000, v76
	v_lshlrev_b32_e32 v98, 16, v77
	v_and_b32_e32 v99, 0xffff0000, v77
	v_sub_f32_e32 v81, v88, v98
	v_sub_f32_e32 v88, v89, v99
	v_sub_f32_e32 v80, v90, v96
	v_sub_f32_e32 v89, v91, v97
	v_cvt_pk_bf16_f32 v80, v80, v89
	v_cvt_pk_bf16_f32 v81, v81, v88
	global_store_dwordx4 v[82:83], v[74:77], off
	global_store_dwordx4 v[84:85], v[78:81], off
	v_lshlrev_b32_e32 v88, 16, v80
	v_and_b32_e32 v89, 0xffff0000, v80
	v_mul_f32_e32 v74, v95, v95
	v_mul_f32_e32 v75, v93, v93
	v_pk_add_f32 v[88:89], v[96:97], v[88:89]
	v_fmac_f32_e32 v74, v94, v94
	v_fmac_f32_e32 v75, v92, v92
	v_lshlrev_b32_e32 v90, 16, v81
	v_and_b32_e32 v91, 0xffff0000, v81
	v_add_f32_e32 v74, v74, v75
	v_mul_f32_e32 v75, v89, v89
	v_pk_add_f32 v[90:91], v[98:99], v[90:91]
	v_fmac_f32_e32 v75, v88, v88
	v_add_f32_e32 v74, v74, v75
	v_mul_f32_e32 v75, v91, v91
	v_fmac_f32_e32 v75, v90, v90
	v_add_f32_e32 v92, v75, v74
	s_waitcnt vmcnt(18)
	v_lshlrev_b32_e32 v88, 16, v194
	v_and_b32_e32 v89, 0xffff0000, v194
	v_lshlrev_b32_e32 v90, 16, v214
	v_and_b32_e32 v91, 0xffff0000, v214
	v_lshlrev_b32_e32 v74, 16, v195
	v_and_b32_e32 v75, 0xffff0000, v195
	v_lshlrev_b32_e32 v78, 16, v215
	v_and_b32_e32 v79, 0xffff0000, v215
	v_pk_add_f32 v[88:89], v[88:89], v[90:91]
	v_pk_add_f32 v[74:75], v[74:75], v[78:79]
	v_lshlrev_b32_e32 v78, 16, v196
	v_and_b32_e32 v79, 0xffff0000, v196
	v_lshlrev_b32_e32 v90, 16, v216
	v_and_b32_e32 v91, 0xffff0000, v216
	v_lshlrev_b32_e32 v76, 16, v197
	v_and_b32_e32 v77, 0xffff0000, v197
	v_lshlrev_b32_e32 v80, 16, v217
	v_and_b32_e32 v81, 0xffff0000, v217
	v_add_u32_e32 v251, 0x50000, v249
	global_load_dwordx4 v[194:197], v251, s[66:67]
	global_load_dwordx4 v[214:217], v251, s[64:65]
	v_pk_add_f32 v[78:79], v[78:79], v[90:91]
	v_pk_add_f32 v[76:77], v[76:77], v[80:81]
	v_pk_add_f32 v[72:73], v[72:73], v[74:75]
	v_pk_add_f32 v[70:71], v[70:71], v[88:89]
	v_pk_add_f32 v[74:75], v[68:69], v[76:77]
	v_pk_add_f32 v[76:77], v[66:67], v[78:79]
	v_cvt_pk_bf16_f32 v66, v70, v71
	v_cvt_pk_bf16_f32 v67, v72, v73
	s_nop 0
	v_lshlrev_b32_e32 v68, 16, v66
	v_and_b32_e32 v69, 0xffff0000, v66
	v_lshlrev_b32_e32 v78, 16, v67
	v_and_b32_e32 v79, 0xffff0000, v67
	v_sub_f32_e32 v72, v72, v78
	v_sub_f32_e32 v73, v73, v79
	v_sub_f32_e32 v70, v70, v68
	v_sub_f32_e32 v71, v71, v69
	v_cvt_pk_bf16_f32 v70, v70, v71
	v_cvt_pk_bf16_f32 v71, v72, v73
	s_nop 0
	v_lshlrev_b32_e32 v72, 16, v70
	v_and_b32_e32 v73, 0xffff0000, v70
	v_lshlrev_b32_e32 v80, 16, v71
	v_and_b32_e32 v81, 0xffff0000, v71
	v_pk_add_f32 v[78:79], v[78:79], v[80:81]
	v_pk_add_f32 v[80:81], v[68:69], v[72:73]
	v_cvt_pk_bf16_f32 v68, v76, v77
	v_cvt_pk_bf16_f32 v69, v74, v75
	s_nop 0
	v_lshlrev_b32_e32 v88, 16, v68
	v_and_b32_e32 v89, 0xffff0000, v68
	v_lshlrev_b32_e32 v90, 16, v69
	v_and_b32_e32 v91, 0xffff0000, v69
	v_sub_f32_e32 v73, v74, v90
	v_sub_f32_e32 v74, v75, v91
	v_sub_f32_e32 v72, v76, v88
	v_sub_f32_e32 v75, v77, v89
	v_cvt_pk_bf16_f32 v72, v72, v75
	v_cvt_pk_bf16_f32 v73, v73, v74
	global_store_dwordx4 v[82:83], v[66:69], off offset:256
	global_store_dwordx4 v[84:85], v[70:73], off offset:256
	v_lshlrev_b32_e32 v74, 16, v72
	v_and_b32_e32 v75, 0xffff0000, v72
	v_mul_f32_e32 v66, v81, v81
	v_mul_f32_e32 v67, v79, v79
	v_pk_add_f32 v[74:75], v[88:89], v[74:75]
	v_fmac_f32_e32 v66, v80, v80
	v_fmac_f32_e32 v67, v78, v78
	v_lshlrev_b32_e32 v76, 16, v73
	v_and_b32_e32 v77, 0xffff0000, v73
	v_add_f32_e32 v66, v66, v67
	v_mul_f32_e32 v67, v75, v75
	v_pk_add_f32 v[76:77], v[90:91], v[76:77]
	v_fmac_f32_e32 v67, v74, v74
	v_add_f32_e32 v66, v66, v67
	v_mul_f32_e32 v67, v77, v77
	v_fmac_f32_e32 v67, v76, v76
	v_add_f32_e32 v66, v67, v66
	v_add_f32_e32 v66, v92, v66
	ds_bpermute_b32 v67, v204, v66
	s_waitcnt lgkmcnt(0)
	v_add_f32_e32 v70, v66, v67
	v_add_u32_e32 v66, 0x80, v144
	v_ashrrev_i32_e32 v67, 31, v66
	v_lshlrev_b64 v[68:69], 11, v[66:67]
	v_lshl_add_u64 v[66:67], s[66:67], 0, v[68:69]
	v_lshl_add_u64 v[66:67], v[66:67], 0, v[142:143]
	v_lshl_add_u64 v[68:69], s[64:65], 0, v[68:69]
	v_lshl_add_u64 v[68:69], v[68:69], 0, v[142:143]
	ds_bpermute_b32 v71, v205, v70
	s_waitcnt vmcnt(18)
	v_lshlrev_b32_e32 v80, 16, v218
	v_and_b32_e32 v81, 0xffff0000, v218
	v_lshlrev_b32_e32 v82, 16, v222
	v_and_b32_e32 v83, 0xffff0000, v222
	v_lshlrev_b32_e32 v72, 16, v219
	v_and_b32_e32 v73, 0xffff0000, v219
	v_lshlrev_b32_e32 v76, 16, v223
	v_and_b32_e32 v77, 0xffff0000, v223
	v_pk_add_f32 v[80:81], v[80:81], v[82:83]
	v_pk_add_f32 v[72:73], v[72:73], v[76:77]
	v_lshlrev_b32_e32 v76, 16, v220
	v_and_b32_e32 v77, 0xffff0000, v220
	v_lshlrev_b32_e32 v82, 16, v224
	v_and_b32_e32 v83, 0xffff0000, v224
	v_lshlrev_b32_e32 v74, 16, v221
	v_and_b32_e32 v75, 0xffff0000, v221
	v_lshlrev_b32_e32 v78, 16, v225
	v_and_b32_e32 v79, 0xffff0000, v225
	v_add_u32_e32 v250, 0x50000, v249
	global_load_dwordx4 v[218:221], v250, s[66:67] offset:256
	global_load_dwordx4 v[222:225], v250, s[64:65] offset:256
	v_pk_add_f32 v[76:77], v[76:77], v[82:83]
	v_pk_add_f32 v[74:75], v[74:75], v[78:79]
	v_pk_add_f32 v[64:65], v[64:65], v[72:73]
	v_pk_add_f32 v[62:63], v[62:63], v[80:81]
	v_pk_add_f32 v[72:73], v[60:61], v[74:75]
	v_pk_add_f32 v[74:75], v[58:59], v[76:77]
	v_cvt_pk_bf16_f32 v58, v62, v63
	v_cvt_pk_bf16_f32 v59, v64, v65
	s_nop 0
	v_lshlrev_b32_e32 v60, 16, v58
	v_and_b32_e32 v61, 0xffff0000, v58
	v_lshlrev_b32_e32 v76, 16, v59
	v_and_b32_e32 v77, 0xffff0000, v59
	v_sub_f32_e32 v64, v64, v76
	v_sub_f32_e32 v65, v65, v77
	v_sub_f32_e32 v62, v62, v60
	v_sub_f32_e32 v63, v63, v61
	v_cvt_pk_bf16_f32 v62, v62, v63
	v_cvt_pk_bf16_f32 v63, v64, v65
	s_nop 0
	v_lshlrev_b32_e32 v64, 16, v62
	v_and_b32_e32 v65, 0xffff0000, v62
	v_lshlrev_b32_e32 v78, 16, v63
	v_and_b32_e32 v79, 0xffff0000, v63
	v_pk_add_f32 v[76:77], v[76:77], v[78:79]
	v_pk_add_f32 v[78:79], v[60:61], v[64:65]
	v_cvt_pk_bf16_f32 v60, v74, v75
	v_cvt_pk_bf16_f32 v61, v72, v73
	s_nop 0
	v_lshlrev_b32_e32 v80, 16, v60
	v_and_b32_e32 v81, 0xffff0000, v60
	v_lshlrev_b32_e32 v82, 16, v61
	v_and_b32_e32 v83, 0xffff0000, v61
	v_sub_f32_e32 v65, v72, v82
	v_sub_f32_e32 v72, v73, v83
	v_sub_f32_e32 v64, v74, v80
	v_sub_f32_e32 v73, v75, v81
	v_cvt_pk_bf16_f32 v64, v64, v73
	v_cvt_pk_bf16_f32 v65, v65, v72
	global_store_dwordx4 v[66:67], v[58:61], off
	global_store_dwordx4 v[68:69], v[62:65], off
	v_lshlrev_b32_e32 v72, 16, v64
	v_and_b32_e32 v73, 0xffff0000, v64
	v_mul_f32_e32 v58, v79, v79
	v_mul_f32_e32 v59, v77, v77
	v_pk_add_f32 v[72:73], v[80:81], v[72:73]
	v_fmac_f32_e32 v58, v78, v78
	v_fmac_f32_e32 v59, v76, v76
	v_lshlrev_b32_e32 v74, 16, v65
	v_and_b32_e32 v75, 0xffff0000, v65
	v_add_f32_e32 v58, v58, v59
	v_mul_f32_e32 v59, v73, v73
	v_pk_add_f32 v[74:75], v[82:83], v[74:75]
	v_fmac_f32_e32 v59, v72, v72
	v_add_f32_e32 v58, v58, v59
	v_mul_f32_e32 v59, v75, v75
	v_fmac_f32_e32 v59, v74, v74
	v_add_f32_e32 v76, v59, v58
	s_waitcnt vmcnt(18)
	v_lshlrev_b32_e32 v72, 16, v226
	v_and_b32_e32 v73, 0xffff0000, v226
	v_lshlrev_b32_e32 v74, 16, v230
	v_and_b32_e32 v75, 0xffff0000, v230
	v_lshlrev_b32_e32 v58, 16, v227
	v_and_b32_e32 v59, 0xffff0000, v227
	v_lshlrev_b32_e32 v62, 16, v231
	v_and_b32_e32 v63, 0xffff0000, v231
	v_pk_add_f32 v[72:73], v[72:73], v[74:75]
	v_pk_add_f32 v[58:59], v[58:59], v[62:63]
	v_lshlrev_b32_e32 v62, 16, v228
	v_and_b32_e32 v63, 0xffff0000, v228
	v_lshlrev_b32_e32 v74, 16, v232
	v_and_b32_e32 v75, 0xffff0000, v232
	v_lshlrev_b32_e32 v60, 16, v229
	v_and_b32_e32 v61, 0xffff0000, v229
	v_lshlrev_b32_e32 v64, 16, v233
	v_and_b32_e32 v65, 0xffff0000, v233
	v_add_u32_e32 v251, 0x58000, v249
	global_load_dwordx4 v[226:229], v251, s[66:67]
	global_load_dwordx4 v[230:233], v251, s[64:65]
	v_pk_add_f32 v[62:63], v[62:63], v[74:75]
	v_pk_add_f32 v[60:61], v[60:61], v[64:65]
	v_pk_add_f32 v[56:57], v[56:57], v[58:59]
	v_pk_add_f32 v[54:55], v[54:55], v[72:73]
	v_pk_add_f32 v[58:59], v[52:53], v[60:61]
	v_pk_add_f32 v[60:61], v[50:51], v[62:63]
	v_cvt_pk_bf16_f32 v50, v54, v55
	v_cvt_pk_bf16_f32 v51, v56, v57
	s_nop 0
	v_lshlrev_b32_e32 v52, 16, v50
	v_and_b32_e32 v53, 0xffff0000, v50
	v_lshlrev_b32_e32 v62, 16, v51
	v_and_b32_e32 v63, 0xffff0000, v51
	v_sub_f32_e32 v56, v56, v62
	v_sub_f32_e32 v57, v57, v63
	v_sub_f32_e32 v54, v54, v52
	v_sub_f32_e32 v55, v55, v53
	v_cvt_pk_bf16_f32 v54, v54, v55
	v_cvt_pk_bf16_f32 v55, v56, v57
	s_nop 0
	v_lshlrev_b32_e32 v56, 16, v54
	v_and_b32_e32 v57, 0xffff0000, v54
	v_lshlrev_b32_e32 v64, 16, v55
	v_and_b32_e32 v65, 0xffff0000, v55
	v_pk_add_f32 v[62:63], v[62:63], v[64:65]
	v_pk_add_f32 v[64:65], v[52:53], v[56:57]
	v_cvt_pk_bf16_f32 v52, v60, v61
	v_cvt_pk_bf16_f32 v53, v58, v59
	s_nop 0
	v_lshlrev_b32_e32 v72, 16, v52
	v_and_b32_e32 v73, 0xffff0000, v52
	v_lshlrev_b32_e32 v74, 16, v53
	v_and_b32_e32 v75, 0xffff0000, v53
	v_sub_f32_e32 v57, v58, v74
	v_sub_f32_e32 v58, v59, v75
	v_sub_f32_e32 v56, v60, v72
	v_sub_f32_e32 v59, v61, v73
	v_cvt_pk_bf16_f32 v56, v56, v59
	v_cvt_pk_bf16_f32 v57, v57, v58
	global_store_dwordx4 v[66:67], v[50:53], off offset:256
	global_store_dwordx4 v[68:69], v[54:57], off offset:256
	v_lshlrev_b32_e32 v58, 16, v56
	v_and_b32_e32 v59, 0xffff0000, v56
	v_mul_f32_e32 v50, v65, v65
	v_mul_f32_e32 v51, v63, v63
	v_pk_add_f32 v[58:59], v[72:73], v[58:59]
	v_fmac_f32_e32 v50, v64, v64
	v_fmac_f32_e32 v51, v62, v62
	v_lshlrev_b32_e32 v60, 16, v57
	v_and_b32_e32 v61, 0xffff0000, v57
	v_add_f32_e32 v50, v50, v51
	v_mul_f32_e32 v51, v59, v59
	v_pk_add_f32 v[60:61], v[74:75], v[60:61]
	v_fmac_f32_e32 v51, v58, v58
	v_add_f32_e32 v50, v50, v51
	v_mul_f32_e32 v51, v61, v61
	v_fmac_f32_e32 v51, v60, v60
	v_add_f32_e32 v50, v51, v50
	v_add_f32_e32 v50, v76, v50
	ds_bpermute_b32 v51, v204, v50
	s_waitcnt lgkmcnt(0)
	v_add_f32_e32 v54, v50, v51
	v_add_u32_e32 v50, 0x90, v144
	v_ashrrev_i32_e32 v51, 31, v50
	v_lshlrev_b64 v[52:53], 11, v[50:51]
	v_lshl_add_u64 v[50:51], s[66:67], 0, v[52:53]
	v_lshl_add_u64 v[50:51], v[50:51], 0, v[142:143]
	v_lshl_add_u64 v[52:53], s[64:65], 0, v[52:53]
	v_lshl_add_u64 v[52:53], v[52:53], 0, v[142:143]
	ds_bpermute_b32 v55, v205, v54
	s_waitcnt vmcnt(18)
	v_lshlrev_b32_e32 v64, 16, v170
	v_and_b32_e32 v65, 0xffff0000, v170
	v_lshlrev_b32_e32 v66, 16, v174
	v_and_b32_e32 v67, 0xffff0000, v174
	v_lshlrev_b32_e32 v56, 16, v171
	v_and_b32_e32 v57, 0xffff0000, v171
	v_lshlrev_b32_e32 v60, 16, v175
	v_and_b32_e32 v61, 0xffff0000, v175
	v_pk_add_f32 v[64:65], v[64:65], v[66:67]
	v_pk_add_f32 v[56:57], v[56:57], v[60:61]
	v_lshlrev_b32_e32 v60, 16, v172
	v_and_b32_e32 v61, 0xffff0000, v172
	v_lshlrev_b32_e32 v66, 16, v176
	v_and_b32_e32 v67, 0xffff0000, v176
	v_lshlrev_b32_e32 v58, 16, v173
	v_and_b32_e32 v59, 0xffff0000, v173
	v_lshlrev_b32_e32 v62, 16, v177
	v_and_b32_e32 v63, 0xffff0000, v177
	v_add_u32_e32 v250, 0x58000, v249
	global_load_dwordx4 v[170:173], v250, s[66:67] offset:256
	global_load_dwordx4 v[174:177], v250, s[64:65] offset:256
	v_pk_add_f32 v[60:61], v[60:61], v[66:67]
	v_pk_add_f32 v[58:59], v[58:59], v[62:63]
	v_pk_add_f32 v[48:49], v[48:49], v[56:57]
	v_pk_add_f32 v[46:47], v[46:47], v[64:65]
	v_pk_add_f32 v[56:57], v[44:45], v[58:59]
	v_pk_add_f32 v[58:59], v[42:43], v[60:61]
	v_cvt_pk_bf16_f32 v42, v46, v47
	v_cvt_pk_bf16_f32 v43, v48, v49
	s_nop 0
	v_lshlrev_b32_e32 v44, 16, v42
	v_and_b32_e32 v45, 0xffff0000, v42
	v_lshlrev_b32_e32 v60, 16, v43
	v_and_b32_e32 v61, 0xffff0000, v43
	v_sub_f32_e32 v48, v48, v60
	v_sub_f32_e32 v49, v49, v61
	v_sub_f32_e32 v46, v46, v44
	v_sub_f32_e32 v47, v47, v45
	v_cvt_pk_bf16_f32 v46, v46, v47
	v_cvt_pk_bf16_f32 v47, v48, v49
	s_nop 0
	v_lshlrev_b32_e32 v48, 16, v46
	v_and_b32_e32 v49, 0xffff0000, v46
	v_lshlrev_b32_e32 v62, 16, v47
	v_and_b32_e32 v63, 0xffff0000, v47
	v_pk_add_f32 v[60:61], v[60:61], v[62:63]
	v_pk_add_f32 v[62:63], v[44:45], v[48:49]
	v_cvt_pk_bf16_f32 v44, v58, v59
	v_cvt_pk_bf16_f32 v45, v56, v57
	s_nop 0
	v_lshlrev_b32_e32 v64, 16, v44
	v_and_b32_e32 v65, 0xffff0000, v44
	v_lshlrev_b32_e32 v66, 16, v45
	v_and_b32_e32 v67, 0xffff0000, v45
	v_sub_f32_e32 v49, v56, v66
	v_sub_f32_e32 v56, v57, v67
	v_sub_f32_e32 v48, v58, v64
	v_sub_f32_e32 v57, v59, v65
	v_cvt_pk_bf16_f32 v48, v48, v57
	v_cvt_pk_bf16_f32 v49, v49, v56
	global_store_dwordx4 v[50:51], v[42:45], off
	global_store_dwordx4 v[52:53], v[46:49], off
	v_lshlrev_b32_e32 v56, 16, v48
	v_and_b32_e32 v57, 0xffff0000, v48
	v_mul_f32_e32 v42, v63, v63
	v_mul_f32_e32 v43, v61, v61
	v_pk_add_f32 v[56:57], v[64:65], v[56:57]
	v_fmac_f32_e32 v42, v62, v62
	v_fmac_f32_e32 v43, v60, v60
	v_lshlrev_b32_e32 v58, 16, v49
	v_and_b32_e32 v59, 0xffff0000, v49
	v_add_f32_e32 v42, v42, v43
	v_mul_f32_e32 v43, v57, v57
	v_pk_add_f32 v[58:59], v[66:67], v[58:59]
	v_fmac_f32_e32 v43, v56, v56
	v_add_f32_e32 v42, v42, v43
	v_mul_f32_e32 v43, v59, v59
	v_fmac_f32_e32 v43, v58, v58
	v_add_f32_e32 v60, v43, v42
	s_waitcnt vmcnt(18)
	v_lshlrev_b32_e32 v56, 16, v178
	v_and_b32_e32 v57, 0xffff0000, v178
	v_lshlrev_b32_e32 v58, 16, v190
	v_and_b32_e32 v59, 0xffff0000, v190
	v_lshlrev_b32_e32 v42, 16, v179
	v_and_b32_e32 v43, 0xffff0000, v179
	v_lshlrev_b32_e32 v46, 16, v191
	v_and_b32_e32 v47, 0xffff0000, v191
	v_pk_add_f32 v[56:57], v[56:57], v[58:59]
	v_pk_add_f32 v[42:43], v[42:43], v[46:47]
	v_lshlrev_b32_e32 v46, 16, v180
	v_and_b32_e32 v47, 0xffff0000, v180
	v_lshlrev_b32_e32 v58, 16, v192
	v_and_b32_e32 v59, 0xffff0000, v192
	v_lshlrev_b32_e32 v44, 16, v181
	v_and_b32_e32 v45, 0xffff0000, v181
	v_lshlrev_b32_e32 v48, 16, v193
	v_and_b32_e32 v49, 0xffff0000, v193
	v_pk_add_f32 v[46:47], v[46:47], v[58:59]
	v_pk_add_f32 v[44:45], v[44:45], v[48:49]
	v_pk_add_f32 v[40:41], v[40:41], v[42:43]
	v_pk_add_f32 v[38:39], v[38:39], v[56:57]
	v_pk_add_f32 v[42:43], v[36:37], v[44:45]
	v_pk_add_f32 v[44:45], v[34:35], v[46:47]
	v_cvt_pk_bf16_f32 v34, v38, v39
	v_cvt_pk_bf16_f32 v35, v40, v41
	s_nop 0
	v_lshlrev_b32_e32 v36, 16, v34
	v_and_b32_e32 v37, 0xffff0000, v34
	v_lshlrev_b32_e32 v46, 16, v35
	v_and_b32_e32 v47, 0xffff0000, v35
	v_sub_f32_e32 v40, v40, v46
	v_sub_f32_e32 v41, v41, v47
	v_sub_f32_e32 v38, v38, v36
	v_sub_f32_e32 v39, v39, v37
	v_cvt_pk_bf16_f32 v38, v38, v39
	v_cvt_pk_bf16_f32 v39, v40, v41
	s_nop 0
	v_lshlrev_b32_e32 v40, 16, v38
	v_and_b32_e32 v41, 0xffff0000, v38
	v_lshlrev_b32_e32 v48, 16, v39
	v_and_b32_e32 v49, 0xffff0000, v39
	v_pk_add_f32 v[46:47], v[46:47], v[48:49]
	v_pk_add_f32 v[48:49], v[36:37], v[40:41]
	v_cvt_pk_bf16_f32 v36, v44, v45
	v_cvt_pk_bf16_f32 v37, v42, v43
	s_nop 0
	v_lshlrev_b32_e32 v56, 16, v36
	v_and_b32_e32 v57, 0xffff0000, v36
	v_lshlrev_b32_e32 v58, 16, v37
	v_and_b32_e32 v59, 0xffff0000, v37
	v_sub_f32_e32 v41, v42, v58
	v_sub_f32_e32 v42, v43, v59
	v_sub_f32_e32 v40, v44, v56
	v_sub_f32_e32 v43, v45, v57
	v_cvt_pk_bf16_f32 v40, v40, v43
	v_cvt_pk_bf16_f32 v41, v41, v42
	global_store_dwordx4 v[50:51], v[34:37], off offset:256
	global_store_dwordx4 v[52:53], v[38:41], off offset:256
	v_lshlrev_b32_e32 v42, 16, v40
	v_and_b32_e32 v43, 0xffff0000, v40
	v_mul_f32_e32 v34, v49, v49
	v_mul_f32_e32 v35, v47, v47
	v_pk_add_f32 v[42:43], v[56:57], v[42:43]
	v_fmac_f32_e32 v34, v48, v48
	v_fmac_f32_e32 v35, v46, v46
	v_add_u32_e32 v36, 0xa0, v144
	v_lshlrev_b32_e32 v44, 16, v41
	v_and_b32_e32 v45, 0xffff0000, v41
	v_add_f32_e32 v34, v34, v35
	v_mul_f32_e32 v35, v43, v43
	v_ashrrev_i32_e32 v37, 31, v36
	v_pk_add_f32 v[44:45], v[58:59], v[44:45]
	v_fmac_f32_e32 v35, v42, v42
	v_lshlrev_b64 v[36:37], 11, v[36:37]
	v_add_f32_e32 v34, v34, v35
	v_mul_f32_e32 v35, v45, v45
	v_lshl_add_u64 v[38:39], s[66:67], 0, v[36:37]
	v_fmac_f32_e32 v35, v44, v44
	v_lshl_add_u64 v[44:45], v[38:39], 0, v[142:143]
	v_lshl_add_u64 v[36:37], s[64:65], 0, v[36:37]
	v_lshl_add_u64 v[46:47], v[36:37], 0, v[142:143]
	v_add_f32_e32 v34, v35, v34
	v_add_f32_e32 v34, v60, v34
	ds_bpermute_b32 v35, v204, v34
	s_waitcnt lgkmcnt(0)
	v_add_f32_e32 v34, v34, v35
	ds_bpermute_b32 v35, v205, v34
	s_waitcnt vmcnt(16)
	v_lshlrev_b32_e32 v48, 16, v194
	v_and_b32_e32 v49, 0xffff0000, v194
	v_lshlrev_b32_e32 v50, 16, v214
	v_and_b32_e32 v51, 0xffff0000, v214
	v_lshlrev_b32_e32 v36, 16, v195
	v_and_b32_e32 v37, 0xffff0000, v195
	v_lshlrev_b32_e32 v40, 16, v215
	v_and_b32_e32 v41, 0xffff0000, v215
	v_pk_add_f32 v[48:49], v[48:49], v[50:51]
	v_pk_add_f32 v[36:37], v[36:37], v[40:41]
	v_lshlrev_b32_e32 v40, 16, v196
	v_and_b32_e32 v41, 0xffff0000, v196
	v_lshlrev_b32_e32 v50, 16, v216
	v_and_b32_e32 v51, 0xffff0000, v216
	v_lshlrev_b32_e32 v38, 16, v197
	v_and_b32_e32 v39, 0xffff0000, v197
	v_lshlrev_b32_e32 v42, 16, v217
	v_and_b32_e32 v43, 0xffff0000, v217
	v_pk_add_f32 v[40:41], v[40:41], v[50:51]
	v_pk_add_f32 v[38:39], v[38:39], v[42:43]
	v_pk_add_f32 v[32:33], v[32:33], v[36:37]
	v_pk_add_f32 v[30:31], v[30:31], v[48:49]
	v_pk_add_f32 v[36:37], v[28:29], v[38:39]
	v_pk_add_f32 v[38:39], v[26:27], v[40:41]
	v_cvt_pk_bf16_f32 v26, v30, v31
	v_cvt_pk_bf16_f32 v27, v32, v33
	s_nop 0
	v_lshlrev_b32_e32 v28, 16, v26
	v_and_b32_e32 v29, 0xffff0000, v26
	v_lshlrev_b32_e32 v40, 16, v27
	v_and_b32_e32 v41, 0xffff0000, v27
	v_sub_f32_e32 v32, v32, v40
	v_sub_f32_e32 v33, v33, v41
	v_sub_f32_e32 v30, v30, v28
	v_sub_f32_e32 v31, v31, v29
	v_cvt_pk_bf16_f32 v30, v30, v31
	v_cvt_pk_bf16_f32 v31, v32, v33
	s_nop 0
	v_lshlrev_b32_e32 v32, 16, v30
	v_and_b32_e32 v33, 0xffff0000, v30
	v_lshlrev_b32_e32 v42, 16, v31
	v_and_b32_e32 v43, 0xffff0000, v31
	v_pk_add_f32 v[40:41], v[40:41], v[42:43]
	v_pk_add_f32 v[42:43], v[28:29], v[32:33]
	v_cvt_pk_bf16_f32 v28, v38, v39
	v_cvt_pk_bf16_f32 v29, v36, v37
	s_nop 0
	v_lshlrev_b32_e32 v48, 16, v28
	v_and_b32_e32 v49, 0xffff0000, v28
	v_lshlrev_b32_e32 v50, 16, v29
	v_and_b32_e32 v51, 0xffff0000, v29
	v_sub_f32_e32 v33, v36, v50
	v_sub_f32_e32 v36, v37, v51
	v_sub_f32_e32 v32, v38, v48
	v_sub_f32_e32 v37, v39, v49
	v_cvt_pk_bf16_f32 v32, v32, v37
	v_cvt_pk_bf16_f32 v33, v33, v36
	global_store_dwordx4 v[44:45], v[26:29], off
	global_store_dwordx4 v[46:47], v[30:33], off
	v_lshlrev_b32_e32 v36, 16, v32
	v_and_b32_e32 v37, 0xffff0000, v32
	v_mul_f32_e32 v26, v43, v43
	v_mul_f32_e32 v27, v41, v41
	v_pk_add_f32 v[36:37], v[48:49], v[36:37]
	v_fmac_f32_e32 v26, v42, v42
	v_fmac_f32_e32 v27, v40, v40
	v_lshlrev_b32_e32 v38, 16, v33
	v_and_b32_e32 v39, 0xffff0000, v33
	v_add_f32_e32 v26, v26, v27
	v_mul_f32_e32 v27, v37, v37
	v_pk_add_f32 v[38:39], v[50:51], v[38:39]
	v_fmac_f32_e32 v27, v36, v36
	v_add_f32_e32 v26, v26, v27
	v_mul_f32_e32 v27, v39, v39
	v_fmac_f32_e32 v27, v38, v38
	v_add_f32_e32 v40, v27, v26
	s_waitcnt vmcnt(14)
	v_lshlrev_b32_e32 v36, 16, v218
	v_and_b32_e32 v37, 0xffff0000, v218
	v_lshlrev_b32_e32 v38, 16, v222
	v_and_b32_e32 v39, 0xffff0000, v222
	v_lshlrev_b32_e32 v26, 16, v219
	v_and_b32_e32 v27, 0xffff0000, v219
	v_lshlrev_b32_e32 v30, 16, v223
	v_and_b32_e32 v31, 0xffff0000, v223
	v_pk_add_f32 v[36:37], v[36:37], v[38:39]
	v_pk_add_f32 v[26:27], v[26:27], v[30:31]
	v_lshlrev_b32_e32 v30, 16, v220
	v_and_b32_e32 v31, 0xffff0000, v220
	v_lshlrev_b32_e32 v38, 16, v224
	v_and_b32_e32 v39, 0xffff0000, v224
	v_lshlrev_b32_e32 v28, 16, v221
	v_and_b32_e32 v29, 0xffff0000, v221
	v_lshlrev_b32_e32 v32, 16, v225
	v_and_b32_e32 v33, 0xffff0000, v225
	v_pk_add_f32 v[30:31], v[30:31], v[38:39]
	v_pk_add_f32 v[28:29], v[28:29], v[32:33]
	v_pk_add_f32 v[24:25], v[24:25], v[26:27]
	v_pk_add_f32 v[22:23], v[22:23], v[36:37]
	v_pk_add_f32 v[26:27], v[20:21], v[28:29]
	v_pk_add_f32 v[28:29], v[18:19], v[30:31]
	v_cvt_pk_bf16_f32 v18, v22, v23
	v_cvt_pk_bf16_f32 v19, v24, v25
	s_nop 0
	v_lshlrev_b32_e32 v20, 16, v18
	v_and_b32_e32 v21, 0xffff0000, v18
	v_lshlrev_b32_e32 v30, 16, v19
	v_and_b32_e32 v31, 0xffff0000, v19
	v_sub_f32_e32 v24, v24, v30
	v_sub_f32_e32 v25, v25, v31
	v_sub_f32_e32 v22, v22, v20
	v_sub_f32_e32 v23, v23, v21
	v_cvt_pk_bf16_f32 v22, v22, v23
	v_cvt_pk_bf16_f32 v23, v24, v25
	s_nop 0
	v_lshlrev_b32_e32 v24, 16, v22
	v_and_b32_e32 v25, 0xffff0000, v22
	v_lshlrev_b32_e32 v32, 16, v23
	v_and_b32_e32 v33, 0xffff0000, v23
	v_pk_add_f32 v[30:31], v[30:31], v[32:33]
	v_pk_add_f32 v[32:33], v[20:21], v[24:25]
	v_cvt_pk_bf16_f32 v20, v28, v29
	v_cvt_pk_bf16_f32 v21, v26, v27
	s_nop 0
	v_lshlrev_b32_e32 v36, 16, v20
	v_and_b32_e32 v37, 0xffff0000, v20
	v_lshlrev_b32_e32 v38, 16, v21
	v_and_b32_e32 v39, 0xffff0000, v21
	v_sub_f32_e32 v25, v26, v38
	v_sub_f32_e32 v26, v27, v39
	v_sub_f32_e32 v24, v28, v36
	v_sub_f32_e32 v27, v29, v37
	v_cvt_pk_bf16_f32 v24, v24, v27
	v_cvt_pk_bf16_f32 v25, v25, v26
	global_store_dwordx4 v[44:45], v[18:21], off offset:256
	global_store_dwordx4 v[46:47], v[22:25], off offset:256
	v_lshlrev_b32_e32 v26, 16, v24
	v_and_b32_e32 v27, 0xffff0000, v24
	v_mul_f32_e32 v18, v33, v33
	v_mul_f32_e32 v19, v31, v31
	v_pk_add_f32 v[26:27], v[36:37], v[26:27]
	v_fmac_f32_e32 v18, v32, v32
	v_fmac_f32_e32 v19, v30, v30
	v_lshlrev_b32_e32 v28, 16, v25
	v_and_b32_e32 v29, 0xffff0000, v25
	v_add_f32_e32 v18, v18, v19
	v_mul_f32_e32 v19, v27, v27
	v_pk_add_f32 v[28:29], v[38:39], v[28:29]
	v_fmac_f32_e32 v19, v26, v26
	v_add_f32_e32 v18, v18, v19
	v_mul_f32_e32 v19, v29, v29
	v_fmac_f32_e32 v19, v28, v28
	v_add_f32_e32 v18, v19, v18
	v_add_f32_e32 v18, v40, v18
	ds_bpermute_b32 v19, v204, v18
	s_waitcnt lgkmcnt(0)
	v_add_f32_e32 v30, v18, v19
	v_add_u32_e32 v18, 0xb0, v144
	v_ashrrev_i32_e32 v19, 31, v18
	v_lshlrev_b64 v[18:19], 11, v[18:19]
	v_lshl_add_u64 v[20:21], s[66:67], 0, v[18:19]
	v_lshl_add_u64 v[26:27], v[20:21], 0, v[142:143]
	v_lshl_add_u64 v[18:19], s[64:65], 0, v[18:19]
	v_lshl_add_u64 v[28:29], v[18:19], 0, v[142:143]
	ds_bpermute_b32 v31, v205, v30
	s_waitcnt vmcnt(12)
	v_lshlrev_b32_e32 v32, 16, v226
	v_and_b32_e32 v33, 0xffff0000, v226
	v_lshlrev_b32_e32 v36, 16, v230
	v_and_b32_e32 v37, 0xffff0000, v230
	v_lshlrev_b32_e32 v18, 16, v227
	v_and_b32_e32 v19, 0xffff0000, v227
	v_lshlrev_b32_e32 v22, 16, v231
	v_and_b32_e32 v23, 0xffff0000, v231
	v_pk_add_f32 v[32:33], v[32:33], v[36:37]
	v_pk_add_f32 v[18:19], v[18:19], v[22:23]
	v_lshlrev_b32_e32 v22, 16, v228
	v_and_b32_e32 v23, 0xffff0000, v228
	v_lshlrev_b32_e32 v36, 16, v232
	v_and_b32_e32 v37, 0xffff0000, v232
	v_lshlrev_b32_e32 v20, 16, v229
	v_and_b32_e32 v21, 0xffff0000, v229
	v_lshlrev_b32_e32 v24, 16, v233
	v_and_b32_e32 v25, 0xffff0000, v233
	v_pk_add_f32 v[22:23], v[22:23], v[36:37]
	v_pk_add_f32 v[20:21], v[20:21], v[24:25]
	v_pk_add_f32 v[16:17], v[16:17], v[18:19]
	v_pk_add_f32 v[14:15], v[14:15], v[32:33]
	v_pk_add_f32 v[18:19], v[12:13], v[20:21]
	v_pk_add_f32 v[20:21], v[10:11], v[22:23]
	v_cvt_pk_bf16_f32 v10, v14, v15
	v_cvt_pk_bf16_f32 v11, v16, v17
	s_nop 0
	v_lshlrev_b32_e32 v12, 16, v10
	v_and_b32_e32 v13, 0xffff0000, v10
	v_lshlrev_b32_e32 v22, 16, v11
	v_and_b32_e32 v23, 0xffff0000, v11
	v_sub_f32_e32 v16, v16, v22
	v_sub_f32_e32 v17, v17, v23
	v_sub_f32_e32 v14, v14, v12
	v_sub_f32_e32 v15, v15, v13
	v_cvt_pk_bf16_f32 v14, v14, v15
	v_cvt_pk_bf16_f32 v15, v16, v17
	s_nop 0
	v_lshlrev_b32_e32 v16, 16, v14
	v_and_b32_e32 v17, 0xffff0000, v14
	v_lshlrev_b32_e32 v24, 16, v15
	v_and_b32_e32 v25, 0xffff0000, v15
	v_pk_add_f32 v[22:23], v[22:23], v[24:25]
	v_pk_add_f32 v[24:25], v[12:13], v[16:17]
	v_cvt_pk_bf16_f32 v12, v20, v21
	v_cvt_pk_bf16_f32 v13, v18, v19
	s_nop 0
	v_lshlrev_b32_e32 v32, 16, v12
	v_and_b32_e32 v33, 0xffff0000, v12
	v_lshlrev_b32_e32 v36, 16, v13
	v_and_b32_e32 v37, 0xffff0000, v13
	v_sub_f32_e32 v17, v18, v36
	v_sub_f32_e32 v18, v19, v37
	v_sub_f32_e32 v16, v20, v32
	v_sub_f32_e32 v19, v21, v33
	v_cvt_pk_bf16_f32 v16, v16, v19
	v_cvt_pk_bf16_f32 v17, v17, v18
	global_store_dwordx4 v[26:27], v[10:13], off
	global_store_dwordx4 v[28:29], v[14:17], off
	v_lshlrev_b32_e32 v18, 16, v16
	v_and_b32_e32 v19, 0xffff0000, v16
	v_mul_f32_e32 v10, v25, v25
	v_mul_f32_e32 v11, v23, v23
	v_pk_add_f32 v[18:19], v[32:33], v[18:19]
	v_fmac_f32_e32 v10, v24, v24
	v_fmac_f32_e32 v11, v22, v22
	v_lshlrev_b32_e32 v20, 16, v17
	v_and_b32_e32 v21, 0xffff0000, v17
	v_add_f32_e32 v10, v10, v11
	v_mul_f32_e32 v11, v19, v19
	v_pk_add_f32 v[20:21], v[36:37], v[20:21]
	v_fmac_f32_e32 v11, v18, v18
	v_add_f32_e32 v10, v10, v11
	v_mul_f32_e32 v11, v21, v21
	v_fmac_f32_e32 v11, v20, v20
	v_add_f32_e32 v18, v11, v10
	s_waitcnt vmcnt(10)
	v_lshlrev_b32_e32 v20, 16, v170
	v_and_b32_e32 v21, 0xffff0000, v170
	v_lshlrev_b32_e32 v22, 16, v174
	v_and_b32_e32 v23, 0xffff0000, v174
	v_lshlrev_b32_e32 v10, 16, v171
	v_and_b32_e32 v11, 0xffff0000, v171
	v_lshlrev_b32_e32 v14, 16, v175
	v_and_b32_e32 v15, 0xffff0000, v175
	v_pk_add_f32 v[20:21], v[20:21], v[22:23]
	v_pk_add_f32 v[10:11], v[10:11], v[14:15]
	v_lshlrev_b32_e32 v14, 16, v172
	v_and_b32_e32 v15, 0xffff0000, v172
	v_lshlrev_b32_e32 v22, 16, v176
	v_and_b32_e32 v23, 0xffff0000, v176
	v_lshlrev_b32_e32 v12, 16, v173
	v_and_b32_e32 v13, 0xffff0000, v173
	v_lshlrev_b32_e32 v16, 16, v177
	v_and_b32_e32 v17, 0xffff0000, v177
	v_pk_add_f32 v[14:15], v[14:15], v[22:23]
	v_pk_add_f32 v[12:13], v[12:13], v[16:17]
	v_pk_add_f32 v[8:9], v[8:9], v[10:11]
	v_pk_add_f32 v[6:7], v[6:7], v[20:21]
	v_pk_add_f32 v[10:11], v[4:5], v[12:13]
	v_pk_add_f32 v[12:13], v[2:3], v[14:15]
	v_cvt_pk_bf16_f32 v2, v6, v7
	v_cvt_pk_bf16_f32 v3, v8, v9
	s_nop 0
	v_lshlrev_b32_e32 v4, 16, v2
	v_and_b32_e32 v5, 0xffff0000, v2
	v_lshlrev_b32_e32 v14, 16, v3
	v_and_b32_e32 v15, 0xffff0000, v3
	v_sub_f32_e32 v8, v8, v14
	v_sub_f32_e32 v9, v9, v15
	v_sub_f32_e32 v6, v6, v4
	v_sub_f32_e32 v7, v7, v5
	v_cvt_pk_bf16_f32 v6, v6, v7
	v_cvt_pk_bf16_f32 v7, v8, v9
	s_nop 0
	v_lshlrev_b32_e32 v8, 16, v6
	v_and_b32_e32 v9, 0xffff0000, v6
	v_lshlrev_b32_e32 v16, 16, v7
	v_and_b32_e32 v17, 0xffff0000, v7
	v_pk_add_f32 v[14:15], v[14:15], v[16:17]
	v_pk_add_f32 v[16:17], v[4:5], v[8:9]
	v_cvt_pk_bf16_f32 v4, v12, v13
	v_cvt_pk_bf16_f32 v5, v10, v11
	s_nop 0
	v_lshlrev_b32_e32 v20, 16, v4
	v_and_b32_e32 v21, 0xffff0000, v4
	v_lshlrev_b32_e32 v22, 16, v5
	v_and_b32_e32 v23, 0xffff0000, v5
	v_sub_f32_e32 v9, v10, v22
	v_sub_f32_e32 v10, v11, v23
	v_sub_f32_e32 v8, v12, v20
	v_sub_f32_e32 v11, v13, v21
	v_cvt_pk_bf16_f32 v8, v8, v11
	v_cvt_pk_bf16_f32 v9, v9, v10
	global_store_dwordx4 v[26:27], v[2:5], off offset:256
	global_store_dwordx4 v[28:29], v[6:9], off offset:256
	v_lshlrev_b32_e32 v10, 16, v8
	v_and_b32_e32 v11, 0xffff0000, v8
	v_mul_f32_e32 v2, v17, v17
	v_mul_f32_e32 v3, v15, v15
	v_pk_add_f32 v[10:11], v[20:21], v[10:11]
	v_fmac_f32_e32 v2, v16, v16
	v_fmac_f32_e32 v3, v14, v14
	v_lshlrev_b32_e32 v12, 16, v9
	v_and_b32_e32 v13, 0xffff0000, v9
	v_add_f32_e32 v2, v2, v3
	v_mul_f32_e32 v3, v11, v11
	v_pk_add_f32 v[12:13], v[22:23], v[12:13]
	v_fmac_f32_e32 v3, v10, v10
	v_add_f32_e32 v2, v2, v3
	v_mul_f32_e32 v3, v13, v13
	v_fmac_f32_e32 v3, v12, v12
	v_add_f32_e32 v2, v3, v2
	v_add_f32_e32 v2, v18, v2
	ds_bpermute_b32 v3, v204, v2
	s_waitcnt lgkmcnt(0)
	v_add_f32_e32 v2, v2, v3
	ds_bpermute_b32 v3, v205, v2
	s_and_saveexec_b64 s[24:25], s[10:11]
	s_cbranch_execz .LBB11_1634
	s_ashr_i32 s23, s22, 31
	s_lshl_b64 s[0:1], s[22:23], 2
	s_add_u32 s0, s28, s0
	v_ashrrev_i32_e32 v141, 31, v140
	s_addc_u32 s1, s29, s1
	s_waitcnt lgkmcnt(0)
	v_add_f32_e32 v4, v2, v3
	v_add_f32_e32 v11, v118, v119
	v_lshl_add_u64 v[2:3], v[140:141], 2, s[0:1]
	v_add_f32_e32 v5, v30, v31
	v_add_f32_e32 v6, v34, v35
	v_add_f32_e32 v7, v54, v55
	v_add_f32_e32 v8, v70, v71
	v_add_f32_e32 v9, v86, v87
	v_add_f32_e32 v10, v102, v103
	global_atomic_add_f32 v[2:3], v11, off
	global_atomic_add_f32 v[2:3], v10, off offset:64
	global_atomic_add_f32 v[2:3], v9, off offset:128
	global_atomic_add_f32 v[2:3], v8, off offset:192
	global_atomic_add_f32 v[2:3], v7, off offset:512
	global_atomic_add_f32 v[2:3], v6, off offset:576
	global_atomic_add_f32 v[2:3], v5, off offset:640
	global_atomic_add_f32 v[2:3], v4, off offset:704

.LBB11_2332:
	v_mov_b32_e32 v140, v150
	v_mov_b32_e32 v141, v152
	s_lshl_b32 s22, s7, 8
	s_nop 0
	v_add_u32_e32 v144, s22, v140
	v_lshl_add_u32 v142, s6, 8, v141
	v_ashrrev_i32_e32 v145, 31, v144
	v_lshlrev_b64 v[148:149], 11, v[144:145]
	v_ashrrev_i32_e32 v143, 31, v142
	v_lshl_add_u64 v[146:147], s[66:67], 0, v[148:149]
	v_lshlrev_b64 v[142:143], 1, v[142:143]
	v_lshl_add_u64 v[146:147], v[146:147], 0, v[142:143]
	v_lshl_add_u64 v[148:149], s[64:65], 0, v[148:149]
	v_lshl_add_u64 v[148:149], v[148:149], 0, v[142:143]
	v_lshl_add_u32 v249, v144, 11, v142
	global_load_dwordx4 v[170:173], v249, s[66:67]
	global_load_dwordx4 v[174:177], v249, s[64:65]
	global_load_dwordx4 v[178:181], v249, s[66:67] offset:256
	global_load_dwordx4 v[190:193], v249, s[64:65] offset:256
	v_add_u32_e32 v251, 0x8000, v249
	global_load_dwordx4 v[194:197], v251, s[66:67]
	global_load_dwordx4 v[214:217], v251, s[64:65]
	v_add_u32_e32 v250, 0x8000, v249
	global_load_dwordx4 v[218:221], v250, s[66:67] offset:256
	global_load_dwordx4 v[222:225], v250, s[64:65] offset:256
	v_add_u32_e32 v251, 0x10000, v249
	global_load_dwordx4 v[226:229], v251, s[66:67]
	global_load_dwordx4 v[230:233], v251, s[64:65]
	s_waitcnt vmcnt(8)
	v_lshlrev_b32_e32 v162, 16, v170
	v_and_b32_e32 v163, 0xffff0000, v170
	v_lshlrev_b32_e32 v164, 16, v174
	v_and_b32_e32 v165, 0xffff0000, v174
	v_lshlrev_b32_e32 v154, 16, v171
	v_and_b32_e32 v155, 0xffff0000, v171
	v_lshlrev_b32_e32 v158, 16, v175
	v_and_b32_e32 v159, 0xffff0000, v175
	v_pk_add_f32 v[162:163], v[162:163], v[164:165]
	v_pk_add_f32 v[154:155], v[154:155], v[158:159]
	v_lshlrev_b32_e32 v158, 16, v172
	v_and_b32_e32 v159, 0xffff0000, v172
	v_lshlrev_b32_e32 v164, 16, v176
	v_and_b32_e32 v165, 0xffff0000, v176
	v_lshlrev_b32_e32 v156, 16, v173
	v_and_b32_e32 v157, 0xffff0000, v173
	v_lshlrev_b32_e32 v160, 16, v177
	v_and_b32_e32 v161, 0xffff0000, v177
	v_add_u32_e32 v250, 0x10000, v249
	global_load_dwordx4 v[170:173], v250, s[66:67] offset:256
	global_load_dwordx4 v[174:177], v250, s[64:65] offset:256
	v_pk_add_f32 v[158:159], v[158:159], v[164:165]
	v_pk_add_f32 v[156:157], v[156:157], v[160:161]
	v_pk_add_f32 v[128:129], v[128:129], v[154:155]
	v_pk_add_f32 v[126:127], v[126:127], v[162:163]
	v_pk_add_f32 v[154:155], v[124:125], v[156:157]
	v_pk_add_f32 v[156:157], v[122:123], v[158:159]
	v_cvt_pk_bf16_f32 v122, v126, v127
	v_cvt_pk_bf16_f32 v123, v128, v129
	s_nop 0
	v_lshlrev_b32_e32 v124, 16, v122
	v_and_b32_e32 v125, 0xffff0000, v122
	v_lshlrev_b32_e32 v158, 16, v123
	v_and_b32_e32 v159, 0xffff0000, v123
	v_sub_f32_e32 v128, v128, v158
	v_sub_f32_e32 v129, v129, v159
	v_sub_f32_e32 v126, v126, v124
	v_sub_f32_e32 v127, v127, v125
	v_cvt_pk_bf16_f32 v126, v126, v127
	v_cvt_pk_bf16_f32 v127, v128, v129
	s_nop 0
	v_lshlrev_b32_e32 v128, 16, v126
	v_and_b32_e32 v129, 0xffff0000, v126
	v_lshlrev_b32_e32 v160, 16, v127
	v_and_b32_e32 v161, 0xffff0000, v127
	v_pk_add_f32 v[158:159], v[158:159], v[160:161]
	v_pk_add_f32 v[160:161], v[124:125], v[128:129]
	v_cvt_pk_bf16_f32 v124, v156, v157
	v_cvt_pk_bf16_f32 v125, v154, v155
	s_nop 0
	v_lshlrev_b32_e32 v162, 16, v124
	v_lshlrev_b32_e32 v164, 16, v125
	v_and_b32_e32 v163, 0xffff0000, v124
	v_and_b32_e32 v165, 0xffff0000, v125
	v_sub_f32_e32 v129, v154, v164
	v_sub_f32_e32 v128, v156, v162
	v_sub_f32_e32 v141, v155, v165
	v_sub_f32_e32 v145, v157, v163
	v_cvt_pk_bf16_f32 v128, v128, v145
	v_cvt_pk_bf16_f32 v129, v129, v141
	global_store_dwordx4 v[146:147], v[122:125], off
	global_store_dwordx4 v[148:149], v[126:129], off
	v_lshlrev_b32_e32 v154, 16, v128
	v_and_b32_e32 v155, 0xffff0000, v128
	v_mul_f32_e32 v122, v161, v161
	v_mul_f32_e32 v123, v159, v159
	v_pk_add_f32 v[154:155], v[162:163], v[154:155]
	v_fmac_f32_e32 v122, v160, v160
	v_fmac_f32_e32 v123, v158, v158
	v_lshlrev_b32_e32 v156, 16, v129
	v_and_b32_e32 v157, 0xffff0000, v129
	v_add_f32_e32 v122, v122, v123
	v_mul_f32_e32 v123, v155, v155
	v_pk_add_f32 v[156:157], v[164:165], v[156:157]
	v_fmac_f32_e32 v123, v154, v154
	v_add_f32_e32 v122, v122, v123
	v_mul_f32_e32 v123, v157, v157
	v_fmac_f32_e32 v123, v156, v156
	v_add_f32_e32 v141, v123, v122
	s_waitcnt vmcnt(10)
	v_lshlrev_b32_e32 v154, 16, v178
	v_and_b32_e32 v155, 0xffff0000, v178
	v_lshlrev_b32_e32 v156, 16, v190
	v_and_b32_e32 v157, 0xffff0000, v190
	v_lshlrev_b32_e32 v122, 16, v179
	v_and_b32_e32 v123, 0xffff0000, v179
	v_lshlrev_b32_e32 v126, 16, v191
	v_and_b32_e32 v127, 0xffff0000, v191
	v_pk_add_f32 v[154:155], v[154:155], v[156:157]
	v_pk_add_f32 v[122:123], v[122:123], v[126:127]
	v_lshlrev_b32_e32 v126, 16, v180
	v_and_b32_e32 v127, 0xffff0000, v180
	v_lshlrev_b32_e32 v156, 16, v192
	v_and_b32_e32 v157, 0xffff0000, v192
	v_lshlrev_b32_e32 v124, 16, v181
	v_and_b32_e32 v125, 0xffff0000, v181
	v_lshlrev_b32_e32 v128, 16, v193
	v_and_b32_e32 v129, 0xffff0000, v193
	v_add_u32_e32 v251, 0x18000, v249
	global_load_dwordx4 v[178:181], v251, s[66:67]
	global_load_dwordx4 v[190:193], v251, s[64:65]
	v_pk_add_f32 v[126:127], v[126:127], v[156:157]
	v_pk_add_f32 v[124:125], v[124:125], v[128:129]
	v_pk_add_f32 v[120:121], v[120:121], v[122:123]
	v_pk_add_f32 v[118:119], v[118:119], v[154:155]
	v_pk_add_f32 v[122:123], v[116:117], v[124:125]
	v_pk_add_f32 v[124:125], v[114:115], v[126:127]
	v_cvt_pk_bf16_f32 v114, v118, v119
	v_cvt_pk_bf16_f32 v115, v120, v121
	s_nop 0
	v_lshlrev_b32_e32 v116, 16, v114
	v_and_b32_e32 v117, 0xffff0000, v114
	v_lshlrev_b32_e32 v126, 16, v115
	v_and_b32_e32 v127, 0xffff0000, v115
	v_sub_f32_e32 v120, v120, v126
	v_sub_f32_e32 v121, v121, v127
	v_sub_f32_e32 v118, v118, v116
	v_sub_f32_e32 v119, v119, v117
	v_cvt_pk_bf16_f32 v118, v118, v119
	v_cvt_pk_bf16_f32 v119, v120, v121
	s_nop 0
	v_lshlrev_b32_e32 v120, 16, v118
	v_and_b32_e32 v121, 0xffff0000, v118
	v_lshlrev_b32_e32 v128, 16, v119
	v_and_b32_e32 v129, 0xffff0000, v119
	v_pk_add_f32 v[126:127], v[126:127], v[128:129]
	v_pk_add_f32 v[128:129], v[116:117], v[120:121]
	v_cvt_pk_bf16_f32 v116, v124, v125
	v_cvt_pk_bf16_f32 v117, v122, v123
	s_nop 0
	v_lshlrev_b32_e32 v154, 16, v116
	v_and_b32_e32 v155, 0xffff0000, v116
	v_lshlrev_b32_e32 v156, 16, v117
	v_and_b32_e32 v157, 0xffff0000, v117
	v_sub_f32_e32 v121, v122, v156
	v_sub_f32_e32 v122, v123, v157
	v_sub_f32_e32 v120, v124, v154
	v_sub_f32_e32 v123, v125, v155
	v_cvt_pk_bf16_f32 v120, v120, v123
	v_cvt_pk_bf16_f32 v121, v121, v122
	global_store_dwordx4 v[146:147], v[114:117], off offset:256
	global_store_dwordx4 v[148:149], v[118:121], off offset:256
	v_lshlrev_b32_e32 v122, 16, v120
	v_and_b32_e32 v123, 0xffff0000, v120
	v_mul_f32_e32 v114, v129, v129
	v_mul_f32_e32 v115, v127, v127
	v_pk_add_f32 v[122:123], v[154:155], v[122:123]
	v_fmac_f32_e32 v114, v128, v128
	v_fmac_f32_e32 v115, v126, v126
	v_lshlrev_b32_e32 v124, 16, v121
	v_and_b32_e32 v125, 0xffff0000, v121
	v_add_f32_e32 v114, v114, v115
	v_mul_f32_e32 v115, v123, v123
	v_pk_add_f32 v[124:125], v[156:157], v[124:125]
	v_fmac_f32_e32 v115, v122, v122
	v_add_f32_e32 v114, v114, v115
	v_mul_f32_e32 v115, v125, v125
	v_fmac_f32_e32 v115, v124, v124
	v_add_f32_e32 v114, v115, v114
	v_add_f32_e32 v114, v141, v114
	ds_bpermute_b32 v115, v204, v114
	s_waitcnt lgkmcnt(0)
	v_add_f32_e32 v118, v114, v115
	v_add_u32_e32 v114, 16, v144
	v_ashrrev_i32_e32 v115, 31, v114
	v_lshlrev_b64 v[116:117], 11, v[114:115]
	v_lshl_add_u64 v[114:115], s[66:67], 0, v[116:117]
	v_lshl_add_u64 v[114:115], v[114:115], 0, v[142:143]
	v_lshl_add_u64 v[116:117], s[64:65], 0, v[116:117]
	v_lshl_add_u64 v[116:117], v[116:117], 0, v[142:143]
	ds_bpermute_b32 v119, v205, v118
	s_waitcnt vmcnt(12)
	v_lshlrev_b32_e32 v128, 16, v194
	v_and_b32_e32 v129, 0xffff0000, v194
	v_lshlrev_b32_e32 v146, 16, v214
	v_and_b32_e32 v147, 0xffff0000, v214
	v_lshlrev_b32_e32 v120, 16, v195
	v_and_b32_e32 v121, 0xffff0000, v195
	v_lshlrev_b32_e32 v124, 16, v215
	v_and_b32_e32 v125, 0xffff0000, v215
	v_pk_add_f32 v[128:129], v[128:129], v[146:147]
	v_pk_add_f32 v[120:121], v[120:121], v[124:125]
	v_lshlrev_b32_e32 v124, 16, v196
	v_and_b32_e32 v125, 0xffff0000, v196
	v_lshlrev_b32_e32 v146, 16, v216
	v_and_b32_e32 v147, 0xffff0000, v216
	v_lshlrev_b32_e32 v122, 16, v197
	v_and_b32_e32 v123, 0xffff0000, v197
	v_lshlrev_b32_e32 v126, 16, v217
	v_and_b32_e32 v127, 0xffff0000, v217
	v_add_u32_e32 v250, 0x18000, v249
	global_load_dwordx4 v[194:197], v250, s[66:67] offset:256
	global_load_dwordx4 v[214:217], v250, s[64:65] offset:256
	v_pk_add_f32 v[124:125], v[124:125], v[146:147]
	v_pk_add_f32 v[122:123], v[122:123], v[126:127]
	v_pk_add_f32 v[112:113], v[112:113], v[120:121]
	v_pk_add_f32 v[110:111], v[110:111], v[128:129]
	v_pk_add_f32 v[120:121], v[108:109], v[122:123]
	v_pk_add_f32 v[122:123], v[106:107], v[124:125]
	v_cvt_pk_bf16_f32 v106, v110, v111
	v_cvt_pk_bf16_f32 v107, v112, v113
	s_nop 0
	v_lshlrev_b32_e32 v108, 16, v106
	v_and_b32_e32 v109, 0xffff0000, v106
	v_lshlrev_b32_e32 v124, 16, v107
	v_and_b32_e32 v125, 0xffff0000, v107
	v_sub_f32_e32 v112, v112, v124
	v_sub_f32_e32 v113, v113, v125
	v_sub_f32_e32 v110, v110, v108
	v_sub_f32_e32 v111, v111, v109
	v_cvt_pk_bf16_f32 v110, v110, v111
	v_cvt_pk_bf16_f32 v111, v112, v113
	s_nop 0
	v_lshlrev_b32_e32 v112, 16, v110
	v_and_b32_e32 v113, 0xffff0000, v110
	v_lshlrev_b32_e32 v126, 16, v111
	v_and_b32_e32 v127, 0xffff0000, v111
	v_pk_add_f32 v[124:125], v[124:125], v[126:127]
	v_pk_add_f32 v[126:127], v[108:109], v[112:113]
	v_cvt_pk_bf16_f32 v108, v122, v123
	v_cvt_pk_bf16_f32 v109, v120, v121
	s_nop 0
	v_lshlrev_b32_e32 v128, 16, v108
	v_and_b32_e32 v129, 0xffff0000, v108
	v_lshlrev_b32_e32 v146, 16, v109
	v_and_b32_e32 v147, 0xffff0000, v109
	v_sub_f32_e32 v113, v120, v146
	v_sub_f32_e32 v120, v121, v147
	v_sub_f32_e32 v112, v122, v128
	v_sub_f32_e32 v121, v123, v129
	v_cvt_pk_bf16_f32 v112, v112, v121
	v_cvt_pk_bf16_f32 v113, v113, v120
	global_store_dwordx4 v[114:115], v[106:109], off
	global_store_dwordx4 v[116:117], v[110:113], off
	v_lshlrev_b32_e32 v120, 16, v112
	v_and_b32_e32 v121, 0xffff0000, v112
	v_mul_f32_e32 v106, v127, v127
	v_mul_f32_e32 v107, v125, v125
	v_pk_add_f32 v[120:121], v[128:129], v[120:121]
	v_fmac_f32_e32 v106, v126, v126
	v_fmac_f32_e32 v107, v124, v124
	v_lshlrev_b32_e32 v122, 16, v113
	v_and_b32_e32 v123, 0xffff0000, v113
	v_add_f32_e32 v106, v106, v107
	v_mul_f32_e32 v107, v121, v121
	v_pk_add_f32 v[122:123], v[146:147], v[122:123]
	v_fmac_f32_e32 v107, v120, v120
	v_add_f32_e32 v106, v106, v107
	v_mul_f32_e32 v107, v123, v123
	v_fmac_f32_e32 v107, v122, v122
	v_add_f32_e32 v124, v107, v106
	s_waitcnt vmcnt(14)
	v_lshlrev_b32_e32 v120, 16, v218
	v_and_b32_e32 v121, 0xffff0000, v218
	v_lshlrev_b32_e32 v122, 16, v222
	v_and_b32_e32 v123, 0xffff0000, v222
	v_lshlrev_b32_e32 v106, 16, v219
	v_and_b32_e32 v107, 0xffff0000, v219
	v_lshlrev_b32_e32 v110, 16, v223
	v_and_b32_e32 v111, 0xffff0000, v223
	v_pk_add_f32 v[120:121], v[120:121], v[122:123]
	v_pk_add_f32 v[106:107], v[106:107], v[110:111]
	v_lshlrev_b32_e32 v110, 16, v220
	v_and_b32_e32 v111, 0xffff0000, v220
	v_lshlrev_b32_e32 v122, 16, v224
	v_and_b32_e32 v123, 0xffff0000, v224
	v_lshlrev_b32_e32 v108, 16, v221
	v_and_b32_e32 v109, 0xffff0000, v221
	v_lshlrev_b32_e32 v112, 16, v225
	v_and_b32_e32 v113, 0xffff0000, v225
	v_add_u32_e32 v251, 0x40000, v249
	global_load_dwordx4 v[218:221], v251, s[66:67]
	global_load_dwordx4 v[222:225], v251, s[64:65]
	v_pk_add_f32 v[110:111], v[110:111], v[122:123]
	v_pk_add_f32 v[108:109], v[108:109], v[112:113]
	v_pk_add_f32 v[104:105], v[104:105], v[106:107]
	v_pk_add_f32 v[102:103], v[102:103], v[120:121]
	v_pk_add_f32 v[106:107], v[100:101], v[108:109]
	v_pk_add_f32 v[108:109], v[98:99], v[110:111]
	v_cvt_pk_bf16_f32 v98, v102, v103
	v_cvt_pk_bf16_f32 v99, v104, v105
	s_nop 0
	v_lshlrev_b32_e32 v100, 16, v98
	v_and_b32_e32 v101, 0xffff0000, v98
	v_lshlrev_b32_e32 v110, 16, v99
	v_and_b32_e32 v111, 0xffff0000, v99
	v_sub_f32_e32 v104, v104, v110
	v_sub_f32_e32 v105, v105, v111
	v_sub_f32_e32 v102, v102, v100
	v_sub_f32_e32 v103, v103, v101
	v_cvt_pk_bf16_f32 v102, v102, v103
	v_cvt_pk_bf16_f32 v103, v104, v105
	s_nop 0
	v_lshlrev_b32_e32 v104, 16, v102
	v_and_b32_e32 v105, 0xffff0000, v102
	v_lshlrev_b32_e32 v112, 16, v103
	v_and_b32_e32 v113, 0xffff0000, v103
	v_pk_add_f32 v[110:111], v[110:111], v[112:113]
	v_pk_add_f32 v[112:113], v[100:101], v[104:105]
	v_cvt_pk_bf16_f32 v100, v108, v109
	v_cvt_pk_bf16_f32 v101, v106, v107
	s_nop 0
	v_lshlrev_b32_e32 v120, 16, v100
	v_and_b32_e32 v121, 0xffff0000, v100
	v_lshlrev_b32_e32 v122, 16, v101
	v_and_b32_e32 v123, 0xffff0000, v101
	v_sub_f32_e32 v105, v106, v122
	v_sub_f32_e32 v106, v107, v123
	v_sub_f32_e32 v104, v108, v120
	v_sub_f32_e32 v107, v109, v121
	v_cvt_pk_bf16_f32 v104, v104, v107
	v_cvt_pk_bf16_f32 v105, v105, v106
	global_store_dwordx4 v[114:115], v[98:101], off offset:256
	global_store_dwordx4 v[116:117], v[102:105], off offset:256
	v_lshlrev_b32_e32 v106, 16, v104
	v_and_b32_e32 v107, 0xffff0000, v104
	v_mul_f32_e32 v98, v113, v113
	v_mul_f32_e32 v99, v111, v111
	v_pk_add_f32 v[106:107], v[120:121], v[106:107]
	v_fmac_f32_e32 v98, v112, v112
	v_fmac_f32_e32 v99, v110, v110
	v_lshlrev_b32_e32 v108, 16, v105
	v_and_b32_e32 v109, 0xffff0000, v105
	v_add_f32_e32 v98, v98, v99
	v_mul_f32_e32 v99, v107, v107
	v_pk_add_f32 v[108:109], v[122:123], v[108:109]
	v_fmac_f32_e32 v99, v106, v106
	v_add_f32_e32 v98, v98, v99
	v_mul_f32_e32 v99, v109, v109
	v_fmac_f32_e32 v99, v108, v108
	v_add_f32_e32 v98, v99, v98
	v_add_f32_e32 v98, v124, v98
	ds_bpermute_b32 v99, v204, v98
	s_waitcnt lgkmcnt(0)
	v_add_f32_e32 v102, v98, v99
	v_add_u32_e32 v98, 32, v144
	v_ashrrev_i32_e32 v99, 31, v98
	v_lshlrev_b64 v[100:101], 11, v[98:99]
	v_lshl_add_u64 v[98:99], s[66:67], 0, v[100:101]
	v_lshl_add_u64 v[98:99], v[98:99], 0, v[142:143]
	v_lshl_add_u64 v[100:101], s[64:65], 0, v[100:101]
	v_lshl_add_u64 v[100:101], v[100:101], 0, v[142:143]
	ds_bpermute_b32 v103, v205, v102
	s_waitcnt vmcnt(16)
	v_lshlrev_b32_e32 v112, 16, v226
	v_and_b32_e32 v113, 0xffff0000, v226
	v_lshlrev_b32_e32 v114, 16, v230
	v_and_b32_e32 v115, 0xffff0000, v230
	v_lshlrev_b32_e32 v104, 16, v227
	v_and_b32_e32 v105, 0xffff0000, v227
	v_lshlrev_b32_e32 v108, 16, v231
	v_and_b32_e32 v109, 0xffff0000, v231
	v_pk_add_f32 v[112:113], v[112:113], v[114:115]
	v_pk_add_f32 v[104:105], v[104:105], v[108:109]
	v_lshlrev_b32_e32 v108, 16, v228
	v_and_b32_e32 v109, 0xffff0000, v228
	v_lshlrev_b32_e32 v114, 16, v232
	v_and_b32_e32 v115, 0xffff0000, v232
	v_lshlrev_b32_e32 v106, 16, v229
	v_and_b32_e32 v107, 0xffff0000, v229
	v_lshlrev_b32_e32 v110, 16, v233
	v_and_b32_e32 v111, 0xffff0000, v233
	v_add_u32_e32 v250, 0x40000, v249
	global_load_dwordx4 v[226:229], v250, s[66:67] offset:256
	global_load_dwordx4 v[230:233], v250, s[64:65] offset:256
	v_pk_add_f32 v[108:109], v[108:109], v[114:115]
	v_pk_add_f32 v[106:107], v[106:107], v[110:111]
	v_pk_add_f32 v[96:97], v[96:97], v[104:105]
	v_pk_add_f32 v[94:95], v[94:95], v[112:113]
	v_pk_add_f32 v[104:105], v[92:93], v[106:107]
	v_pk_add_f32 v[106:107], v[90:91], v[108:109]
	v_cvt_pk_bf16_f32 v90, v94, v95
	v_cvt_pk_bf16_f32 v91, v96, v97
	s_nop 0
	v_lshlrev_b32_e32 v92, 16, v90
	v_and_b32_e32 v93, 0xffff0000, v90
	v_lshlrev_b32_e32 v108, 16, v91
	v_and_b32_e32 v109, 0xffff0000, v91
	v_sub_f32_e32 v96, v96, v108
	v_sub_f32_e32 v97, v97, v109
	v_sub_f32_e32 v94, v94, v92
	v_sub_f32_e32 v95, v95, v93
	v_cvt_pk_bf16_f32 v94, v94, v95
	v_cvt_pk_bf16_f32 v95, v96, v97
	s_nop 0
	v_lshlrev_b32_e32 v96, 16, v94
	v_and_b32_e32 v97, 0xffff0000, v94
	v_lshlrev_b32_e32 v110, 16, v95
	v_and_b32_e32 v111, 0xffff0000, v95
	v_pk_add_f32 v[108:109], v[108:109], v[110:111]
	v_pk_add_f32 v[110:111], v[92:93], v[96:97]
	v_cvt_pk_bf16_f32 v92, v106, v107
	v_cvt_pk_bf16_f32 v93, v104, v105
	s_nop 0
	v_lshlrev_b32_e32 v112, 16, v92
	v_and_b32_e32 v113, 0xffff0000, v92
	v_lshlrev_b32_e32 v114, 16, v93
	v_and_b32_e32 v115, 0xffff0000, v93
	v_sub_f32_e32 v97, v104, v114
	v_sub_f32_e32 v104, v105, v115
	v_sub_f32_e32 v96, v106, v112
	v_sub_f32_e32 v105, v107, v113
	v_cvt_pk_bf16_f32 v96, v96, v105
	v_cvt_pk_bf16_f32 v97, v97, v104
	global_store_dwordx4 v[98:99], v[90:93], off
	global_store_dwordx4 v[100:101], v[94:97], off
	v_lshlrev_b32_e32 v104, 16, v96
	v_and_b32_e32 v105, 0xffff0000, v96
	v_mul_f32_e32 v90, v111, v111
	v_mul_f32_e32 v91, v109, v109
	v_pk_add_f32 v[104:105], v[112:113], v[104:105]
	v_fmac_f32_e32 v90, v110, v110
	v_fmac_f32_e32 v91, v108, v108
	v_lshlrev_b32_e32 v106, 16, v97
	v_and_b32_e32 v107, 0xffff0000, v97
	v_add_f32_e32 v90, v90, v91
	v_mul_f32_e32 v91, v105, v105
	v_pk_add_f32 v[106:107], v[114:115], v[106:107]
	v_fmac_f32_e32 v91, v104, v104
	v_add_f32_e32 v90, v90, v91
	v_mul_f32_e32 v91, v107, v107
	v_fmac_f32_e32 v91, v106, v106
	v_add_f32_e32 v108, v91, v90
	s_waitcnt vmcnt(18)
	v_lshlrev_b32_e32 v104, 16, v170
	v_and_b32_e32 v105, 0xffff0000, v170
	v_lshlrev_b32_e32 v106, 16, v174
	v_and_b32_e32 v107, 0xffff0000, v174
	v_lshlrev_b32_e32 v90, 16, v171
	v_and_b32_e32 v91, 0xffff0000, v171
	v_lshlrev_b32_e32 v94, 16, v175
	v_and_b32_e32 v95, 0xffff0000, v175
	v_pk_add_f32 v[104:105], v[104:105], v[106:107]
	v_pk_add_f32 v[90:91], v[90:91], v[94:95]
	v_lshlrev_b32_e32 v94, 16, v172
	v_and_b32_e32 v95, 0xffff0000, v172
	v_lshlrev_b32_e32 v106, 16, v176
	v_and_b32_e32 v107, 0xffff0000, v176
	v_lshlrev_b32_e32 v92, 16, v173
	v_and_b32_e32 v93, 0xffff0000, v173
	v_lshlrev_b32_e32 v96, 16, v177
	v_and_b32_e32 v97, 0xffff0000, v177
	v_add_u32_e32 v251, 0x48000, v249
	global_load_dwordx4 v[170:173], v251, s[66:67]
	global_load_dwordx4 v[174:177], v251, s[64:65]
	v_pk_add_f32 v[94:95], v[94:95], v[106:107]
	v_pk_add_f32 v[92:93], v[92:93], v[96:97]
	v_pk_add_f32 v[88:89], v[88:89], v[90:91]
	v_pk_add_f32 v[86:87], v[86:87], v[104:105]
	v_pk_add_f32 v[90:91], v[84:85], v[92:93]
	v_pk_add_f32 v[92:93], v[82:83], v[94:95]
	v_cvt_pk_bf16_f32 v82, v86, v87
	v_cvt_pk_bf16_f32 v83, v88, v89
	s_nop 0
	v_lshlrev_b32_e32 v84, 16, v82
	v_and_b32_e32 v85, 0xffff0000, v82
	v_lshlrev_b32_e32 v94, 16, v83
	v_and_b32_e32 v95, 0xffff0000, v83
	v_sub_f32_e32 v88, v88, v94
	v_sub_f32_e32 v89, v89, v95
	v_sub_f32_e32 v86, v86, v84
	v_sub_f32_e32 v87, v87, v85
	v_cvt_pk_bf16_f32 v86, v86, v87
	v_cvt_pk_bf16_f32 v87, v88, v89
	s_nop 0
	v_lshlrev_b32_e32 v88, 16, v86
	v_and_b32_e32 v89, 0xffff0000, v86
	v_lshlrev_b32_e32 v96, 16, v87
	v_and_b32_e32 v97, 0xffff0000, v87
	v_pk_add_f32 v[94:95], v[94:95], v[96:97]
	v_pk_add_f32 v[96:97], v[84:85], v[88:89]
	v_cvt_pk_bf16_f32 v84, v92, v93
	v_cvt_pk_bf16_f32 v85, v90, v91
	s_nop 0
	v_lshlrev_b32_e32 v104, 16, v84
	v_and_b32_e32 v105, 0xffff0000, v84
	v_lshlrev_b32_e32 v106, 16, v85
	v_and_b32_e32 v107, 0xffff0000, v85
	v_sub_f32_e32 v89, v90, v106
	v_sub_f32_e32 v90, v91, v107
	v_sub_f32_e32 v88, v92, v104
	v_sub_f32_e32 v91, v93, v105
	v_cvt_pk_bf16_f32 v88, v88, v91
	v_cvt_pk_bf16_f32 v89, v89, v90
	global_store_dwordx4 v[98:99], v[82:85], off offset:256
	global_store_dwordx4 v[100:101], v[86:89], off offset:256
	v_lshlrev_b32_e32 v90, 16, v88
	v_and_b32_e32 v91, 0xffff0000, v88
	v_mul_f32_e32 v82, v97, v97
	v_mul_f32_e32 v83, v95, v95
	v_pk_add_f32 v[90:91], v[104:105], v[90:91]
	v_fmac_f32_e32 v82, v96, v96
	v_fmac_f32_e32 v83, v94, v94
	v_lshlrev_b32_e32 v92, 16, v89
	v_and_b32_e32 v93, 0xffff0000, v89
	v_add_f32_e32 v82, v82, v83
	v_mul_f32_e32 v83, v91, v91
	v_pk_add_f32 v[92:93], v[106:107], v[92:93]
	v_fmac_f32_e32 v83, v90, v90
	v_add_f32_e32 v82, v82, v83
	v_mul_f32_e32 v83, v93, v93
	v_fmac_f32_e32 v83, v92, v92
	v_add_f32_e32 v82, v83, v82
	v_add_f32_e32 v82, v108, v82
	ds_bpermute_b32 v83, v204, v82
	s_waitcnt lgkmcnt(0)
	v_add_f32_e32 v86, v82, v83
	v_add_u32_e32 v82, 48, v144
	v_ashrrev_i32_e32 v83, 31, v82
	v_lshlrev_b64 v[84:85], 11, v[82:83]
	v_lshl_add_u64 v[82:83], s[66:67], 0, v[84:85]
	v_lshl_add_u64 v[82:83], v[82:83], 0, v[142:143]
	v_lshl_add_u64 v[84:85], s[64:65], 0, v[84:85]
	v_lshl_add_u64 v[84:85], v[84:85], 0, v[142:143]
	ds_bpermute_b32 v87, v205, v86
	s_waitcnt vmcnt(18)
	v_lshlrev_b32_e32 v96, 16, v178
	v_and_b32_e32 v97, 0xffff0000, v178
	v_lshlrev_b32_e32 v98, 16, v190
	v_and_b32_e32 v99, 0xffff0000, v190
	v_lshlrev_b32_e32 v88, 16, v179
	v_and_b32_e32 v89, 0xffff0000, v179
	v_lshlrev_b32_e32 v92, 16, v191
	v_and_b32_e32 v93, 0xffff0000, v191
	v_pk_add_f32 v[96:97], v[96:97], v[98:99]
	v_pk_add_f32 v[88:89], v[88:89], v[92:93]
	v_lshlrev_b32_e32 v92, 16, v180
	v_and_b32_e32 v93, 0xffff0000, v180
	v_lshlrev_b32_e32 v98, 16, v192
	v_and_b32_e32 v99, 0xffff0000, v192
	v_lshlrev_b32_e32 v90, 16, v181
	v_and_b32_e32 v91, 0xffff0000, v181
	v_lshlrev_b32_e32 v94, 16, v193
	v_and_b32_e32 v95, 0xffff0000, v193
	v_add_u32_e32 v250, 0x48000, v249
	global_load_dwordx4 v[178:181], v250, s[66:67] offset:256
	global_load_dwordx4 v[190:193], v250, s[64:65] offset:256
	v_pk_add_f32 v[92:93], v[92:93], v[98:99]
	v_pk_add_f32 v[90:91], v[90:91], v[94:95]
	v_pk_add_f32 v[80:81], v[80:81], v[88:89]
	v_pk_add_f32 v[78:79], v[78:79], v[96:97]
	v_pk_add_f32 v[88:89], v[76:77], v[90:91]
	v_pk_add_f32 v[90:91], v[74:75], v[92:93]
	v_cvt_pk_bf16_f32 v74, v78, v79
	v_cvt_pk_bf16_f32 v75, v80, v81
	s_nop 0
	v_lshlrev_b32_e32 v76, 16, v74
	v_and_b32_e32 v77, 0xffff0000, v74
	v_lshlrev_b32_e32 v92, 16, v75
	v_and_b32_e32 v93, 0xffff0000, v75
	v_sub_f32_e32 v80, v80, v92
	v_sub_f32_e32 v81, v81, v93
	v_sub_f32_e32 v78, v78, v76
	v_sub_f32_e32 v79, v79, v77
	v_cvt_pk_bf16_f32 v78, v78, v79
	v_cvt_pk_bf16_f32 v79, v80, v81
	s_nop 0
	v_lshlrev_b32_e32 v80, 16, v78
	v_and_b32_e32 v81, 0xffff0000, v78
	v_lshlrev_b32_e32 v94, 16, v79
	v_and_b32_e32 v95, 0xffff0000, v79
	v_pk_add_f32 v[92:93], v[92:93], v[94:95]
	v_pk_add_f32 v[94:95], v[76:77], v[80:81]
	v_cvt_pk_bf16_f32 v76, v90, v91
	v_cvt_pk_bf16_f32 v77, v88, v89
	s_nop 0
	v_lshlrev_b32_e32 v96, 16, v76
	v_and_b32_e32 v97, 0xffff0000, v76
	v_lshlrev_b32_e32 v98, 16, v77
	v_and_b32_e32 v99, 0xffff0000, v77
	v_sub_f32_e32 v81, v88, v98
	v_sub_f32_e32 v88, v89, v99
	v_sub_f32_e32 v80, v90, v96
	v_sub_f32_e32 v89, v91, v97
	v_cvt_pk_bf16_f32 v80, v80, v89
	v_cvt_pk_bf16_f32 v81, v81, v88
	global_store_dwordx4 v[82:83], v[74:77], off
	global_store_dwordx4 v[84:85], v[78:81], off
	v_lshlrev_b32_e32 v88, 16, v80
	v_and_b32_e32 v89, 0xffff0000, v80
	v_mul_f32_e32 v74, v95, v95
	v_mul_f32_e32 v75, v93, v93
	v_pk_add_f32 v[88:89], v[96:97], v[88:89]
	v_fmac_f32_e32 v74, v94, v94
	v_fmac_f32_e32 v75, v92, v92
	v_lshlrev_b32_e32 v90, 16, v81
	v_and_b32_e32 v91, 0xffff0000, v81
	v_add_f32_e32 v74, v74, v75
	v_mul_f32_e32 v75, v89, v89
	v_pk_add_f32 v[90:91], v[98:99], v[90:91]
	v_fmac_f32_e32 v75, v88, v88
	v_add_f32_e32 v74, v74, v75
	v_mul_f32_e32 v75, v91, v91
	v_fmac_f32_e32 v75, v90, v90
	v_add_f32_e32 v92, v75, v74
	s_waitcnt vmcnt(18)
	v_lshlrev_b32_e32 v88, 16, v194
	v_and_b32_e32 v89, 0xffff0000, v194
	v_lshlrev_b32_e32 v90, 16, v214
	v_and_b32_e32 v91, 0xffff0000, v214
	v_lshlrev_b32_e32 v74, 16, v195
	v_and_b32_e32 v75, 0xffff0000, v195
	v_lshlrev_b32_e32 v78, 16, v215
	v_and_b32_e32 v79, 0xffff0000, v215
	v_pk_add_f32 v[88:89], v[88:89], v[90:91]
	v_pk_add_f32 v[74:75], v[74:75], v[78:79]
	v_lshlrev_b32_e32 v78, 16, v196
	v_and_b32_e32 v79, 0xffff0000, v196
	v_lshlrev_b32_e32 v90, 16, v216
	v_and_b32_e32 v91, 0xffff0000, v216
	v_lshlrev_b32_e32 v76, 16, v197
	v_and_b32_e32 v77, 0xffff0000, v197
	v_lshlrev_b32_e32 v80, 16, v217
	v_and_b32_e32 v81, 0xffff0000, v217
	v_add_u32_e32 v251, 0x50000, v249
	global_load_dwordx4 v[194:197], v251, s[66:67]
	global_load_dwordx4 v[214:217], v251, s[64:65]
	v_pk_add_f32 v[78:79], v[78:79], v[90:91]
	v_pk_add_f32 v[76:77], v[76:77], v[80:81]
	v_pk_add_f32 v[72:73], v[72:73], v[74:75]
	v_pk_add_f32 v[70:71], v[70:71], v[88:89]
	v_pk_add_f32 v[74:75], v[68:69], v[76:77]
	v_pk_add_f32 v[76:77], v[66:67], v[78:79]
	v_cvt_pk_bf16_f32 v66, v70, v71
	v_cvt_pk_bf16_f32 v67, v72, v73
	s_nop 0
	v_lshlrev_b32_e32 v68, 16, v66
	v_and_b32_e32 v69, 0xffff0000, v66
	v_lshlrev_b32_e32 v78, 16, v67
	v_and_b32_e32 v79, 0xffff0000, v67
	v_sub_f32_e32 v72, v72, v78
	v_sub_f32_e32 v73, v73, v79
	v_sub_f32_e32 v70, v70, v68
	v_sub_f32_e32 v71, v71, v69
	v_cvt_pk_bf16_f32 v70, v70, v71
	v_cvt_pk_bf16_f32 v71, v72, v73
	s_nop 0
	v_lshlrev_b32_e32 v72, 16, v70
	v_and_b32_e32 v73, 0xffff0000, v70
	v_lshlrev_b32_e32 v80, 16, v71
	v_and_b32_e32 v81, 0xffff0000, v71
	v_pk_add_f32 v[78:79], v[78:79], v[80:81]
	v_pk_add_f32 v[80:81], v[68:69], v[72:73]
	v_cvt_pk_bf16_f32 v68, v76, v77
	v_cvt_pk_bf16_f32 v69, v74, v75
	s_nop 0
	v_lshlrev_b32_e32 v88, 16, v68
	v_and_b32_e32 v89, 0xffff0000, v68
	v_lshlrev_b32_e32 v90, 16, v69
	v_and_b32_e32 v91, 0xffff0000, v69
	v_sub_f32_e32 v73, v74, v90
	v_sub_f32_e32 v74, v75, v91
	v_sub_f32_e32 v72, v76, v88
	v_sub_f32_e32 v75, v77, v89
	v_cvt_pk_bf16_f32 v72, v72, v75
	v_cvt_pk_bf16_f32 v73, v73, v74
	global_store_dwordx4 v[82:83], v[66:69], off offset:256
	global_store_dwordx4 v[84:85], v[70:73], off offset:256
	v_lshlrev_b32_e32 v74, 16, v72
	v_and_b32_e32 v75, 0xffff0000, v72
	v_mul_f32_e32 v66, v81, v81
	v_mul_f32_e32 v67, v79, v79
	v_pk_add_f32 v[74:75], v[88:89], v[74:75]
	v_fmac_f32_e32 v66, v80, v80
	v_fmac_f32_e32 v67, v78, v78
	v_lshlrev_b32_e32 v76, 16, v73
	v_and_b32_e32 v77, 0xffff0000, v73
	v_add_f32_e32 v66, v66, v67
	v_mul_f32_e32 v67, v75, v75
	v_pk_add_f32 v[76:77], v[90:91], v[76:77]
	v_fmac_f32_e32 v67, v74, v74
	v_add_f32_e32 v66, v66, v67
	v_mul_f32_e32 v67, v77, v77
	v_fmac_f32_e32 v67, v76, v76
	v_add_f32_e32 v66, v67, v66
	v_add_f32_e32 v66, v92, v66
	ds_bpermute_b32 v67, v204, v66
	s_waitcnt lgkmcnt(0)
	v_add_f32_e32 v70, v66, v67
	v_add_u32_e32 v66, 0x80, v144
	v_ashrrev_i32_e32 v67, 31, v66
	v_lshlrev_b64 v[68:69], 11, v[66:67]
	v_lshl_add_u64 v[66:67], s[66:67], 0, v[68:69]
	v_lshl_add_u64 v[66:67], v[66:67], 0, v[142:143]
	v_lshl_add_u64 v[68:69], s[64:65], 0, v[68:69]
	v_lshl_add_u64 v[68:69], v[68:69], 0, v[142:143]
	ds_bpermute_b32 v71, v205, v70
	s_waitcnt vmcnt(18)
	v_lshlrev_b32_e32 v80, 16, v218
	v_and_b32_e32 v81, 0xffff0000, v218
	v_lshlrev_b32_e32 v82, 16, v222
	v_and_b32_e32 v83, 0xffff0000, v222
	v_lshlrev_b32_e32 v72, 16, v219
	v_and_b32_e32 v73, 0xffff0000, v219
	v_lshlrev_b32_e32 v76, 16, v223
	v_and_b32_e32 v77, 0xffff0000, v223
	v_pk_add_f32 v[80:81], v[80:81], v[82:83]
	v_pk_add_f32 v[72:73], v[72:73], v[76:77]
	v_lshlrev_b32_e32 v76, 16, v220
	v_and_b32_e32 v77, 0xffff0000, v220
	v_lshlrev_b32_e32 v82, 16, v224
	v_and_b32_e32 v83, 0xffff0000, v224
	v_lshlrev_b32_e32 v74, 16, v221
	v_and_b32_e32 v75, 0xffff0000, v221
	v_lshlrev_b32_e32 v78, 16, v225
	v_and_b32_e32 v79, 0xffff0000, v225
	v_add_u32_e32 v250, 0x50000, v249
	global_load_dwordx4 v[218:221], v250, s[66:67] offset:256
	global_load_dwordx4 v[222:225], v250, s[64:65] offset:256
	v_pk_add_f32 v[76:77], v[76:77], v[82:83]
	v_pk_add_f32 v[74:75], v[74:75], v[78:79]
	v_pk_add_f32 v[64:65], v[64:65], v[72:73]
	v_pk_add_f32 v[62:63], v[62:63], v[80:81]
	v_pk_add_f32 v[72:73], v[60:61], v[74:75]
	v_pk_add_f32 v[74:75], v[58:59], v[76:77]
	v_cvt_pk_bf16_f32 v58, v62, v63
	v_cvt_pk_bf16_f32 v59, v64, v65
	s_nop 0
	v_lshlrev_b32_e32 v60, 16, v58
	v_and_b32_e32 v61, 0xffff0000, v58
	v_lshlrev_b32_e32 v76, 16, v59
	v_and_b32_e32 v77, 0xffff0000, v59
	v_sub_f32_e32 v64, v64, v76
	v_sub_f32_e32 v65, v65, v77
	v_sub_f32_e32 v62, v62, v60
	v_sub_f32_e32 v63, v63, v61
	v_cvt_pk_bf16_f32 v62, v62, v63
	v_cvt_pk_bf16_f32 v63, v64, v65
	s_nop 0
	v_lshlrev_b32_e32 v64, 16, v62
	v_and_b32_e32 v65, 0xffff0000, v62
	v_lshlrev_b32_e32 v78, 16, v63
	v_and_b32_e32 v79, 0xffff0000, v63
	v_pk_add_f32 v[76:77], v[76:77], v[78:79]
	v_pk_add_f32 v[78:79], v[60:61], v[64:65]
	v_cvt_pk_bf16_f32 v60, v74, v75
	v_cvt_pk_bf16_f32 v61, v72, v73
	s_nop 0
	v_lshlrev_b32_e32 v80, 16, v60
	v_and_b32_e32 v81, 0xffff0000, v60
	v_lshlrev_b32_e32 v82, 16, v61
	v_and_b32_e32 v83, 0xffff0000, v61
	v_sub_f32_e32 v65, v72, v82
	v_sub_f32_e32 v72, v73, v83
	v_sub_f32_e32 v64, v74, v80
	v_sub_f32_e32 v73, v75, v81
	v_cvt_pk_bf16_f32 v64, v64, v73
	v_cvt_pk_bf16_f32 v65, v65, v72
	global_store_dwordx4 v[66:67], v[58:61], off
	global_store_dwordx4 v[68:69], v[62:65], off
	v_lshlrev_b32_e32 v72, 16, v64
	v_and_b32_e32 v73, 0xffff0000, v64
	v_mul_f32_e32 v58, v79, v79
	v_mul_f32_e32 v59, v77, v77
	v_pk_add_f32 v[72:73], v[80:81], v[72:73]
	v_fmac_f32_e32 v58, v78, v78
	v_fmac_f32_e32 v59, v76, v76
	v_lshlrev_b32_e32 v74, 16, v65
	v_and_b32_e32 v75, 0xffff0000, v65
	v_add_f32_e32 v58, v58, v59
	v_mul_f32_e32 v59, v73, v73
	v_pk_add_f32 v[74:75], v[82:83], v[74:75]
	v_fmac_f32_e32 v59, v72, v72
	v_add_f32_e32 v58, v58, v59
	v_mul_f32_e32 v59, v75, v75
	v_fmac_f32_e32 v59, v74, v74
	v_add_f32_e32 v76, v59, v58
	s_waitcnt vmcnt(18)
	v_lshlrev_b32_e32 v72, 16, v226
	v_and_b32_e32 v73, 0xffff0000, v226
	v_lshlrev_b32_e32 v74, 16, v230
	v_and_b32_e32 v75, 0xffff0000, v230
	v_lshlrev_b32_e32 v58, 16, v227
	v_and_b32_e32 v59, 0xffff0000, v227
	v_lshlrev_b32_e32 v62, 16, v231
	v_and_b32_e32 v63, 0xffff0000, v231
	v_pk_add_f32 v[72:73], v[72:73], v[74:75]
	v_pk_add_f32 v[58:59], v[58:59], v[62:63]
	v_lshlrev_b32_e32 v62, 16, v228
	v_and_b32_e32 v63, 0xffff0000, v228
	v_lshlrev_b32_e32 v74, 16, v232
	v_and_b32_e32 v75, 0xffff0000, v232
	v_lshlrev_b32_e32 v60, 16, v229
	v_and_b32_e32 v61, 0xffff0000, v229
	v_lshlrev_b32_e32 v64, 16, v233
	v_and_b32_e32 v65, 0xffff0000, v233
	v_add_u32_e32 v251, 0x58000, v249
	global_load_dwordx4 v[226:229], v251, s[66:67]
	global_load_dwordx4 v[230:233], v251, s[64:65]
	v_pk_add_f32 v[62:63], v[62:63], v[74:75]
	v_pk_add_f32 v[60:61], v[60:61], v[64:65]
	v_pk_add_f32 v[56:57], v[56:57], v[58:59]
	v_pk_add_f32 v[54:55], v[54:55], v[72:73]
	v_pk_add_f32 v[58:59], v[52:53], v[60:61]
	v_pk_add_f32 v[60:61], v[50:51], v[62:63]
	v_cvt_pk_bf16_f32 v50, v54, v55
	v_cvt_pk_bf16_f32 v51, v56, v57
	s_nop 0
	v_lshlrev_b32_e32 v52, 16, v50
	v_and_b32_e32 v53, 0xffff0000, v50
	v_lshlrev_b32_e32 v62, 16, v51
	v_and_b32_e32 v63, 0xffff0000, v51
	v_sub_f32_e32 v56, v56, v62
	v_sub_f32_e32 v57, v57, v63
	v_sub_f32_e32 v54, v54, v52
	v_sub_f32_e32 v55, v55, v53
	v_cvt_pk_bf16_f32 v54, v54, v55
	v_cvt_pk_bf16_f32 v55, v56, v57
	s_nop 0
	v_lshlrev_b32_e32 v56, 16, v54
	v_and_b32_e32 v57, 0xffff0000, v54
	v_lshlrev_b32_e32 v64, 16, v55
	v_and_b32_e32 v65, 0xffff0000, v55
	v_pk_add_f32 v[62:63], v[62:63], v[64:65]
	v_pk_add_f32 v[64:65], v[52:53], v[56:57]
	v_cvt_pk_bf16_f32 v52, v60, v61
	v_cvt_pk_bf16_f32 v53, v58, v59
	s_nop 0
	v_lshlrev_b32_e32 v72, 16, v52
	v_and_b32_e32 v73, 0xffff0000, v52
	v_lshlrev_b32_e32 v74, 16, v53
	v_and_b32_e32 v75, 0xffff0000, v53
	v_sub_f32_e32 v57, v58, v74
	v_sub_f32_e32 v58, v59, v75
	v_sub_f32_e32 v56, v60, v72
	v_sub_f32_e32 v59, v61, v73
	v_cvt_pk_bf16_f32 v56, v56, v59
	v_cvt_pk_bf16_f32 v57, v57, v58
	global_store_dwordx4 v[66:67], v[50:53], off offset:256
	global_store_dwordx4 v[68:69], v[54:57], off offset:256
	v_lshlrev_b32_e32 v58, 16, v56
	v_and_b32_e32 v59, 0xffff0000, v56
	v_mul_f32_e32 v50, v65, v65
	v_mul_f32_e32 v51, v63, v63
	v_pk_add_f32 v[58:59], v[72:73], v[58:59]
	v_fmac_f32_e32 v50, v64, v64
	v_fmac_f32_e32 v51, v62, v62
	v_lshlrev_b32_e32 v60, 16, v57
	v_and_b32_e32 v61, 0xffff0000, v57
	v_add_f32_e32 v50, v50, v51
	v_mul_f32_e32 v51, v59, v59
	v_pk_add_f32 v[60:61], v[74:75], v[60:61]
	v_fmac_f32_e32 v51, v58, v58
	v_add_f32_e32 v50, v50, v51
	v_mul_f32_e32 v51, v61, v61
	v_fmac_f32_e32 v51, v60, v60
	v_add_f32_e32 v50, v51, v50
	v_add_f32_e32 v50, v76, v50
	ds_bpermute_b32 v51, v204, v50
	s_waitcnt lgkmcnt(0)
	v_add_f32_e32 v54, v50, v51
	v_add_u32_e32 v50, 0x90, v144
	v_ashrrev_i32_e32 v51, 31, v50
	v_lshlrev_b64 v[52:53], 11, v[50:51]
	v_lshl_add_u64 v[50:51], s[66:67], 0, v[52:53]
	v_lshl_add_u64 v[50:51], v[50:51], 0, v[142:143]
	v_lshl_add_u64 v[52:53], s[64:65], 0, v[52:53]
	v_lshl_add_u64 v[52:53], v[52:53], 0, v[142:143]
	ds_bpermute_b32 v55, v205, v54
	s_waitcnt vmcnt(18)
	v_lshlrev_b32_e32 v64, 16, v170
	v_and_b32_e32 v65, 0xffff0000, v170
	v_lshlrev_b32_e32 v66, 16, v174
	v_and_b32_e32 v67, 0xffff0000, v174
	v_lshlrev_b32_e32 v56, 16, v171
	v_and_b32_e32 v57, 0xffff0000, v171
	v_lshlrev_b32_e32 v60, 16, v175
	v_and_b32_e32 v61, 0xffff0000, v175
	v_pk_add_f32 v[64:65], v[64:65], v[66:67]
	v_pk_add_f32 v[56:57], v[56:57], v[60:61]
	v_lshlrev_b32_e32 v60, 16, v172
	v_and_b32_e32 v61, 0xffff0000, v172
	v_lshlrev_b32_e32 v66, 16, v176
	v_and_b32_e32 v67, 0xffff0000, v176
	v_lshlrev_b32_e32 v58, 16, v173
	v_and_b32_e32 v59, 0xffff0000, v173
	v_lshlrev_b32_e32 v62, 16, v177
	v_and_b32_e32 v63, 0xffff0000, v177
	v_add_u32_e32 v250, 0x58000, v249
	global_load_dwordx4 v[170:173], v250, s[66:67] offset:256
	global_load_dwordx4 v[174:177], v250, s[64:65] offset:256
	v_pk_add_f32 v[60:61], v[60:61], v[66:67]
	v_pk_add_f32 v[58:59], v[58:59], v[62:63]
	v_pk_add_f32 v[48:49], v[48:49], v[56:57]
	v_pk_add_f32 v[46:47], v[46:47], v[64:65]
	v_pk_add_f32 v[56:57], v[44:45], v[58:59]
	v_pk_add_f32 v[58:59], v[42:43], v[60:61]
	v_cvt_pk_bf16_f32 v42, v46, v47
	v_cvt_pk_bf16_f32 v43, v48, v49
	s_nop 0
	v_lshlrev_b32_e32 v44, 16, v42
	v_and_b32_e32 v45, 0xffff0000, v42
	v_lshlrev_b32_e32 v60, 16, v43
	v_and_b32_e32 v61, 0xffff0000, v43
	v_sub_f32_e32 v48, v48, v60
	v_sub_f32_e32 v49, v49, v61
	v_sub_f32_e32 v46, v46, v44
	v_sub_f32_e32 v47, v47, v45
	v_cvt_pk_bf16_f32 v46, v46, v47
	v_cvt_pk_bf16_f32 v47, v48, v49
	s_nop 0
	v_lshlrev_b32_e32 v48, 16, v46
	v_and_b32_e32 v49, 0xffff0000, v46
	v_lshlrev_b32_e32 v62, 16, v47
	v_and_b32_e32 v63, 0xffff0000, v47
	v_pk_add_f32 v[60:61], v[60:61], v[62:63]
	v_pk_add_f32 v[62:63], v[44:45], v[48:49]
	v_cvt_pk_bf16_f32 v44, v58, v59
	v_cvt_pk_bf16_f32 v45, v56, v57
	s_nop 0
	v_lshlrev_b32_e32 v64, 16, v44
	v_and_b32_e32 v65, 0xffff0000, v44
	v_lshlrev_b32_e32 v66, 16, v45
	v_and_b32_e32 v67, 0xffff0000, v45
	v_sub_f32_e32 v49, v56, v66
	v_sub_f32_e32 v56, v57, v67
	v_sub_f32_e32 v48, v58, v64
	v_sub_f32_e32 v57, v59, v65
	v_cvt_pk_bf16_f32 v48, v48, v57
	v_cvt_pk_bf16_f32 v49, v49, v56
	global_store_dwordx4 v[50:51], v[42:45], off
	global_store_dwordx4 v[52:53], v[46:49], off
	v_lshlrev_b32_e32 v56, 16, v48
	v_and_b32_e32 v57, 0xffff0000, v48
	v_mul_f32_e32 v42, v63, v63
	v_mul_f32_e32 v43, v61, v61
	v_pk_add_f32 v[56:57], v[64:65], v[56:57]
	v_fmac_f32_e32 v42, v62, v62
	v_fmac_f32_e32 v43, v60, v60
	v_lshlrev_b32_e32 v58, 16, v49
	v_and_b32_e32 v59, 0xffff0000, v49
	v_add_f32_e32 v42, v42, v43
	v_mul_f32_e32 v43, v57, v57
	v_pk_add_f32 v[58:59], v[66:67], v[58:59]
	v_fmac_f32_e32 v43, v56, v56
	v_add_f32_e32 v42, v42, v43
	v_mul_f32_e32 v43, v59, v59
	v_fmac_f32_e32 v43, v58, v58
	v_add_f32_e32 v60, v43, v42
	s_waitcnt vmcnt(18)
	v_lshlrev_b32_e32 v56, 16, v178
	v_and_b32_e32 v57, 0xffff0000, v178
	v_lshlrev_b32_e32 v58, 16, v190
	v_and_b32_e32 v59, 0xffff0000, v190
	v_lshlrev_b32_e32 v42, 16, v179
	v_and_b32_e32 v43, 0xffff0000, v179
	v_lshlrev_b32_e32 v46, 16, v191
	v_and_b32_e32 v47, 0xffff0000, v191
	v_pk_add_f32 v[56:57], v[56:57], v[58:59]
	v_pk_add_f32 v[42:43], v[42:43], v[46:47]
	v_lshlrev_b32_e32 v46, 16, v180
	v_and_b32_e32 v47, 0xffff0000, v180
	v_lshlrev_b32_e32 v58, 16, v192
	v_and_b32_e32 v59, 0xffff0000, v192
	v_lshlrev_b32_e32 v44, 16, v181
	v_and_b32_e32 v45, 0xffff0000, v181
	v_lshlrev_b32_e32 v48, 16, v193
	v_and_b32_e32 v49, 0xffff0000, v193
	v_pk_add_f32 v[46:47], v[46:47], v[58:59]
	v_pk_add_f32 v[44:45], v[44:45], v[48:49]
	v_pk_add_f32 v[40:41], v[40:41], v[42:43]
	v_pk_add_f32 v[38:39], v[38:39], v[56:57]
	v_pk_add_f32 v[42:43], v[36:37], v[44:45]
	v_pk_add_f32 v[44:45], v[34:35], v[46:47]
	v_cvt_pk_bf16_f32 v34, v38, v39
	v_cvt_pk_bf16_f32 v35, v40, v41
	s_nop 0
	v_lshlrev_b32_e32 v36, 16, v34
	v_and_b32_e32 v37, 0xffff0000, v34
	v_lshlrev_b32_e32 v46, 16, v35
	v_and_b32_e32 v47, 0xffff0000, v35
	v_sub_f32_e32 v40, v40, v46
	v_sub_f32_e32 v41, v41, v47
	v_sub_f32_e32 v38, v38, v36
	v_sub_f32_e32 v39, v39, v37
	v_cvt_pk_bf16_f32 v38, v38, v39
	v_cvt_pk_bf16_f32 v39, v40, v41
	s_nop 0
	v_lshlrev_b32_e32 v40, 16, v38
	v_and_b32_e32 v41, 0xffff0000, v38
	v_lshlrev_b32_e32 v48, 16, v39
	v_and_b32_e32 v49, 0xffff0000, v39
	v_pk_add_f32 v[46:47], v[46:47], v[48:49]
	v_pk_add_f32 v[48:49], v[36:37], v[40:41]
	v_cvt_pk_bf16_f32 v36, v44, v45
	v_cvt_pk_bf16_f32 v37, v42, v43
	s_nop 0
	v_lshlrev_b32_e32 v56, 16, v36
	v_and_b32_e32 v57, 0xffff0000, v36
	v_lshlrev_b32_e32 v58, 16, v37
	v_and_b32_e32 v59, 0xffff0000, v37
	v_sub_f32_e32 v41, v42, v58
	v_sub_f32_e32 v42, v43, v59
	v_sub_f32_e32 v40, v44, v56
	v_sub_f32_e32 v43, v45, v57
	v_cvt_pk_bf16_f32 v40, v40, v43
	v_cvt_pk_bf16_f32 v41, v41, v42
	global_store_dwordx4 v[50:51], v[34:37], off offset:256
	global_store_dwordx4 v[52:53], v[38:41], off offset:256
	v_lshlrev_b32_e32 v42, 16, v40
	v_and_b32_e32 v43, 0xffff0000, v40
	v_mul_f32_e32 v34, v49, v49
	v_mul_f32_e32 v35, v47, v47
	v_pk_add_f32 v[42:43], v[56:57], v[42:43]
	v_fmac_f32_e32 v34, v48, v48
	v_fmac_f32_e32 v35, v46, v46
	v_add_u32_e32 v36, 0xa0, v144
	v_lshlrev_b32_e32 v44, 16, v41
	v_and_b32_e32 v45, 0xffff0000, v41
	v_add_f32_e32 v34, v34, v35
	v_mul_f32_e32 v35, v43, v43
	v_ashrrev_i32_e32 v37, 31, v36
	v_pk_add_f32 v[44:45], v[58:59], v[44:45]
	v_fmac_f32_e32 v35, v42, v42
	v_lshlrev_b64 v[36:37], 11, v[36:37]
	v_add_f32_e32 v34, v34, v35
	v_mul_f32_e32 v35, v45, v45
	v_lshl_add_u64 v[38:39], s[66:67], 0, v[36:37]
	v_fmac_f32_e32 v35, v44, v44
	v_lshl_add_u64 v[44:45], v[38:39], 0, v[142:143]
	v_lshl_add_u64 v[36:37], s[64:65], 0, v[36:37]
	v_lshl_add_u64 v[46:47], v[36:37], 0, v[142:143]
	v_add_f32_e32 v34, v35, v34
	v_add_f32_e32 v34, v60, v34
	ds_bpermute_b32 v35, v204, v34
	s_waitcnt lgkmcnt(0)
	v_add_f32_e32 v34, v34, v35
	ds_bpermute_b32 v35, v205, v34
	s_waitcnt vmcnt(16)
	v_lshlrev_b32_e32 v48, 16, v194
	v_and_b32_e32 v49, 0xffff0000, v194
	v_lshlrev_b32_e32 v50, 16, v214
	v_and_b32_e32 v51, 0xffff0000, v214
	v_lshlrev_b32_e32 v36, 16, v195
	v_and_b32_e32 v37, 0xffff0000, v195
	v_lshlrev_b32_e32 v40, 16, v215
	v_and_b32_e32 v41, 0xffff0000, v215
	v_pk_add_f32 v[48:49], v[48:49], v[50:51]
	v_pk_add_f32 v[36:37], v[36:37], v[40:41]
	v_lshlrev_b32_e32 v40, 16, v196
	v_and_b32_e32 v41, 0xffff0000, v196
	v_lshlrev_b32_e32 v50, 16, v216
	v_and_b32_e32 v51, 0xffff0000, v216
	v_lshlrev_b32_e32 v38, 16, v197
	v_and_b32_e32 v39, 0xffff0000, v197
	v_lshlrev_b32_e32 v42, 16, v217
	v_and_b32_e32 v43, 0xffff0000, v217
	v_pk_add_f32 v[40:41], v[40:41], v[50:51]
	v_pk_add_f32 v[38:39], v[38:39], v[42:43]
	v_pk_add_f32 v[32:33], v[32:33], v[36:37]
	v_pk_add_f32 v[30:31], v[30:31], v[48:49]
	v_pk_add_f32 v[36:37], v[28:29], v[38:39]
	v_pk_add_f32 v[38:39], v[26:27], v[40:41]
	v_cvt_pk_bf16_f32 v26, v30, v31
	v_cvt_pk_bf16_f32 v27, v32, v33
	s_nop 0
	v_lshlrev_b32_e32 v28, 16, v26
	v_and_b32_e32 v29, 0xffff0000, v26
	v_lshlrev_b32_e32 v40, 16, v27
	v_and_b32_e32 v41, 0xffff0000, v27
	v_sub_f32_e32 v32, v32, v40
	v_sub_f32_e32 v33, v33, v41
	v_sub_f32_e32 v30, v30, v28
	v_sub_f32_e32 v31, v31, v29
	v_cvt_pk_bf16_f32 v30, v30, v31
	v_cvt_pk_bf16_f32 v31, v32, v33
	s_nop 0
	v_lshlrev_b32_e32 v32, 16, v30
	v_and_b32_e32 v33, 0xffff0000, v30
	v_lshlrev_b32_e32 v42, 16, v31
	v_and_b32_e32 v43, 0xffff0000, v31
	v_pk_add_f32 v[40:41], v[40:41], v[42:43]
	v_pk_add_f32 v[42:43], v[28:29], v[32:33]
	v_cvt_pk_bf16_f32 v28, v38, v39
	v_cvt_pk_bf16_f32 v29, v36, v37
	s_nop 0
	v_lshlrev_b32_e32 v48, 16, v28
	v_and_b32_e32 v49, 0xffff0000, v28
	v_lshlrev_b32_e32 v50, 16, v29
	v_and_b32_e32 v51, 0xffff0000, v29
	v_sub_f32_e32 v33, v36, v50
	v_sub_f32_e32 v36, v37, v51
	v_sub_f32_e32 v32, v38, v48
	v_sub_f32_e32 v37, v39, v49
	v_cvt_pk_bf16_f32 v32, v32, v37
	v_cvt_pk_bf16_f32 v33, v33, v36
	global_store_dwordx4 v[44:45], v[26:29], off
	global_store_dwordx4 v[46:47], v[30:33], off
	v_lshlrev_b32_e32 v36, 16, v32
	v_and_b32_e32 v37, 0xffff0000, v32
	v_mul_f32_e32 v26, v43, v43
	v_mul_f32_e32 v27, v41, v41
	v_pk_add_f32 v[36:37], v[48:49], v[36:37]
	v_fmac_f32_e32 v26, v42, v42
	v_fmac_f32_e32 v27, v40, v40
	v_lshlrev_b32_e32 v38, 16, v33
	v_and_b32_e32 v39, 0xffff0000, v33
	v_add_f32_e32 v26, v26, v27
	v_mul_f32_e32 v27, v37, v37
	v_pk_add_f32 v[38:39], v[50:51], v[38:39]
	v_fmac_f32_e32 v27, v36, v36
	v_add_f32_e32 v26, v26, v27
	v_mul_f32_e32 v27, v39, v39
	v_fmac_f32_e32 v27, v38, v38
	v_add_f32_e32 v40, v27, v26
	s_waitcnt vmcnt(14)
	v_lshlrev_b32_e32 v36, 16, v218
	v_and_b32_e32 v37, 0xffff0000, v218
	v_lshlrev_b32_e32 v38, 16, v222
	v_and_b32_e32 v39, 0xffff0000, v222
	v_lshlrev_b32_e32 v26, 16, v219
	v_and_b32_e32 v27, 0xffff0000, v219
	v_lshlrev_b32_e32 v30, 16, v223
	v_and_b32_e32 v31, 0xffff0000, v223
	v_pk_add_f32 v[36:37], v[36:37], v[38:39]
	v_pk_add_f32 v[26:27], v[26:27], v[30:31]
	v_lshlrev_b32_e32 v30, 16, v220
	v_and_b32_e32 v31, 0xffff0000, v220
	v_lshlrev_b32_e32 v38, 16, v224
	v_and_b32_e32 v39, 0xffff0000, v224
	v_lshlrev_b32_e32 v28, 16, v221
	v_and_b32_e32 v29, 0xffff0000, v221
	v_lshlrev_b32_e32 v32, 16, v225
	v_and_b32_e32 v33, 0xffff0000, v225
	v_pk_add_f32 v[30:31], v[30:31], v[38:39]
	v_pk_add_f32 v[28:29], v[28:29], v[32:33]
	v_pk_add_f32 v[24:25], v[24:25], v[26:27]
	v_pk_add_f32 v[22:23], v[22:23], v[36:37]
	v_pk_add_f32 v[26:27], v[20:21], v[28:29]
	v_pk_add_f32 v[28:29], v[18:19], v[30:31]
	v_cvt_pk_bf16_f32 v18, v22, v23
	v_cvt_pk_bf16_f32 v19, v24, v25
	s_nop 0
	v_lshlrev_b32_e32 v20, 16, v18
	v_and_b32_e32 v21, 0xffff0000, v18
	v_lshlrev_b32_e32 v30, 16, v19
	v_and_b32_e32 v31, 0xffff0000, v19
	v_sub_f32_e32 v24, v24, v30
	v_sub_f32_e32 v25, v25, v31
	v_sub_f32_e32 v22, v22, v20
	v_sub_f32_e32 v23, v23, v21
	v_cvt_pk_bf16_f32 v22, v22, v23
	v_cvt_pk_bf16_f32 v23, v24, v25
	s_nop 0
	v_lshlrev_b32_e32 v24, 16, v22
	v_and_b32_e32 v25, 0xffff0000, v22
	v_lshlrev_b32_e32 v32, 16, v23
	v_and_b32_e32 v33, 0xffff0000, v23
	v_pk_add_f32 v[30:31], v[30:31], v[32:33]
	v_pk_add_f32 v[32:33], v[20:21], v[24:25]
	v_cvt_pk_bf16_f32 v20, v28, v29
	v_cvt_pk_bf16_f32 v21, v26, v27
	s_nop 0
	v_lshlrev_b32_e32 v36, 16, v20
	v_and_b32_e32 v37, 0xffff0000, v20
	v_lshlrev_b32_e32 v38, 16, v21
	v_and_b32_e32 v39, 0xffff0000, v21
	v_sub_f32_e32 v25, v26, v38
	v_sub_f32_e32 v26, v27, v39
	v_sub_f32_e32 v24, v28, v36
	v_sub_f32_e32 v27, v29, v37
	v_cvt_pk_bf16_f32 v24, v24, v27
	v_cvt_pk_bf16_f32 v25, v25, v26
	global_store_dwordx4 v[44:45], v[18:21], off offset:256
	global_store_dwordx4 v[46:47], v[22:25], off offset:256
	v_lshlrev_b32_e32 v26, 16, v24
	v_and_b32_e32 v27, 0xffff0000, v24
	v_mul_f32_e32 v18, v33, v33
	v_mul_f32_e32 v19, v31, v31
	v_pk_add_f32 v[26:27], v[36:37], v[26:27]
	v_fmac_f32_e32 v18, v32, v32
	v_fmac_f32_e32 v19, v30, v30
	v_lshlrev_b32_e32 v28, 16, v25
	v_and_b32_e32 v29, 0xffff0000, v25
	v_add_f32_e32 v18, v18, v19
	v_mul_f32_e32 v19, v27, v27
	v_pk_add_f32 v[28:29], v[38:39], v[28:29]
	v_fmac_f32_e32 v19, v26, v26
	v_add_f32_e32 v18, v18, v19
	v_mul_f32_e32 v19, v29, v29
	v_fmac_f32_e32 v19, v28, v28
	v_add_f32_e32 v18, v19, v18
	v_add_f32_e32 v18, v40, v18
	ds_bpermute_b32 v19, v204, v18
	s_waitcnt lgkmcnt(0)
	v_add_f32_e32 v30, v18, v19
	v_add_u32_e32 v18, 0xb0, v144
	v_ashrrev_i32_e32 v19, 31, v18
	v_lshlrev_b64 v[18:19], 11, v[18:19]
	v_lshl_add_u64 v[20:21], s[66:67], 0, v[18:19]
	v_lshl_add_u64 v[26:27], v[20:21], 0, v[142:143]
	v_lshl_add_u64 v[18:19], s[64:65], 0, v[18:19]
	v_lshl_add_u64 v[28:29], v[18:19], 0, v[142:143]
	ds_bpermute_b32 v31, v205, v30
	s_waitcnt vmcnt(12)
	v_lshlrev_b32_e32 v32, 16, v226
	v_and_b32_e32 v33, 0xffff0000, v226
	v_lshlrev_b32_e32 v36, 16, v230
	v_and_b32_e32 v37, 0xffff0000, v230
	v_lshlrev_b32_e32 v18, 16, v227
	v_and_b32_e32 v19, 0xffff0000, v227
	v_lshlrev_b32_e32 v22, 16, v231
	v_and_b32_e32 v23, 0xffff0000, v231
	v_pk_add_f32 v[32:33], v[32:33], v[36:37]
	v_pk_add_f32 v[18:19], v[18:19], v[22:23]
	v_lshlrev_b32_e32 v22, 16, v228
	v_and_b32_e32 v23, 0xffff0000, v228
	v_lshlrev_b32_e32 v36, 16, v232
	v_and_b32_e32 v37, 0xffff0000, v232
	v_lshlrev_b32_e32 v20, 16, v229
	v_and_b32_e32 v21, 0xffff0000, v229
	v_lshlrev_b32_e32 v24, 16, v233
	v_and_b32_e32 v25, 0xffff0000, v233
	v_pk_add_f32 v[22:23], v[22:23], v[36:37]
	v_pk_add_f32 v[20:21], v[20:21], v[24:25]
	v_pk_add_f32 v[16:17], v[16:17], v[18:19]
	v_pk_add_f32 v[14:15], v[14:15], v[32:33]
	v_pk_add_f32 v[18:19], v[12:13], v[20:21]
	v_pk_add_f32 v[20:21], v[10:11], v[22:23]
	v_cvt_pk_bf16_f32 v10, v14, v15
	v_cvt_pk_bf16_f32 v11, v16, v17
	s_nop 0
	v_lshlrev_b32_e32 v12, 16, v10
	v_and_b32_e32 v13, 0xffff0000, v10
	v_lshlrev_b32_e32 v22, 16, v11
	v_and_b32_e32 v23, 0xffff0000, v11
	v_sub_f32_e32 v16, v16, v22
	v_sub_f32_e32 v17, v17, v23
	v_sub_f32_e32 v14, v14, v12
	v_sub_f32_e32 v15, v15, v13
	v_cvt_pk_bf16_f32 v14, v14, v15
	v_cvt_pk_bf16_f32 v15, v16, v17
	s_nop 0
	v_lshlrev_b32_e32 v16, 16, v14
	v_and_b32_e32 v17, 0xffff0000, v14
	v_lshlrev_b32_e32 v24, 16, v15
	v_and_b32_e32 v25, 0xffff0000, v15
	v_pk_add_f32 v[22:23], v[22:23], v[24:25]
	v_pk_add_f32 v[24:25], v[12:13], v[16:17]
	v_cvt_pk_bf16_f32 v12, v20, v21
	v_cvt_pk_bf16_f32 v13, v18, v19
	s_nop 0
	v_lshlrev_b32_e32 v32, 16, v12
	v_and_b32_e32 v33, 0xffff0000, v12
	v_lshlrev_b32_e32 v36, 16, v13
	v_and_b32_e32 v37, 0xffff0000, v13
	v_sub_f32_e32 v17, v18, v36
	v_sub_f32_e32 v18, v19, v37
	v_sub_f32_e32 v16, v20, v32
	v_sub_f32_e32 v19, v21, v33
	v_cvt_pk_bf16_f32 v16, v16, v19
	v_cvt_pk_bf16_f32 v17, v17, v18
	global_store_dwordx4 v[26:27], v[10:13], off
	global_store_dwordx4 v[28:29], v[14:17], off
	v_lshlrev_b32_e32 v18, 16, v16
	v_and_b32_e32 v19, 0xffff0000, v16
	v_mul_f32_e32 v10, v25, v25
	v_mul_f32_e32 v11, v23, v23
	v_pk_add_f32 v[18:19], v[32:33], v[18:19]
	v_fmac_f32_e32 v10, v24, v24
	v_fmac_f32_e32 v11, v22, v22
	v_lshlrev_b32_e32 v20, 16, v17
	v_and_b32_e32 v21, 0xffff0000, v17
	v_add_f32_e32 v10, v10, v11
	v_mul_f32_e32 v11, v19, v19
	v_pk_add_f32 v[20:21], v[36:37], v[20:21]
	v_fmac_f32_e32 v11, v18, v18
	v_add_f32_e32 v10, v10, v11
	v_mul_f32_e32 v11, v21, v21
	v_fmac_f32_e32 v11, v20, v20
	v_add_f32_e32 v18, v11, v10
	s_waitcnt vmcnt(10)
	v_lshlrev_b32_e32 v20, 16, v170
	v_and_b32_e32 v21, 0xffff0000, v170
	v_lshlrev_b32_e32 v22, 16, v174
	v_and_b32_e32 v23, 0xffff0000, v174
	v_lshlrev_b32_e32 v10, 16, v171
	v_and_b32_e32 v11, 0xffff0000, v171
	v_lshlrev_b32_e32 v14, 16, v175
	v_and_b32_e32 v15, 0xffff0000, v175
	v_pk_add_f32 v[20:21], v[20:21], v[22:23]
	v_pk_add_f32 v[10:11], v[10:11], v[14:15]
	v_lshlrev_b32_e32 v14, 16, v172
	v_and_b32_e32 v15, 0xffff0000, v172
	v_lshlrev_b32_e32 v22, 16, v176
	v_and_b32_e32 v23, 0xffff0000, v176
	v_lshlrev_b32_e32 v12, 16, v173
	v_and_b32_e32 v13, 0xffff0000, v173
	v_lshlrev_b32_e32 v16, 16, v177
	v_and_b32_e32 v17, 0xffff0000, v177
	v_pk_add_f32 v[14:15], v[14:15], v[22:23]
	v_pk_add_f32 v[12:13], v[12:13], v[16:17]
	v_pk_add_f32 v[8:9], v[8:9], v[10:11]
	v_pk_add_f32 v[6:7], v[6:7], v[20:21]
	v_pk_add_f32 v[10:11], v[4:5], v[12:13]
	v_pk_add_f32 v[12:13], v[2:3], v[14:15]
	v_cvt_pk_bf16_f32 v2, v6, v7
	v_cvt_pk_bf16_f32 v3, v8, v9
	s_nop 0
	v_lshlrev_b32_e32 v4, 16, v2
	v_and_b32_e32 v5, 0xffff0000, v2
	v_lshlrev_b32_e32 v14, 16, v3
	v_and_b32_e32 v15, 0xffff0000, v3
	v_sub_f32_e32 v8, v8, v14
	v_sub_f32_e32 v9, v9, v15
	v_sub_f32_e32 v6, v6, v4
	v_sub_f32_e32 v7, v7, v5
	v_cvt_pk_bf16_f32 v6, v6, v7
	v_cvt_pk_bf16_f32 v7, v8, v9
	s_nop 0
	v_lshlrev_b32_e32 v8, 16, v6
	v_and_b32_e32 v9, 0xffff0000, v6
	v_lshlrev_b32_e32 v16, 16, v7
	v_and_b32_e32 v17, 0xffff0000, v7
	v_pk_add_f32 v[14:15], v[14:15], v[16:17]
	v_pk_add_f32 v[16:17], v[4:5], v[8:9]
	v_cvt_pk_bf16_f32 v4, v12, v13
	v_cvt_pk_bf16_f32 v5, v10, v11
	s_nop 0
	v_lshlrev_b32_e32 v20, 16, v4
	v_and_b32_e32 v21, 0xffff0000, v4
	v_lshlrev_b32_e32 v22, 16, v5
	v_and_b32_e32 v23, 0xffff0000, v5
	v_sub_f32_e32 v9, v10, v22
	v_sub_f32_e32 v10, v11, v23
	v_sub_f32_e32 v8, v12, v20
	v_sub_f32_e32 v11, v13, v21
	v_cvt_pk_bf16_f32 v8, v8, v11
	v_cvt_pk_bf16_f32 v9, v9, v10
	global_store_dwordx4 v[26:27], v[2:5], off offset:256
	global_store_dwordx4 v[28:29], v[6:9], off offset:256
	v_lshlrev_b32_e32 v10, 16, v8
	v_and_b32_e32 v11, 0xffff0000, v8
	v_mul_f32_e32 v2, v17, v17
	v_mul_f32_e32 v3, v15, v15
	v_pk_add_f32 v[10:11], v[20:21], v[10:11]
	v_fmac_f32_e32 v2, v16, v16
	v_fmac_f32_e32 v3, v14, v14
	v_lshlrev_b32_e32 v12, 16, v9
	v_and_b32_e32 v13, 0xffff0000, v9
	v_add_f32_e32 v2, v2, v3
	v_mul_f32_e32 v3, v11, v11
	v_pk_add_f32 v[12:13], v[22:23], v[12:13]
	v_fmac_f32_e32 v3, v10, v10
	v_add_f32_e32 v2, v2, v3
	v_mul_f32_e32 v3, v13, v13
	v_fmac_f32_e32 v3, v12, v12
	v_add_f32_e32 v2, v3, v2
	v_add_f32_e32 v2, v18, v2
	ds_bpermute_b32 v3, v204, v2
	s_waitcnt lgkmcnt(0)
	v_add_f32_e32 v2, v2, v3
	ds_bpermute_b32 v3, v205, v2
	s_and_saveexec_b64 s[24:25], s[10:11]
	s_cbranch_execz .LBB11_2334
	s_ashr_i32 s23, s22, 31
	s_lshl_b64 s[0:1], s[22:23], 2
	s_add_u32 s0, s28, s0
	v_ashrrev_i32_e32 v141, 31, v140
	s_addc_u32 s1, s29, s1
	s_waitcnt lgkmcnt(0)
	v_add_f32_e32 v4, v2, v3
	v_add_f32_e32 v11, v118, v119
	v_lshl_add_u64 v[2:3], v[140:141], 2, s[0:1]
	v_add_f32_e32 v5, v30, v31
	v_add_f32_e32 v6, v34, v35
	v_add_f32_e32 v7, v54, v55
	v_add_f32_e32 v8, v70, v71
	v_add_f32_e32 v9, v86, v87
	v_add_f32_e32 v10, v102, v103
	global_atomic_add_f32 v[2:3], v11, off
	global_atomic_add_f32 v[2:3], v10, off offset:64
	global_atomic_add_f32 v[2:3], v9, off offset:128
	global_atomic_add_f32 v[2:3], v8, off offset:192
	global_atomic_add_f32 v[2:3], v7, off offset:512
	global_atomic_add_f32 v[2:3], v6, off offset:576
	global_atomic_add_f32 v[2:3], v5, off offset:640
	global_atomic_add_f32 v[2:3], v4, off offset:704

.LBB11_2773:
	v_mov_b32_e32 v140, v150
	v_mov_b32_e32 v141, v152
	s_lshl_b32 s22, s7, 8
	s_nop 0
	v_add_u32_e32 v144, s22, v140
	v_lshl_add_u32 v142, s6, 8, v141
	v_ashrrev_i32_e32 v145, 31, v144
	v_lshlrev_b64 v[148:149], 11, v[144:145]
	v_ashrrev_i32_e32 v143, 31, v142
	v_lshl_add_u64 v[146:147], s[66:67], 0, v[148:149]
	v_lshlrev_b64 v[142:143], 1, v[142:143]
	v_lshl_add_u64 v[146:147], v[146:147], 0, v[142:143]
	v_lshl_add_u64 v[148:149], s[64:65], 0, v[148:149]
	v_lshl_add_u64 v[148:149], v[148:149], 0, v[142:143]
	v_lshl_add_u32 v249, v144, 11, v142
	global_load_dwordx4 v[170:173], v249, s[66:67]
	global_load_dwordx4 v[174:177], v249, s[64:65]
	global_load_dwordx4 v[178:181], v249, s[66:67] offset:256
	global_load_dwordx4 v[190:193], v249, s[64:65] offset:256
	v_add_u32_e32 v251, 0x8000, v249
	global_load_dwordx4 v[194:197], v251, s[66:67]
	global_load_dwordx4 v[214:217], v251, s[64:65]
	v_add_u32_e32 v250, 0x8000, v249
	global_load_dwordx4 v[218:221], v250, s[66:67] offset:256
	global_load_dwordx4 v[222:225], v250, s[64:65] offset:256
	v_add_u32_e32 v251, 0x10000, v249
	global_load_dwordx4 v[226:229], v251, s[66:67]
	global_load_dwordx4 v[230:233], v251, s[64:65]
	s_waitcnt vmcnt(8)
	v_lshlrev_b32_e32 v162, 16, v170
	v_and_b32_e32 v163, 0xffff0000, v170
	v_lshlrev_b32_e32 v164, 16, v174
	v_and_b32_e32 v165, 0xffff0000, v174
	v_lshlrev_b32_e32 v154, 16, v171
	v_and_b32_e32 v155, 0xffff0000, v171
	v_lshlrev_b32_e32 v158, 16, v175
	v_and_b32_e32 v159, 0xffff0000, v175
	v_pk_add_f32 v[162:163], v[162:163], v[164:165]
	v_pk_add_f32 v[154:155], v[154:155], v[158:159]
	v_lshlrev_b32_e32 v158, 16, v172
	v_and_b32_e32 v159, 0xffff0000, v172
	v_lshlrev_b32_e32 v164, 16, v176
	v_and_b32_e32 v165, 0xffff0000, v176
	v_lshlrev_b32_e32 v156, 16, v173
	v_and_b32_e32 v157, 0xffff0000, v173
	v_lshlrev_b32_e32 v160, 16, v177
	v_and_b32_e32 v161, 0xffff0000, v177
	v_add_u32_e32 v250, 0x10000, v249
	global_load_dwordx4 v[170:173], v250, s[66:67] offset:256
	global_load_dwordx4 v[174:177], v250, s[64:65] offset:256
	v_pk_add_f32 v[158:159], v[158:159], v[164:165]
	v_pk_add_f32 v[156:157], v[156:157], v[160:161]
	v_pk_fma_f32 v[128:129], v[128:129], 0.5, v[154:155] op_sel_hi:[1,0,1]
	v_pk_fma_f32 v[126:127], v[126:127], 0.5, v[162:163] op_sel_hi:[1,0,1]
	v_pk_fma_f32 v[154:155], v[124:125], 0.5, v[156:157] op_sel_hi:[1,0,1]
	v_pk_fma_f32 v[156:157], v[122:123], 0.5, v[158:159] op_sel_hi:[1,0,1]
	v_cvt_pk_bf16_f32 v122, v126, v127
	v_cvt_pk_bf16_f32 v123, v128, v129
	s_nop 0
	v_lshlrev_b32_e32 v124, 16, v122
	v_and_b32_e32 v125, 0xffff0000, v122
	v_lshlrev_b32_e32 v158, 16, v123
	v_and_b32_e32 v159, 0xffff0000, v123
	v_sub_f32_e32 v128, v128, v158
	v_sub_f32_e32 v129, v129, v159
	v_sub_f32_e32 v126, v126, v124
	v_sub_f32_e32 v127, v127, v125
	v_cvt_pk_bf16_f32 v126, v126, v127
	v_cvt_pk_bf16_f32 v127, v128, v129
	s_nop 0
	v_lshlrev_b32_e32 v128, 16, v126
	v_and_b32_e32 v129, 0xffff0000, v126
	v_lshlrev_b32_e32 v160, 16, v127
	v_and_b32_e32 v161, 0xffff0000, v127
	v_pk_add_f32 v[158:159], v[158:159], v[160:161]
	v_pk_add_f32 v[160:161], v[124:125], v[128:129]
	v_cvt_pk_bf16_f32 v124, v156, v157
	v_cvt_pk_bf16_f32 v125, v154, v155
	s_nop 0
	v_lshlrev_b32_e32 v162, 16, v124
	v_lshlrev_b32_e32 v164, 16, v125
	v_and_b32_e32 v163, 0xffff0000, v124
	v_and_b32_e32 v165, 0xffff0000, v125
	v_sub_f32_e32 v129, v154, v164
	v_sub_f32_e32 v128, v156, v162
	v_sub_f32_e32 v141, v155, v165
	v_sub_f32_e32 v145, v157, v163
	v_cvt_pk_bf16_f32 v128, v128, v145
	v_cvt_pk_bf16_f32 v129, v129, v141
	global_store_dwordx4 v[146:147], v[122:125], off
	global_store_dwordx4 v[148:149], v[126:129], off
	v_lshlrev_b32_e32 v154, 16, v128
	v_and_b32_e32 v155, 0xffff0000, v128
	v_mul_f32_e32 v122, v161, v161
	v_mul_f32_e32 v123, v159, v159
	v_pk_add_f32 v[154:155], v[162:163], v[154:155]
	v_fmac_f32_e32 v122, v160, v160
	v_fmac_f32_e32 v123, v158, v158
	v_lshlrev_b32_e32 v156, 16, v129
	v_and_b32_e32 v157, 0xffff0000, v129
	v_add_f32_e32 v122, v122, v123
	v_mul_f32_e32 v123, v155, v155
	v_pk_add_f32 v[156:157], v[164:165], v[156:157]
	v_fmac_f32_e32 v123, v154, v154
	v_add_f32_e32 v122, v122, v123
	v_mul_f32_e32 v123, v157, v157
	v_fmac_f32_e32 v123, v156, v156
	v_add_f32_e32 v141, v123, v122
	s_waitcnt vmcnt(10)
	v_lshlrev_b32_e32 v154, 16, v178
	v_and_b32_e32 v155, 0xffff0000, v178
	v_lshlrev_b32_e32 v156, 16, v190
	v_and_b32_e32 v157, 0xffff0000, v190
	v_lshlrev_b32_e32 v122, 16, v179
	v_and_b32_e32 v123, 0xffff0000, v179
	v_lshlrev_b32_e32 v126, 16, v191
	v_and_b32_e32 v127, 0xffff0000, v191
	v_pk_add_f32 v[154:155], v[154:155], v[156:157]
	v_pk_add_f32 v[122:123], v[122:123], v[126:127]
	v_lshlrev_b32_e32 v126, 16, v180
	v_and_b32_e32 v127, 0xffff0000, v180
	v_lshlrev_b32_e32 v156, 16, v192
	v_and_b32_e32 v157, 0xffff0000, v192
	v_lshlrev_b32_e32 v124, 16, v181
	v_and_b32_e32 v125, 0xffff0000, v181
	v_lshlrev_b32_e32 v128, 16, v193
	v_and_b32_e32 v129, 0xffff0000, v193
	v_add_u32_e32 v251, 0x18000, v249
	global_load_dwordx4 v[178:181], v251, s[66:67]
	global_load_dwordx4 v[190:193], v251, s[64:65]
	v_pk_add_f32 v[126:127], v[126:127], v[156:157]
	v_pk_add_f32 v[124:125], v[124:125], v[128:129]
	v_pk_fma_f32 v[120:121], v[120:121], 0.5, v[122:123] op_sel_hi:[1,0,1]
	v_pk_fma_f32 v[118:119], v[118:119], 0.5, v[154:155] op_sel_hi:[1,0,1]
	v_pk_fma_f32 v[122:123], v[116:117], 0.5, v[124:125] op_sel_hi:[1,0,1]
	v_pk_fma_f32 v[124:125], v[114:115], 0.5, v[126:127] op_sel_hi:[1,0,1]
	v_cvt_pk_bf16_f32 v114, v118, v119
	v_cvt_pk_bf16_f32 v115, v120, v121
	s_nop 0
	v_lshlrev_b32_e32 v116, 16, v114
	v_and_b32_e32 v117, 0xffff0000, v114
	v_lshlrev_b32_e32 v126, 16, v115
	v_and_b32_e32 v127, 0xffff0000, v115
	v_sub_f32_e32 v120, v120, v126
	v_sub_f32_e32 v121, v121, v127
	v_sub_f32_e32 v118, v118, v116
	v_sub_f32_e32 v119, v119, v117
	v_cvt_pk_bf16_f32 v118, v118, v119
	v_cvt_pk_bf16_f32 v119, v120, v121
	s_nop 0
	v_lshlrev_b32_e32 v120, 16, v118
	v_and_b32_e32 v121, 0xffff0000, v118
	v_lshlrev_b32_e32 v128, 16, v119
	v_and_b32_e32 v129, 0xffff0000, v119
	v_pk_add_f32 v[126:127], v[126:127], v[128:129]
	v_pk_add_f32 v[128:129], v[116:117], v[120:121]
	v_cvt_pk_bf16_f32 v116, v124, v125
	v_cvt_pk_bf16_f32 v117, v122, v123
	s_nop 0
	v_lshlrev_b32_e32 v154, 16, v116
	v_and_b32_e32 v155, 0xffff0000, v116
	v_lshlrev_b32_e32 v156, 16, v117
	v_and_b32_e32 v157, 0xffff0000, v117
	v_sub_f32_e32 v121, v122, v156
	v_sub_f32_e32 v122, v123, v157
	v_sub_f32_e32 v120, v124, v154
	v_sub_f32_e32 v123, v125, v155
	v_cvt_pk_bf16_f32 v120, v120, v123
	v_cvt_pk_bf16_f32 v121, v121, v122
	global_store_dwordx4 v[146:147], v[114:117], off offset:256
	global_store_dwordx4 v[148:149], v[118:121], off offset:256
	v_lshlrev_b32_e32 v122, 16, v120
	v_and_b32_e32 v123, 0xffff0000, v120
	v_mul_f32_e32 v114, v129, v129
	v_mul_f32_e32 v115, v127, v127
	v_pk_add_f32 v[122:123], v[154:155], v[122:123]
	v_fmac_f32_e32 v114, v128, v128
	v_fmac_f32_e32 v115, v126, v126
	v_lshlrev_b32_e32 v124, 16, v121
	v_and_b32_e32 v125, 0xffff0000, v121
	v_add_f32_e32 v114, v114, v115
	v_mul_f32_e32 v115, v123, v123
	v_pk_add_f32 v[124:125], v[156:157], v[124:125]
	v_fmac_f32_e32 v115, v122, v122
	v_add_f32_e32 v114, v114, v115
	v_mul_f32_e32 v115, v125, v125
	v_fmac_f32_e32 v115, v124, v124
	v_add_f32_e32 v114, v115, v114
	v_add_f32_e32 v114, v141, v114
	ds_bpermute_b32 v115, v204, v114
	s_waitcnt lgkmcnt(0)
	v_add_f32_e32 v118, v114, v115
	v_add_u32_e32 v114, 16, v144
	v_ashrrev_i32_e32 v115, 31, v114
	v_lshlrev_b64 v[116:117], 11, v[114:115]
	v_lshl_add_u64 v[114:115], s[66:67], 0, v[116:117]
	v_lshl_add_u64 v[114:115], v[114:115], 0, v[142:143]
	v_lshl_add_u64 v[116:117], s[64:65], 0, v[116:117]
	v_lshl_add_u64 v[116:117], v[116:117], 0, v[142:143]
	ds_bpermute_b32 v119, v205, v118
	s_waitcnt vmcnt(12)
	v_lshlrev_b32_e32 v128, 16, v194
	v_and_b32_e32 v129, 0xffff0000, v194
	v_lshlrev_b32_e32 v146, 16, v214
	v_and_b32_e32 v147, 0xffff0000, v214
	v_lshlrev_b32_e32 v120, 16, v195
	v_and_b32_e32 v121, 0xffff0000, v195
	v_lshlrev_b32_e32 v124, 16, v215
	v_and_b32_e32 v125, 0xffff0000, v215
	v_pk_add_f32 v[128:129], v[128:129], v[146:147]
	v_pk_add_f32 v[120:121], v[120:121], v[124:125]
	v_lshlrev_b32_e32 v124, 16, v196
	v_and_b32_e32 v125, 0xffff0000, v196
	v_lshlrev_b32_e32 v146, 16, v216
	v_and_b32_e32 v147, 0xffff0000, v216
	v_lshlrev_b32_e32 v122, 16, v197
	v_and_b32_e32 v123, 0xffff0000, v197
	v_lshlrev_b32_e32 v126, 16, v217
	v_and_b32_e32 v127, 0xffff0000, v217
	v_add_u32_e32 v250, 0x18000, v249
	global_load_dwordx4 v[194:197], v250, s[66:67] offset:256
	global_load_dwordx4 v[214:217], v250, s[64:65] offset:256
	v_pk_add_f32 v[124:125], v[124:125], v[146:147]
	v_pk_add_f32 v[122:123], v[122:123], v[126:127]
	v_pk_fma_f32 v[112:113], v[112:113], 0.5, v[120:121] op_sel_hi:[1,0,1]
	v_pk_fma_f32 v[110:111], v[110:111], 0.5, v[128:129] op_sel_hi:[1,0,1]
	v_pk_fma_f32 v[120:121], v[108:109], 0.5, v[122:123] op_sel_hi:[1,0,1]
	v_pk_fma_f32 v[122:123], v[106:107], 0.5, v[124:125] op_sel_hi:[1,0,1]
	v_cvt_pk_bf16_f32 v106, v110, v111
	v_cvt_pk_bf16_f32 v107, v112, v113
	s_nop 0
	v_lshlrev_b32_e32 v108, 16, v106
	v_and_b32_e32 v109, 0xffff0000, v106
	v_lshlrev_b32_e32 v124, 16, v107
	v_and_b32_e32 v125, 0xffff0000, v107
	v_sub_f32_e32 v112, v112, v124
	v_sub_f32_e32 v113, v113, v125
	v_sub_f32_e32 v110, v110, v108
	v_sub_f32_e32 v111, v111, v109
	v_cvt_pk_bf16_f32 v110, v110, v111
	v_cvt_pk_bf16_f32 v111, v112, v113
	s_nop 0
	v_lshlrev_b32_e32 v112, 16, v110
	v_and_b32_e32 v113, 0xffff0000, v110
	v_lshlrev_b32_e32 v126, 16, v111
	v_and_b32_e32 v127, 0xffff0000, v111
	v_pk_add_f32 v[124:125], v[124:125], v[126:127]
	v_pk_add_f32 v[126:127], v[108:109], v[112:113]
	v_cvt_pk_bf16_f32 v108, v122, v123
	v_cvt_pk_bf16_f32 v109, v120, v121
	s_nop 0
	v_lshlrev_b32_e32 v128, 16, v108
	v_and_b32_e32 v129, 0xffff0000, v108
	v_lshlrev_b32_e32 v146, 16, v109
	v_and_b32_e32 v147, 0xffff0000, v109
	v_sub_f32_e32 v113, v120, v146
	v_sub_f32_e32 v120, v121, v147
	v_sub_f32_e32 v112, v122, v128
	v_sub_f32_e32 v121, v123, v129
	v_cvt_pk_bf16_f32 v112, v112, v121
	v_cvt_pk_bf16_f32 v113, v113, v120
	global_store_dwordx4 v[114:115], v[106:109], off
	global_store_dwordx4 v[116:117], v[110:113], off
	v_lshlrev_b32_e32 v120, 16, v112
	v_and_b32_e32 v121, 0xffff0000, v112
	v_mul_f32_e32 v106, v127, v127
	v_mul_f32_e32 v107, v125, v125
	v_pk_add_f32 v[120:121], v[128:129], v[120:121]
	v_fmac_f32_e32 v106, v126, v126
	v_fmac_f32_e32 v107, v124, v124
	v_lshlrev_b32_e32 v122, 16, v113
	v_and_b32_e32 v123, 0xffff0000, v113
	v_add_f32_e32 v106, v106, v107
	v_mul_f32_e32 v107, v121, v121
	v_pk_add_f32 v[122:123], v[146:147], v[122:123]
	v_fmac_f32_e32 v107, v120, v120
	v_add_f32_e32 v106, v106, v107
	v_mul_f32_e32 v107, v123, v123
	v_fmac_f32_e32 v107, v122, v122
	v_add_f32_e32 v124, v107, v106
	s_waitcnt vmcnt(14)
	v_lshlrev_b32_e32 v120, 16, v218
	v_and_b32_e32 v121, 0xffff0000, v218
	v_lshlrev_b32_e32 v122, 16, v222
	v_and_b32_e32 v123, 0xffff0000, v222
	v_lshlrev_b32_e32 v106, 16, v219
	v_and_b32_e32 v107, 0xffff0000, v219
	v_lshlrev_b32_e32 v110, 16, v223
	v_and_b32_e32 v111, 0xffff0000, v223
	v_pk_add_f32 v[120:121], v[120:121], v[122:123]
	v_pk_add_f32 v[106:107], v[106:107], v[110:111]
	v_lshlrev_b32_e32 v110, 16, v220
	v_and_b32_e32 v111, 0xffff0000, v220
	v_lshlrev_b32_e32 v122, 16, v224
	v_and_b32_e32 v123, 0xffff0000, v224
	v_lshlrev_b32_e32 v108, 16, v221
	v_and_b32_e32 v109, 0xffff0000, v221
	v_lshlrev_b32_e32 v112, 16, v225
	v_and_b32_e32 v113, 0xffff0000, v225
	v_add_u32_e32 v251, 0x40000, v249
	global_load_dwordx4 v[218:221], v251, s[66:67]
	global_load_dwordx4 v[222:225], v251, s[64:65]
	v_pk_add_f32 v[110:111], v[110:111], v[122:123]
	v_pk_add_f32 v[108:109], v[108:109], v[112:113]
	v_pk_fma_f32 v[104:105], v[104:105], 0.5, v[106:107] op_sel_hi:[1,0,1]
	v_pk_fma_f32 v[102:103], v[102:103], 0.5, v[120:121] op_sel_hi:[1,0,1]
	v_pk_fma_f32 v[106:107], v[100:101], 0.5, v[108:109] op_sel_hi:[1,0,1]
	v_pk_fma_f32 v[108:109], v[98:99], 0.5, v[110:111] op_sel_hi:[1,0,1]
	v_cvt_pk_bf16_f32 v98, v102, v103
	v_cvt_pk_bf16_f32 v99, v104, v105
	s_nop 0
	v_lshlrev_b32_e32 v100, 16, v98
	v_and_b32_e32 v101, 0xffff0000, v98
	v_lshlrev_b32_e32 v110, 16, v99
	v_and_b32_e32 v111, 0xffff0000, v99
	v_sub_f32_e32 v104, v104, v110
	v_sub_f32_e32 v105, v105, v111
	v_sub_f32_e32 v102, v102, v100
	v_sub_f32_e32 v103, v103, v101
	v_cvt_pk_bf16_f32 v102, v102, v103
	v_cvt_pk_bf16_f32 v103, v104, v105
	s_nop 0
	v_lshlrev_b32_e32 v104, 16, v102
	v_and_b32_e32 v105, 0xffff0000, v102
	v_lshlrev_b32_e32 v112, 16, v103
	v_and_b32_e32 v113, 0xffff0000, v103
	v_pk_add_f32 v[110:111], v[110:111], v[112:113]
	v_pk_add_f32 v[112:113], v[100:101], v[104:105]
	v_cvt_pk_bf16_f32 v100, v108, v109
	v_cvt_pk_bf16_f32 v101, v106, v107
	s_nop 0
	v_lshlrev_b32_e32 v120, 16, v100
	v_and_b32_e32 v121, 0xffff0000, v100
	v_lshlrev_b32_e32 v122, 16, v101
	v_and_b32_e32 v123, 0xffff0000, v101
	v_sub_f32_e32 v105, v106, v122
	v_sub_f32_e32 v106, v107, v123
	v_sub_f32_e32 v104, v108, v120
	v_sub_f32_e32 v107, v109, v121
	v_cvt_pk_bf16_f32 v104, v104, v107
	v_cvt_pk_bf16_f32 v105, v105, v106
	global_store_dwordx4 v[114:115], v[98:101], off offset:256
	global_store_dwordx4 v[116:117], v[102:105], off offset:256
	v_lshlrev_b32_e32 v106, 16, v104
	v_and_b32_e32 v107, 0xffff0000, v104
	v_mul_f32_e32 v98, v113, v113
	v_mul_f32_e32 v99, v111, v111
	v_pk_add_f32 v[106:107], v[120:121], v[106:107]
	v_fmac_f32_e32 v98, v112, v112
	v_fmac_f32_e32 v99, v110, v110
	v_lshlrev_b32_e32 v108, 16, v105
	v_and_b32_e32 v109, 0xffff0000, v105
	v_add_f32_e32 v98, v98, v99
	v_mul_f32_e32 v99, v107, v107
	v_pk_add_f32 v[108:109], v[122:123], v[108:109]
	v_fmac_f32_e32 v99, v106, v106
	v_add_f32_e32 v98, v98, v99
	v_mul_f32_e32 v99, v109, v109
	v_fmac_f32_e32 v99, v108, v108
	v_add_f32_e32 v98, v99, v98
	v_add_f32_e32 v98, v124, v98
	ds_bpermute_b32 v99, v204, v98
	s_waitcnt lgkmcnt(0)
	v_add_f32_e32 v102, v98, v99
	v_add_u32_e32 v98, 32, v144
	v_ashrrev_i32_e32 v99, 31, v98
	v_lshlrev_b64 v[100:101], 11, v[98:99]
	v_lshl_add_u64 v[98:99], s[66:67], 0, v[100:101]
	v_lshl_add_u64 v[98:99], v[98:99], 0, v[142:143]
	v_lshl_add_u64 v[100:101], s[64:65], 0, v[100:101]
	v_lshl_add_u64 v[100:101], v[100:101], 0, v[142:143]
	ds_bpermute_b32 v103, v205, v102
	s_waitcnt vmcnt(16)
	v_lshlrev_b32_e32 v112, 16, v226
	v_and_b32_e32 v113, 0xffff0000, v226
	v_lshlrev_b32_e32 v114, 16, v230
	v_and_b32_e32 v115, 0xffff0000, v230
	v_lshlrev_b32_e32 v104, 16, v227
	v_and_b32_e32 v105, 0xffff0000, v227
	v_lshlrev_b32_e32 v108, 16, v231
	v_and_b32_e32 v109, 0xffff0000, v231
	v_pk_add_f32 v[112:113], v[112:113], v[114:115]
	v_pk_add_f32 v[104:105], v[104:105], v[108:109]
	v_lshlrev_b32_e32 v108, 16, v228
	v_and_b32_e32 v109, 0xffff0000, v228
	v_lshlrev_b32_e32 v114, 16, v232
	v_and_b32_e32 v115, 0xffff0000, v232
	v_lshlrev_b32_e32 v106, 16, v229
	v_and_b32_e32 v107, 0xffff0000, v229
	v_lshlrev_b32_e32 v110, 16, v233
	v_and_b32_e32 v111, 0xffff0000, v233
	v_add_u32_e32 v250, 0x40000, v249
	global_load_dwordx4 v[226:229], v250, s[66:67] offset:256
	global_load_dwordx4 v[230:233], v250, s[64:65] offset:256
	v_pk_add_f32 v[108:109], v[108:109], v[114:115]
	v_pk_add_f32 v[106:107], v[106:107], v[110:111]
	v_pk_fma_f32 v[96:97], v[96:97], 0.5, v[104:105] op_sel_hi:[1,0,1]
	v_pk_fma_f32 v[94:95], v[94:95], 0.5, v[112:113] op_sel_hi:[1,0,1]
	v_pk_fma_f32 v[104:105], v[92:93], 0.5, v[106:107] op_sel_hi:[1,0,1]
	v_pk_fma_f32 v[106:107], v[90:91], 0.5, v[108:109] op_sel_hi:[1,0,1]
	v_cvt_pk_bf16_f32 v90, v94, v95
	v_cvt_pk_bf16_f32 v91, v96, v97
	s_nop 0
	v_lshlrev_b32_e32 v92, 16, v90
	v_and_b32_e32 v93, 0xffff0000, v90
	v_lshlrev_b32_e32 v108, 16, v91
	v_and_b32_e32 v109, 0xffff0000, v91
	v_sub_f32_e32 v96, v96, v108
	v_sub_f32_e32 v97, v97, v109
	v_sub_f32_e32 v94, v94, v92
	v_sub_f32_e32 v95, v95, v93
	v_cvt_pk_bf16_f32 v94, v94, v95
	v_cvt_pk_bf16_f32 v95, v96, v97
	s_nop 0
	v_lshlrev_b32_e32 v96, 16, v94
	v_and_b32_e32 v97, 0xffff0000, v94
	v_lshlrev_b32_e32 v110, 16, v95
	v_and_b32_e32 v111, 0xffff0000, v95
	v_pk_add_f32 v[108:109], v[108:109], v[110:111]
	v_pk_add_f32 v[110:111], v[92:93], v[96:97]
	v_cvt_pk_bf16_f32 v92, v106, v107
	v_cvt_pk_bf16_f32 v93, v104, v105
	s_nop 0
	v_lshlrev_b32_e32 v112, 16, v92
	v_and_b32_e32 v113, 0xffff0000, v92
	v_lshlrev_b32_e32 v114, 16, v93
	v_and_b32_e32 v115, 0xffff0000, v93
	v_sub_f32_e32 v97, v104, v114
	v_sub_f32_e32 v104, v105, v115
	v_sub_f32_e32 v96, v106, v112
	v_sub_f32_e32 v105, v107, v113
	v_cvt_pk_bf16_f32 v96, v96, v105
	v_cvt_pk_bf16_f32 v97, v97, v104
	global_store_dwordx4 v[98:99], v[90:93], off
	global_store_dwordx4 v[100:101], v[94:97], off
	v_lshlrev_b32_e32 v104, 16, v96
	v_and_b32_e32 v105, 0xffff0000, v96
	v_mul_f32_e32 v90, v111, v111
	v_mul_f32_e32 v91, v109, v109
	v_pk_add_f32 v[104:105], v[112:113], v[104:105]
	v_fmac_f32_e32 v90, v110, v110
	v_fmac_f32_e32 v91, v108, v108
	v_lshlrev_b32_e32 v106, 16, v97
	v_and_b32_e32 v107, 0xffff0000, v97
	v_add_f32_e32 v90, v90, v91
	v_mul_f32_e32 v91, v105, v105
	v_pk_add_f32 v[106:107], v[114:115], v[106:107]
	v_fmac_f32_e32 v91, v104, v104
	v_add_f32_e32 v90, v90, v91
	v_mul_f32_e32 v91, v107, v107
	v_fmac_f32_e32 v91, v106, v106
	v_add_f32_e32 v108, v91, v90
	s_waitcnt vmcnt(18)
	v_lshlrev_b32_e32 v104, 16, v170
	v_and_b32_e32 v105, 0xffff0000, v170
	v_lshlrev_b32_e32 v106, 16, v174
	v_and_b32_e32 v107, 0xffff0000, v174
	v_lshlrev_b32_e32 v90, 16, v171
	v_and_b32_e32 v91, 0xffff0000, v171
	v_lshlrev_b32_e32 v94, 16, v175
	v_and_b32_e32 v95, 0xffff0000, v175
	v_pk_add_f32 v[104:105], v[104:105], v[106:107]
	v_pk_add_f32 v[90:91], v[90:91], v[94:95]
	v_lshlrev_b32_e32 v94, 16, v172
	v_and_b32_e32 v95, 0xffff0000, v172
	v_lshlrev_b32_e32 v106, 16, v176
	v_and_b32_e32 v107, 0xffff0000, v176
	v_lshlrev_b32_e32 v92, 16, v173
	v_and_b32_e32 v93, 0xffff0000, v173
	v_lshlrev_b32_e32 v96, 16, v177
	v_and_b32_e32 v97, 0xffff0000, v177
	v_add_u32_e32 v251, 0x48000, v249
	global_load_dwordx4 v[170:173], v251, s[66:67]
	global_load_dwordx4 v[174:177], v251, s[64:65]
	v_pk_add_f32 v[94:95], v[94:95], v[106:107]
	v_pk_add_f32 v[92:93], v[92:93], v[96:97]
	v_pk_fma_f32 v[88:89], v[88:89], 0.5, v[90:91] op_sel_hi:[1,0,1]
	v_pk_fma_f32 v[86:87], v[86:87], 0.5, v[104:105] op_sel_hi:[1,0,1]
	v_pk_fma_f32 v[90:91], v[84:85], 0.5, v[92:93] op_sel_hi:[1,0,1]
	v_pk_fma_f32 v[92:93], v[82:83], 0.5, v[94:95] op_sel_hi:[1,0,1]
	v_cvt_pk_bf16_f32 v82, v86, v87
	v_cvt_pk_bf16_f32 v83, v88, v89
	s_nop 0
	v_lshlrev_b32_e32 v84, 16, v82
	v_and_b32_e32 v85, 0xffff0000, v82
	v_lshlrev_b32_e32 v94, 16, v83
	v_and_b32_e32 v95, 0xffff0000, v83
	v_sub_f32_e32 v88, v88, v94
	v_sub_f32_e32 v89, v89, v95
	v_sub_f32_e32 v86, v86, v84
	v_sub_f32_e32 v87, v87, v85
	v_cvt_pk_bf16_f32 v86, v86, v87
	v_cvt_pk_bf16_f32 v87, v88, v89
	s_nop 0
	v_lshlrev_b32_e32 v88, 16, v86
	v_and_b32_e32 v89, 0xffff0000, v86
	v_lshlrev_b32_e32 v96, 16, v87
	v_and_b32_e32 v97, 0xffff0000, v87
	v_pk_add_f32 v[94:95], v[94:95], v[96:97]
	v_pk_add_f32 v[96:97], v[84:85], v[88:89]
	v_cvt_pk_bf16_f32 v84, v92, v93
	v_cvt_pk_bf16_f32 v85, v90, v91
	s_nop 0
	v_lshlrev_b32_e32 v104, 16, v84
	v_and_b32_e32 v105, 0xffff0000, v84
	v_lshlrev_b32_e32 v106, 16, v85
	v_and_b32_e32 v107, 0xffff0000, v85
	v_sub_f32_e32 v89, v90, v106
	v_sub_f32_e32 v90, v91, v107
	v_sub_f32_e32 v88, v92, v104
	v_sub_f32_e32 v91, v93, v105
	v_cvt_pk_bf16_f32 v88, v88, v91
	v_cvt_pk_bf16_f32 v89, v89, v90
	global_store_dwordx4 v[98:99], v[82:85], off offset:256
	global_store_dwordx4 v[100:101], v[86:89], off offset:256
	v_lshlrev_b32_e32 v90, 16, v88
	v_and_b32_e32 v91, 0xffff0000, v88
	v_mul_f32_e32 v82, v97, v97
	v_mul_f32_e32 v83, v95, v95
	v_pk_add_f32 v[90:91], v[104:105], v[90:91]
	v_fmac_f32_e32 v82, v96, v96
	v_fmac_f32_e32 v83, v94, v94
	v_lshlrev_b32_e32 v92, 16, v89
	v_and_b32_e32 v93, 0xffff0000, v89
	v_add_f32_e32 v82, v82, v83
	v_mul_f32_e32 v83, v91, v91
	v_pk_add_f32 v[92:93], v[106:107], v[92:93]
	v_fmac_f32_e32 v83, v90, v90
	v_add_f32_e32 v82, v82, v83
	v_mul_f32_e32 v83, v93, v93
	v_fmac_f32_e32 v83, v92, v92
	v_add_f32_e32 v82, v83, v82
	v_add_f32_e32 v82, v108, v82
	ds_bpermute_b32 v83, v204, v82
	s_waitcnt lgkmcnt(0)
	v_add_f32_e32 v86, v82, v83
	v_add_u32_e32 v82, 48, v144
	v_ashrrev_i32_e32 v83, 31, v82
	v_lshlrev_b64 v[84:85], 11, v[82:83]
	v_lshl_add_u64 v[82:83], s[66:67], 0, v[84:85]
	v_lshl_add_u64 v[82:83], v[82:83], 0, v[142:143]
	v_lshl_add_u64 v[84:85], s[64:65], 0, v[84:85]
	v_lshl_add_u64 v[84:85], v[84:85], 0, v[142:143]
	ds_bpermute_b32 v87, v205, v86
	s_waitcnt vmcnt(18)
	v_lshlrev_b32_e32 v96, 16, v178
	v_and_b32_e32 v97, 0xffff0000, v178
	v_lshlrev_b32_e32 v98, 16, v190
	v_and_b32_e32 v99, 0xffff0000, v190
	v_lshlrev_b32_e32 v88, 16, v179
	v_and_b32_e32 v89, 0xffff0000, v179
	v_lshlrev_b32_e32 v92, 16, v191
	v_and_b32_e32 v93, 0xffff0000, v191
	v_pk_add_f32 v[96:97], v[96:97], v[98:99]
	v_pk_add_f32 v[88:89], v[88:89], v[92:93]
	v_lshlrev_b32_e32 v92, 16, v180
	v_and_b32_e32 v93, 0xffff0000, v180
	v_lshlrev_b32_e32 v98, 16, v192
	v_and_b32_e32 v99, 0xffff0000, v192
	v_lshlrev_b32_e32 v90, 16, v181
	v_and_b32_e32 v91, 0xffff0000, v181
	v_lshlrev_b32_e32 v94, 16, v193
	v_and_b32_e32 v95, 0xffff0000, v193
	v_add_u32_e32 v250, 0x48000, v249
	global_load_dwordx4 v[178:181], v250, s[66:67] offset:256
	global_load_dwordx4 v[190:193], v250, s[64:65] offset:256
	v_pk_add_f32 v[92:93], v[92:93], v[98:99]
	v_pk_add_f32 v[90:91], v[90:91], v[94:95]
	v_pk_fma_f32 v[80:81], v[80:81], 0.5, v[88:89] op_sel_hi:[1,0,1]
	v_pk_fma_f32 v[78:79], v[78:79], 0.5, v[96:97] op_sel_hi:[1,0,1]
	v_pk_fma_f32 v[88:89], v[76:77], 0.5, v[90:91] op_sel_hi:[1,0,1]
	v_pk_fma_f32 v[90:91], v[74:75], 0.5, v[92:93] op_sel_hi:[1,0,1]
	v_cvt_pk_bf16_f32 v74, v78, v79
	v_cvt_pk_bf16_f32 v75, v80, v81
	s_nop 0
	v_lshlrev_b32_e32 v76, 16, v74
	v_and_b32_e32 v77, 0xffff0000, v74
	v_lshlrev_b32_e32 v92, 16, v75
	v_and_b32_e32 v93, 0xffff0000, v75
	v_sub_f32_e32 v80, v80, v92
	v_sub_f32_e32 v81, v81, v93
	v_sub_f32_e32 v78, v78, v76
	v_sub_f32_e32 v79, v79, v77
	v_cvt_pk_bf16_f32 v78, v78, v79
	v_cvt_pk_bf16_f32 v79, v80, v81
	s_nop 0
	v_lshlrev_b32_e32 v80, 16, v78
	v_and_b32_e32 v81, 0xffff0000, v78
	v_lshlrev_b32_e32 v94, 16, v79
	v_and_b32_e32 v95, 0xffff0000, v79
	v_pk_add_f32 v[92:93], v[92:93], v[94:95]
	v_pk_add_f32 v[94:95], v[76:77], v[80:81]
	v_cvt_pk_bf16_f32 v76, v90, v91
	v_cvt_pk_bf16_f32 v77, v88, v89
	s_nop 0
	v_lshlrev_b32_e32 v96, 16, v76
	v_and_b32_e32 v97, 0xffff0000, v76
	v_lshlrev_b32_e32 v98, 16, v77
	v_and_b32_e32 v99, 0xffff0000, v77
	v_sub_f32_e32 v81, v88, v98
	v_sub_f32_e32 v88, v89, v99
	v_sub_f32_e32 v80, v90, v96
	v_sub_f32_e32 v89, v91, v97
	v_cvt_pk_bf16_f32 v80, v80, v89
	v_cvt_pk_bf16_f32 v81, v81, v88
	global_store_dwordx4 v[82:83], v[74:77], off
	global_store_dwordx4 v[84:85], v[78:81], off
	v_lshlrev_b32_e32 v88, 16, v80
	v_and_b32_e32 v89, 0xffff0000, v80
	v_mul_f32_e32 v74, v95, v95
	v_mul_f32_e32 v75, v93, v93
	v_pk_add_f32 v[88:89], v[96:97], v[88:89]
	v_fmac_f32_e32 v74, v94, v94
	v_fmac_f32_e32 v75, v92, v92
	v_lshlrev_b32_e32 v90, 16, v81
	v_and_b32_e32 v91, 0xffff0000, v81
	v_add_f32_e32 v74, v74, v75
	v_mul_f32_e32 v75, v89, v89
	v_pk_add_f32 v[90:91], v[98:99], v[90:91]
	v_fmac_f32_e32 v75, v88, v88
	v_add_f32_e32 v74, v74, v75
	v_mul_f32_e32 v75, v91, v91
	v_fmac_f32_e32 v75, v90, v90
	v_add_f32_e32 v92, v75, v74
	s_waitcnt vmcnt(18)
	v_lshlrev_b32_e32 v88, 16, v194
	v_and_b32_e32 v89, 0xffff0000, v194
	v_lshlrev_b32_e32 v90, 16, v214
	v_and_b32_e32 v91, 0xffff0000, v214
	v_lshlrev_b32_e32 v74, 16, v195
	v_and_b32_e32 v75, 0xffff0000, v195
	v_lshlrev_b32_e32 v78, 16, v215
	v_and_b32_e32 v79, 0xffff0000, v215
	v_pk_add_f32 v[88:89], v[88:89], v[90:91]
	v_pk_add_f32 v[74:75], v[74:75], v[78:79]
	v_lshlrev_b32_e32 v78, 16, v196
	v_and_b32_e32 v79, 0xffff0000, v196
	v_lshlrev_b32_e32 v90, 16, v216
	v_and_b32_e32 v91, 0xffff0000, v216
	v_lshlrev_b32_e32 v76, 16, v197
	v_and_b32_e32 v77, 0xffff0000, v197
	v_lshlrev_b32_e32 v80, 16, v217
	v_and_b32_e32 v81, 0xffff0000, v217
	v_add_u32_e32 v251, 0x50000, v249
	global_load_dwordx4 v[194:197], v251, s[66:67]
	global_load_dwordx4 v[214:217], v251, s[64:65]
	v_pk_add_f32 v[78:79], v[78:79], v[90:91]
	v_pk_add_f32 v[76:77], v[76:77], v[80:81]
	v_pk_fma_f32 v[72:73], v[72:73], 0.5, v[74:75] op_sel_hi:[1,0,1]
	v_pk_fma_f32 v[70:71], v[70:71], 0.5, v[88:89] op_sel_hi:[1,0,1]
	v_pk_fma_f32 v[74:75], v[68:69], 0.5, v[76:77] op_sel_hi:[1,0,1]
	v_pk_fma_f32 v[76:77], v[66:67], 0.5, v[78:79] op_sel_hi:[1,0,1]
	v_cvt_pk_bf16_f32 v66, v70, v71
	v_cvt_pk_bf16_f32 v67, v72, v73
	s_nop 0
	v_lshlrev_b32_e32 v68, 16, v66
	v_and_b32_e32 v69, 0xffff0000, v66
	v_lshlrev_b32_e32 v78, 16, v67
	v_and_b32_e32 v79, 0xffff0000, v67
	v_sub_f32_e32 v72, v72, v78
	v_sub_f32_e32 v73, v73, v79
	v_sub_f32_e32 v70, v70, v68
	v_sub_f32_e32 v71, v71, v69
	v_cvt_pk_bf16_f32 v70, v70, v71
	v_cvt_pk_bf16_f32 v71, v72, v73
	s_nop 0
	v_lshlrev_b32_e32 v72, 16, v70
	v_and_b32_e32 v73, 0xffff0000, v70
	v_lshlrev_b32_e32 v80, 16, v71
	v_and_b32_e32 v81, 0xffff0000, v71
	v_pk_add_f32 v[78:79], v[78:79], v[80:81]
	v_pk_add_f32 v[80:81], v[68:69], v[72:73]
	v_cvt_pk_bf16_f32 v68, v76, v77
	v_cvt_pk_bf16_f32 v69, v74, v75
	s_nop 0
	v_lshlrev_b32_e32 v88, 16, v68
	v_and_b32_e32 v89, 0xffff0000, v68
	v_lshlrev_b32_e32 v90, 16, v69
	v_and_b32_e32 v91, 0xffff0000, v69
	v_sub_f32_e32 v73, v74, v90
	v_sub_f32_e32 v74, v75, v91
	v_sub_f32_e32 v72, v76, v88
	v_sub_f32_e32 v75, v77, v89
	v_cvt_pk_bf16_f32 v72, v72, v75
	v_cvt_pk_bf16_f32 v73, v73, v74
	global_store_dwordx4 v[82:83], v[66:69], off offset:256
	global_store_dwordx4 v[84:85], v[70:73], off offset:256
	v_lshlrev_b32_e32 v74, 16, v72
	v_and_b32_e32 v75, 0xffff0000, v72
	v_mul_f32_e32 v66, v81, v81
	v_mul_f32_e32 v67, v79, v79
	v_pk_add_f32 v[74:75], v[88:89], v[74:75]
	v_fmac_f32_e32 v66, v80, v80
	v_fmac_f32_e32 v67, v78, v78
	v_lshlrev_b32_e32 v76, 16, v73
	v_and_b32_e32 v77, 0xffff0000, v73
	v_add_f32_e32 v66, v66, v67
	v_mul_f32_e32 v67, v75, v75
	v_pk_add_f32 v[76:77], v[90:91], v[76:77]
	v_fmac_f32_e32 v67, v74, v74
	v_add_f32_e32 v66, v66, v67
	v_mul_f32_e32 v67, v77, v77
	v_fmac_f32_e32 v67, v76, v76
	v_add_f32_e32 v66, v67, v66
	v_add_f32_e32 v66, v92, v66
	ds_bpermute_b32 v67, v204, v66
	s_waitcnt lgkmcnt(0)
	v_add_f32_e32 v70, v66, v67
	v_add_u32_e32 v66, 0x80, v144
	v_ashrrev_i32_e32 v67, 31, v66
	v_lshlrev_b64 v[68:69], 11, v[66:67]
	v_lshl_add_u64 v[66:67], s[66:67], 0, v[68:69]
	v_lshl_add_u64 v[66:67], v[66:67], 0, v[142:143]
	v_lshl_add_u64 v[68:69], s[64:65], 0, v[68:69]
	v_lshl_add_u64 v[68:69], v[68:69], 0, v[142:143]
	ds_bpermute_b32 v71, v205, v70
	s_waitcnt vmcnt(18)
	v_lshlrev_b32_e32 v80, 16, v218
	v_and_b32_e32 v81, 0xffff0000, v218
	v_lshlrev_b32_e32 v82, 16, v222
	v_and_b32_e32 v83, 0xffff0000, v222
	v_lshlrev_b32_e32 v72, 16, v219
	v_and_b32_e32 v73, 0xffff0000, v219
	v_lshlrev_b32_e32 v76, 16, v223
	v_and_b32_e32 v77, 0xffff0000, v223
	v_pk_add_f32 v[80:81], v[80:81], v[82:83]
	v_pk_add_f32 v[72:73], v[72:73], v[76:77]
	v_lshlrev_b32_e32 v76, 16, v220
	v_and_b32_e32 v77, 0xffff0000, v220
	v_lshlrev_b32_e32 v82, 16, v224
	v_and_b32_e32 v83, 0xffff0000, v224
	v_lshlrev_b32_e32 v74, 16, v221
	v_and_b32_e32 v75, 0xffff0000, v221
	v_lshlrev_b32_e32 v78, 16, v225
	v_and_b32_e32 v79, 0xffff0000, v225
	v_add_u32_e32 v250, 0x50000, v249
	global_load_dwordx4 v[218:221], v250, s[66:67] offset:256
	global_load_dwordx4 v[222:225], v250, s[64:65] offset:256
	v_pk_add_f32 v[76:77], v[76:77], v[82:83]
	v_pk_add_f32 v[74:75], v[74:75], v[78:79]
	v_pk_fma_f32 v[64:65], v[64:65], 0.5, v[72:73] op_sel_hi:[1,0,1]
	v_pk_fma_f32 v[62:63], v[62:63], 0.5, v[80:81] op_sel_hi:[1,0,1]
	v_pk_fma_f32 v[72:73], v[60:61], 0.5, v[74:75] op_sel_hi:[1,0,1]
	v_pk_fma_f32 v[74:75], v[58:59], 0.5, v[76:77] op_sel_hi:[1,0,1]
	v_cvt_pk_bf16_f32 v58, v62, v63
	v_cvt_pk_bf16_f32 v59, v64, v65
	s_nop 0
	v_lshlrev_b32_e32 v60, 16, v58
	v_and_b32_e32 v61, 0xffff0000, v58
	v_lshlrev_b32_e32 v76, 16, v59
	v_and_b32_e32 v77, 0xffff0000, v59
	v_sub_f32_e32 v64, v64, v76
	v_sub_f32_e32 v65, v65, v77
	v_sub_f32_e32 v62, v62, v60
	v_sub_f32_e32 v63, v63, v61
	v_cvt_pk_bf16_f32 v62, v62, v63
	v_cvt_pk_bf16_f32 v63, v64, v65
	s_nop 0
	v_lshlrev_b32_e32 v64, 16, v62
	v_and_b32_e32 v65, 0xffff0000, v62
	v_lshlrev_b32_e32 v78, 16, v63
	v_and_b32_e32 v79, 0xffff0000, v63
	v_pk_add_f32 v[76:77], v[76:77], v[78:79]
	v_pk_add_f32 v[78:79], v[60:61], v[64:65]
	v_cvt_pk_bf16_f32 v60, v74, v75
	v_cvt_pk_bf16_f32 v61, v72, v73
	s_nop 0
	v_lshlrev_b32_e32 v80, 16, v60
	v_and_b32_e32 v81, 0xffff0000, v60
	v_lshlrev_b32_e32 v82, 16, v61
	v_and_b32_e32 v83, 0xffff0000, v61
	v_sub_f32_e32 v65, v72, v82
	v_sub_f32_e32 v72, v73, v83
	v_sub_f32_e32 v64, v74, v80
	v_sub_f32_e32 v73, v75, v81
	v_cvt_pk_bf16_f32 v64, v64, v73
	v_cvt_pk_bf16_f32 v65, v65, v72
	global_store_dwordx4 v[66:67], v[58:61], off
	global_store_dwordx4 v[68:69], v[62:65], off
	v_lshlrev_b32_e32 v72, 16, v64
	v_and_b32_e32 v73, 0xffff0000, v64
	v_mul_f32_e32 v58, v79, v79
	v_mul_f32_e32 v59, v77, v77
	v_pk_add_f32 v[72:73], v[80:81], v[72:73]
	v_fmac_f32_e32 v58, v78, v78
	v_fmac_f32_e32 v59, v76, v76
	v_lshlrev_b32_e32 v74, 16, v65
	v_and_b32_e32 v75, 0xffff0000, v65
	v_add_f32_e32 v58, v58, v59
	v_mul_f32_e32 v59, v73, v73
	v_pk_add_f32 v[74:75], v[82:83], v[74:75]
	v_fmac_f32_e32 v59, v72, v72
	v_add_f32_e32 v58, v58, v59
	v_mul_f32_e32 v59, v75, v75
	v_fmac_f32_e32 v59, v74, v74
	v_add_f32_e32 v76, v59, v58
	s_waitcnt vmcnt(18)
	v_lshlrev_b32_e32 v72, 16, v226
	v_and_b32_e32 v73, 0xffff0000, v226
	v_lshlrev_b32_e32 v74, 16, v230
	v_and_b32_e32 v75, 0xffff0000, v230
	v_lshlrev_b32_e32 v58, 16, v227
	v_and_b32_e32 v59, 0xffff0000, v227
	v_lshlrev_b32_e32 v62, 16, v231
	v_and_b32_e32 v63, 0xffff0000, v231
	v_pk_add_f32 v[72:73], v[72:73], v[74:75]
	v_pk_add_f32 v[58:59], v[58:59], v[62:63]
	v_lshlrev_b32_e32 v62, 16, v228
	v_and_b32_e32 v63, 0xffff0000, v228
	v_lshlrev_b32_e32 v74, 16, v232
	v_and_b32_e32 v75, 0xffff0000, v232
	v_lshlrev_b32_e32 v60, 16, v229
	v_and_b32_e32 v61, 0xffff0000, v229
	v_lshlrev_b32_e32 v64, 16, v233
	v_and_b32_e32 v65, 0xffff0000, v233
	v_add_u32_e32 v251, 0x58000, v249
	global_load_dwordx4 v[226:229], v251, s[66:67]
	global_load_dwordx4 v[230:233], v251, s[64:65]
	v_pk_add_f32 v[62:63], v[62:63], v[74:75]
	v_pk_add_f32 v[60:61], v[60:61], v[64:65]
	v_pk_fma_f32 v[56:57], v[56:57], 0.5, v[58:59] op_sel_hi:[1,0,1]
	v_pk_fma_f32 v[54:55], v[54:55], 0.5, v[72:73] op_sel_hi:[1,0,1]
	v_pk_fma_f32 v[58:59], v[52:53], 0.5, v[60:61] op_sel_hi:[1,0,1]
	v_pk_fma_f32 v[60:61], v[50:51], 0.5, v[62:63] op_sel_hi:[1,0,1]
	v_cvt_pk_bf16_f32 v50, v54, v55
	v_cvt_pk_bf16_f32 v51, v56, v57
	s_nop 0
	v_lshlrev_b32_e32 v52, 16, v50
	v_and_b32_e32 v53, 0xffff0000, v50
	v_lshlrev_b32_e32 v62, 16, v51
	v_and_b32_e32 v63, 0xffff0000, v51
	v_sub_f32_e32 v56, v56, v62
	v_sub_f32_e32 v57, v57, v63
	v_sub_f32_e32 v54, v54, v52
	v_sub_f32_e32 v55, v55, v53
	v_cvt_pk_bf16_f32 v54, v54, v55
	v_cvt_pk_bf16_f32 v55, v56, v57
	s_nop 0
	v_lshlrev_b32_e32 v56, 16, v54
	v_and_b32_e32 v57, 0xffff0000, v54
	v_lshlrev_b32_e32 v64, 16, v55
	v_and_b32_e32 v65, 0xffff0000, v55
	v_pk_add_f32 v[62:63], v[62:63], v[64:65]
	v_pk_add_f32 v[64:65], v[52:53], v[56:57]
	v_cvt_pk_bf16_f32 v52, v60, v61
	v_cvt_pk_bf16_f32 v53, v58, v59
	s_nop 0
	v_lshlrev_b32_e32 v72, 16, v52
	v_and_b32_e32 v73, 0xffff0000, v52
	v_lshlrev_b32_e32 v74, 16, v53
	v_and_b32_e32 v75, 0xffff0000, v53
	v_sub_f32_e32 v57, v58, v74
	v_sub_f32_e32 v58, v59, v75
	v_sub_f32_e32 v56, v60, v72
	v_sub_f32_e32 v59, v61, v73
	v_cvt_pk_bf16_f32 v56, v56, v59
	v_cvt_pk_bf16_f32 v57, v57, v58
	global_store_dwordx4 v[66:67], v[50:53], off offset:256
	global_store_dwordx4 v[68:69], v[54:57], off offset:256
	v_lshlrev_b32_e32 v58, 16, v56
	v_and_b32_e32 v59, 0xffff0000, v56
	v_mul_f32_e32 v50, v65, v65
	v_mul_f32_e32 v51, v63, v63
	v_pk_add_f32 v[58:59], v[72:73], v[58:59]
	v_fmac_f32_e32 v50, v64, v64
	v_fmac_f32_e32 v51, v62, v62
	v_lshlrev_b32_e32 v60, 16, v57
	v_and_b32_e32 v61, 0xffff0000, v57
	v_add_f32_e32 v50, v50, v51
	v_mul_f32_e32 v51, v59, v59
	v_pk_add_f32 v[60:61], v[74:75], v[60:61]
	v_fmac_f32_e32 v51, v58, v58
	v_add_f32_e32 v50, v50, v51
	v_mul_f32_e32 v51, v61, v61
	v_fmac_f32_e32 v51, v60, v60
	v_add_f32_e32 v50, v51, v50
	v_add_f32_e32 v50, v76, v50
	ds_bpermute_b32 v51, v204, v50
	s_waitcnt lgkmcnt(0)
	v_add_f32_e32 v54, v50, v51
	v_add_u32_e32 v50, 0x90, v144
	v_ashrrev_i32_e32 v51, 31, v50
	v_lshlrev_b64 v[52:53], 11, v[50:51]
	v_lshl_add_u64 v[50:51], s[66:67], 0, v[52:53]
	v_lshl_add_u64 v[50:51], v[50:51], 0, v[142:143]
	v_lshl_add_u64 v[52:53], s[64:65], 0, v[52:53]
	v_lshl_add_u64 v[52:53], v[52:53], 0, v[142:143]
	ds_bpermute_b32 v55, v205, v54
	s_waitcnt vmcnt(18)
	v_lshlrev_b32_e32 v64, 16, v170
	v_and_b32_e32 v65, 0xffff0000, v170
	v_lshlrev_b32_e32 v66, 16, v174
	v_and_b32_e32 v67, 0xffff0000, v174
	v_lshlrev_b32_e32 v56, 16, v171
	v_and_b32_e32 v57, 0xffff0000, v171
	v_lshlrev_b32_e32 v60, 16, v175
	v_and_b32_e32 v61, 0xffff0000, v175
	v_pk_add_f32 v[64:65], v[64:65], v[66:67]
	v_pk_add_f32 v[56:57], v[56:57], v[60:61]
	v_lshlrev_b32_e32 v60, 16, v172
	v_and_b32_e32 v61, 0xffff0000, v172
	v_lshlrev_b32_e32 v66, 16, v176
	v_and_b32_e32 v67, 0xffff0000, v176
	v_lshlrev_b32_e32 v58, 16, v173
	v_and_b32_e32 v59, 0xffff0000, v173
	v_lshlrev_b32_e32 v62, 16, v177
	v_and_b32_e32 v63, 0xffff0000, v177
	v_add_u32_e32 v250, 0x58000, v249
	global_load_dwordx4 v[170:173], v250, s[66:67] offset:256
	global_load_dwordx4 v[174:177], v250, s[64:65] offset:256
	v_pk_add_f32 v[60:61], v[60:61], v[66:67]
	v_pk_add_f32 v[58:59], v[58:59], v[62:63]
	v_pk_fma_f32 v[48:49], v[48:49], 0.5, v[56:57] op_sel_hi:[1,0,1]
	v_pk_fma_f32 v[46:47], v[46:47], 0.5, v[64:65] op_sel_hi:[1,0,1]
	v_pk_fma_f32 v[56:57], v[44:45], 0.5, v[58:59] op_sel_hi:[1,0,1]
	v_pk_fma_f32 v[58:59], v[42:43], 0.5, v[60:61] op_sel_hi:[1,0,1]
	v_cvt_pk_bf16_f32 v42, v46, v47
	v_cvt_pk_bf16_f32 v43, v48, v49
	s_nop 0
	v_lshlrev_b32_e32 v44, 16, v42
	v_and_b32_e32 v45, 0xffff0000, v42
	v_lshlrev_b32_e32 v60, 16, v43
	v_and_b32_e32 v61, 0xffff0000, v43
	v_sub_f32_e32 v48, v48, v60
	v_sub_f32_e32 v49, v49, v61
	v_sub_f32_e32 v46, v46, v44
	v_sub_f32_e32 v47, v47, v45
	v_cvt_pk_bf16_f32 v46, v46, v47
	v_cvt_pk_bf16_f32 v47, v48, v49
	s_nop 0
	v_lshlrev_b32_e32 v48, 16, v46
	v_and_b32_e32 v49, 0xffff0000, v46
	v_lshlrev_b32_e32 v62, 16, v47
	v_and_b32_e32 v63, 0xffff0000, v47
	v_pk_add_f32 v[60:61], v[60:61], v[62:63]
	v_pk_add_f32 v[62:63], v[44:45], v[48:49]
	v_cvt_pk_bf16_f32 v44, v58, v59
	v_cvt_pk_bf16_f32 v45, v56, v57
	s_nop 0
	v_lshlrev_b32_e32 v64, 16, v44
	v_and_b32_e32 v65, 0xffff0000, v44
	v_lshlrev_b32_e32 v66, 16, v45
	v_and_b32_e32 v67, 0xffff0000, v45
	v_sub_f32_e32 v49, v56, v66
	v_sub_f32_e32 v56, v57, v67
	v_sub_f32_e32 v48, v58, v64
	v_sub_f32_e32 v57, v59, v65
	v_cvt_pk_bf16_f32 v48, v48, v57
	v_cvt_pk_bf16_f32 v49, v49, v56
	global_store_dwordx4 v[50:51], v[42:45], off
	global_store_dwordx4 v[52:53], v[46:49], off
	v_lshlrev_b32_e32 v56, 16, v48
	v_and_b32_e32 v57, 0xffff0000, v48
	v_mul_f32_e32 v42, v63, v63
	v_mul_f32_e32 v43, v61, v61
	v_pk_add_f32 v[56:57], v[64:65], v[56:57]
	v_fmac_f32_e32 v42, v62, v62
	v_fmac_f32_e32 v43, v60, v60
	v_lshlrev_b32_e32 v58, 16, v49
	v_and_b32_e32 v59, 0xffff0000, v49
	v_add_f32_e32 v42, v42, v43
	v_mul_f32_e32 v43, v57, v57
	v_pk_add_f32 v[58:59], v[66:67], v[58:59]
	v_fmac_f32_e32 v43, v56, v56
	v_add_f32_e32 v42, v42, v43
	v_mul_f32_e32 v43, v59, v59
	v_fmac_f32_e32 v43, v58, v58
	v_add_f32_e32 v60, v43, v42
	s_waitcnt vmcnt(18)
	v_lshlrev_b32_e32 v56, 16, v178
	v_and_b32_e32 v57, 0xffff0000, v178
	v_lshlrev_b32_e32 v58, 16, v190
	v_and_b32_e32 v59, 0xffff0000, v190
	v_lshlrev_b32_e32 v42, 16, v179
	v_and_b32_e32 v43, 0xffff0000, v179
	v_lshlrev_b32_e32 v46, 16, v191
	v_and_b32_e32 v47, 0xffff0000, v191
	v_pk_add_f32 v[56:57], v[56:57], v[58:59]
	v_pk_add_f32 v[42:43], v[42:43], v[46:47]
	v_lshlrev_b32_e32 v46, 16, v180
	v_and_b32_e32 v47, 0xffff0000, v180
	v_lshlrev_b32_e32 v58, 16, v192
	v_and_b32_e32 v59, 0xffff0000, v192
	v_lshlrev_b32_e32 v44, 16, v181
	v_and_b32_e32 v45, 0xffff0000, v181
	v_lshlrev_b32_e32 v48, 16, v193
	v_and_b32_e32 v49, 0xffff0000, v193
	v_pk_add_f32 v[46:47], v[46:47], v[58:59]
	v_pk_add_f32 v[44:45], v[44:45], v[48:49]
	v_pk_fma_f32 v[40:41], v[40:41], 0.5, v[42:43] op_sel_hi:[1,0,1]
	v_pk_fma_f32 v[38:39], v[38:39], 0.5, v[56:57] op_sel_hi:[1,0,1]
	v_pk_fma_f32 v[42:43], v[36:37], 0.5, v[44:45] op_sel_hi:[1,0,1]
	v_pk_fma_f32 v[44:45], v[34:35], 0.5, v[46:47] op_sel_hi:[1,0,1]
	v_cvt_pk_bf16_f32 v34, v38, v39
	v_cvt_pk_bf16_f32 v35, v40, v41
	s_nop 0
	v_lshlrev_b32_e32 v36, 16, v34
	v_and_b32_e32 v37, 0xffff0000, v34
	v_lshlrev_b32_e32 v46, 16, v35
	v_and_b32_e32 v47, 0xffff0000, v35
	v_sub_f32_e32 v40, v40, v46
	v_sub_f32_e32 v41, v41, v47
	v_sub_f32_e32 v38, v38, v36
	v_sub_f32_e32 v39, v39, v37
	v_cvt_pk_bf16_f32 v38, v38, v39
	v_cvt_pk_bf16_f32 v39, v40, v41
	s_nop 0
	v_lshlrev_b32_e32 v40, 16, v38
	v_and_b32_e32 v41, 0xffff0000, v38
	v_lshlrev_b32_e32 v48, 16, v39
	v_and_b32_e32 v49, 0xffff0000, v39
	v_pk_add_f32 v[46:47], v[46:47], v[48:49]
	v_pk_add_f32 v[48:49], v[36:37], v[40:41]
	v_cvt_pk_bf16_f32 v36, v44, v45
	v_cvt_pk_bf16_f32 v37, v42, v43
	s_nop 0
	v_lshlrev_b32_e32 v56, 16, v36
	v_and_b32_e32 v57, 0xffff0000, v36
	v_lshlrev_b32_e32 v58, 16, v37
	v_and_b32_e32 v59, 0xffff0000, v37
	v_sub_f32_e32 v41, v42, v58
	v_sub_f32_e32 v42, v43, v59
	v_sub_f32_e32 v40, v44, v56
	v_sub_f32_e32 v43, v45, v57
	v_cvt_pk_bf16_f32 v40, v40, v43
	v_cvt_pk_bf16_f32 v41, v41, v42
	global_store_dwordx4 v[50:51], v[34:37], off offset:256
	global_store_dwordx4 v[52:53], v[38:41], off offset:256
	v_lshlrev_b32_e32 v42, 16, v40
	v_and_b32_e32 v43, 0xffff0000, v40
	v_mul_f32_e32 v34, v49, v49
	v_mul_f32_e32 v35, v47, v47
	v_pk_add_f32 v[42:43], v[56:57], v[42:43]
	v_fmac_f32_e32 v34, v48, v48
	v_fmac_f32_e32 v35, v46, v46
	v_add_u32_e32 v36, 0xa0, v144
	v_lshlrev_b32_e32 v44, 16, v41
	v_and_b32_e32 v45, 0xffff0000, v41
	v_add_f32_e32 v34, v34, v35
	v_mul_f32_e32 v35, v43, v43
	v_ashrrev_i32_e32 v37, 31, v36
	v_pk_add_f32 v[44:45], v[58:59], v[44:45]
	v_fmac_f32_e32 v35, v42, v42
	v_lshlrev_b64 v[36:37], 11, v[36:37]
	v_add_f32_e32 v34, v34, v35
	v_mul_f32_e32 v35, v45, v45
	v_lshl_add_u64 v[38:39], s[66:67], 0, v[36:37]
	v_fmac_f32_e32 v35, v44, v44
	v_lshl_add_u64 v[44:45], v[38:39], 0, v[142:143]
	v_lshl_add_u64 v[36:37], s[64:65], 0, v[36:37]
	v_lshl_add_u64 v[46:47], v[36:37], 0, v[142:143]
	v_add_f32_e32 v34, v35, v34
	v_add_f32_e32 v34, v60, v34
	ds_bpermute_b32 v35, v204, v34
	s_waitcnt lgkmcnt(0)
	v_add_f32_e32 v34, v34, v35
	ds_bpermute_b32 v35, v205, v34
	s_waitcnt vmcnt(16)
	v_lshlrev_b32_e32 v48, 16, v194
	v_and_b32_e32 v49, 0xffff0000, v194
	v_lshlrev_b32_e32 v50, 16, v214
	v_and_b32_e32 v51, 0xffff0000, v214
	v_lshlrev_b32_e32 v36, 16, v195
	v_and_b32_e32 v37, 0xffff0000, v195
	v_lshlrev_b32_e32 v40, 16, v215
	v_and_b32_e32 v41, 0xffff0000, v215
	v_pk_add_f32 v[48:49], v[48:49], v[50:51]
	v_pk_add_f32 v[36:37], v[36:37], v[40:41]
	v_lshlrev_b32_e32 v40, 16, v196
	v_and_b32_e32 v41, 0xffff0000, v196
	v_lshlrev_b32_e32 v50, 16, v216
	v_and_b32_e32 v51, 0xffff0000, v216
	v_lshlrev_b32_e32 v38, 16, v197
	v_and_b32_e32 v39, 0xffff0000, v197
	v_lshlrev_b32_e32 v42, 16, v217
	v_and_b32_e32 v43, 0xffff0000, v217
	v_pk_add_f32 v[40:41], v[40:41], v[50:51]
	v_pk_add_f32 v[38:39], v[38:39], v[42:43]
	v_pk_fma_f32 v[32:33], v[32:33], 0.5, v[36:37] op_sel_hi:[1,0,1]
	v_pk_fma_f32 v[30:31], v[30:31], 0.5, v[48:49] op_sel_hi:[1,0,1]
	v_pk_fma_f32 v[36:37], v[28:29], 0.5, v[38:39] op_sel_hi:[1,0,1]
	v_pk_fma_f32 v[38:39], v[26:27], 0.5, v[40:41] op_sel_hi:[1,0,1]
	v_cvt_pk_bf16_f32 v26, v30, v31
	v_cvt_pk_bf16_f32 v27, v32, v33
	s_nop 0
	v_lshlrev_b32_e32 v28, 16, v26
	v_and_b32_e32 v29, 0xffff0000, v26
	v_lshlrev_b32_e32 v40, 16, v27
	v_and_b32_e32 v41, 0xffff0000, v27
	v_sub_f32_e32 v32, v32, v40
	v_sub_f32_e32 v33, v33, v41
	v_sub_f32_e32 v30, v30, v28
	v_sub_f32_e32 v31, v31, v29
	v_cvt_pk_bf16_f32 v30, v30, v31
	v_cvt_pk_bf16_f32 v31, v32, v33
	s_nop 0
	v_lshlrev_b32_e32 v32, 16, v30
	v_and_b32_e32 v33, 0xffff0000, v30
	v_lshlrev_b32_e32 v42, 16, v31
	v_and_b32_e32 v43, 0xffff0000, v31
	v_pk_add_f32 v[40:41], v[40:41], v[42:43]
	v_pk_add_f32 v[42:43], v[28:29], v[32:33]
	v_cvt_pk_bf16_f32 v28, v38, v39
	v_cvt_pk_bf16_f32 v29, v36, v37
	s_nop 0
	v_lshlrev_b32_e32 v48, 16, v28
	v_and_b32_e32 v49, 0xffff0000, v28
	v_lshlrev_b32_e32 v50, 16, v29
	v_and_b32_e32 v51, 0xffff0000, v29
	v_sub_f32_e32 v33, v36, v50
	v_sub_f32_e32 v36, v37, v51
	v_sub_f32_e32 v32, v38, v48
	v_sub_f32_e32 v37, v39, v49
	v_cvt_pk_bf16_f32 v32, v32, v37
	v_cvt_pk_bf16_f32 v33, v33, v36
	global_store_dwordx4 v[44:45], v[26:29], off
	global_store_dwordx4 v[46:47], v[30:33], off
	v_lshlrev_b32_e32 v36, 16, v32
	v_and_b32_e32 v37, 0xffff0000, v32
	v_mul_f32_e32 v26, v43, v43
	v_mul_f32_e32 v27, v41, v41
	v_pk_add_f32 v[36:37], v[48:49], v[36:37]
	v_fmac_f32_e32 v26, v42, v42
	v_fmac_f32_e32 v27, v40, v40
	v_lshlrev_b32_e32 v38, 16, v33
	v_and_b32_e32 v39, 0xffff0000, v33
	v_add_f32_e32 v26, v26, v27
	v_mul_f32_e32 v27, v37, v37
	v_pk_add_f32 v[38:39], v[50:51], v[38:39]
	v_fmac_f32_e32 v27, v36, v36
	v_add_f32_e32 v26, v26, v27
	v_mul_f32_e32 v27, v39, v39
	v_fmac_f32_e32 v27, v38, v38
	v_add_f32_e32 v40, v27, v26
	s_waitcnt vmcnt(14)
	v_lshlrev_b32_e32 v36, 16, v218
	v_and_b32_e32 v37, 0xffff0000, v218
	v_lshlrev_b32_e32 v38, 16, v222
	v_and_b32_e32 v39, 0xffff0000, v222
	v_lshlrev_b32_e32 v26, 16, v219
	v_and_b32_e32 v27, 0xffff0000, v219
	v_lshlrev_b32_e32 v30, 16, v223
	v_and_b32_e32 v31, 0xffff0000, v223
	v_pk_add_f32 v[36:37], v[36:37], v[38:39]
	v_pk_add_f32 v[26:27], v[26:27], v[30:31]
	v_lshlrev_b32_e32 v30, 16, v220
	v_and_b32_e32 v31, 0xffff0000, v220
	v_lshlrev_b32_e32 v38, 16, v224
	v_and_b32_e32 v39, 0xffff0000, v224
	v_lshlrev_b32_e32 v28, 16, v221
	v_and_b32_e32 v29, 0xffff0000, v221
	v_lshlrev_b32_e32 v32, 16, v225
	v_and_b32_e32 v33, 0xffff0000, v225
	v_pk_add_f32 v[30:31], v[30:31], v[38:39]
	v_pk_add_f32 v[28:29], v[28:29], v[32:33]
	v_pk_fma_f32 v[24:25], v[24:25], 0.5, v[26:27] op_sel_hi:[1,0,1]
	v_pk_fma_f32 v[22:23], v[22:23], 0.5, v[36:37] op_sel_hi:[1,0,1]
	v_pk_fma_f32 v[26:27], v[20:21], 0.5, v[28:29] op_sel_hi:[1,0,1]
	v_pk_fma_f32 v[28:29], v[18:19], 0.5, v[30:31] op_sel_hi:[1,0,1]
	v_cvt_pk_bf16_f32 v18, v22, v23
	v_cvt_pk_bf16_f32 v19, v24, v25
	s_nop 0
	v_lshlrev_b32_e32 v20, 16, v18
	v_and_b32_e32 v21, 0xffff0000, v18
	v_lshlrev_b32_e32 v30, 16, v19
	v_and_b32_e32 v31, 0xffff0000, v19
	v_sub_f32_e32 v24, v24, v30
	v_sub_f32_e32 v25, v25, v31
	v_sub_f32_e32 v22, v22, v20
	v_sub_f32_e32 v23, v23, v21
	v_cvt_pk_bf16_f32 v22, v22, v23
	v_cvt_pk_bf16_f32 v23, v24, v25
	s_nop 0
	v_lshlrev_b32_e32 v24, 16, v22
	v_and_b32_e32 v25, 0xffff0000, v22
	v_lshlrev_b32_e32 v32, 16, v23
	v_and_b32_e32 v33, 0xffff0000, v23
	v_pk_add_f32 v[30:31], v[30:31], v[32:33]
	v_pk_add_f32 v[32:33], v[20:21], v[24:25]
	v_cvt_pk_bf16_f32 v20, v28, v29
	v_cvt_pk_bf16_f32 v21, v26, v27
	s_nop 0
	v_lshlrev_b32_e32 v36, 16, v20
	v_and_b32_e32 v37, 0xffff0000, v20
	v_lshlrev_b32_e32 v38, 16, v21
	v_and_b32_e32 v39, 0xffff0000, v21
	v_sub_f32_e32 v25, v26, v38
	v_sub_f32_e32 v26, v27, v39
	v_sub_f32_e32 v24, v28, v36
	v_sub_f32_e32 v27, v29, v37
	v_cvt_pk_bf16_f32 v24, v24, v27
	v_cvt_pk_bf16_f32 v25, v25, v26
	global_store_dwordx4 v[44:45], v[18:21], off offset:256
	global_store_dwordx4 v[46:47], v[22:25], off offset:256
	v_lshlrev_b32_e32 v26, 16, v24
	v_and_b32_e32 v27, 0xffff0000, v24
	v_mul_f32_e32 v18, v33, v33
	v_mul_f32_e32 v19, v31, v31
	v_pk_add_f32 v[26:27], v[36:37], v[26:27]
	v_fmac_f32_e32 v18, v32, v32
	v_fmac_f32_e32 v19, v30, v30
	v_lshlrev_b32_e32 v28, 16, v25
	v_and_b32_e32 v29, 0xffff0000, v25
	v_add_f32_e32 v18, v18, v19
	v_mul_f32_e32 v19, v27, v27
	v_pk_add_f32 v[28:29], v[38:39], v[28:29]
	v_fmac_f32_e32 v19, v26, v26
	v_add_f32_e32 v18, v18, v19
	v_mul_f32_e32 v19, v29, v29
	v_fmac_f32_e32 v19, v28, v28
	v_add_f32_e32 v18, v19, v18
	v_add_f32_e32 v18, v40, v18
	ds_bpermute_b32 v19, v204, v18
	s_waitcnt lgkmcnt(0)
	v_add_f32_e32 v30, v18, v19
	v_add_u32_e32 v18, 0xb0, v144
	v_ashrrev_i32_e32 v19, 31, v18
	v_lshlrev_b64 v[18:19], 11, v[18:19]
	v_lshl_add_u64 v[20:21], s[66:67], 0, v[18:19]
	v_lshl_add_u64 v[26:27], v[20:21], 0, v[142:143]
	v_lshl_add_u64 v[18:19], s[64:65], 0, v[18:19]
	v_lshl_add_u64 v[28:29], v[18:19], 0, v[142:143]
	ds_bpermute_b32 v31, v205, v30
	s_waitcnt vmcnt(12)
	v_lshlrev_b32_e32 v32, 16, v226
	v_and_b32_e32 v33, 0xffff0000, v226
	v_lshlrev_b32_e32 v36, 16, v230
	v_and_b32_e32 v37, 0xffff0000, v230
	v_lshlrev_b32_e32 v18, 16, v227
	v_and_b32_e32 v19, 0xffff0000, v227
	v_lshlrev_b32_e32 v22, 16, v231
	v_and_b32_e32 v23, 0xffff0000, v231
	v_pk_add_f32 v[32:33], v[32:33], v[36:37]
	v_pk_add_f32 v[18:19], v[18:19], v[22:23]
	v_lshlrev_b32_e32 v22, 16, v228
	v_and_b32_e32 v23, 0xffff0000, v228
	v_lshlrev_b32_e32 v36, 16, v232
	v_and_b32_e32 v37, 0xffff0000, v232
	v_lshlrev_b32_e32 v20, 16, v229
	v_and_b32_e32 v21, 0xffff0000, v229
	v_lshlrev_b32_e32 v24, 16, v233
	v_and_b32_e32 v25, 0xffff0000, v233
	v_pk_add_f32 v[22:23], v[22:23], v[36:37]
	v_pk_add_f32 v[20:21], v[20:21], v[24:25]
	v_pk_fma_f32 v[16:17], v[16:17], 0.5, v[18:19] op_sel_hi:[1,0,1]
	v_pk_fma_f32 v[14:15], v[14:15], 0.5, v[32:33] op_sel_hi:[1,0,1]
	v_pk_fma_f32 v[18:19], v[12:13], 0.5, v[20:21] op_sel_hi:[1,0,1]
	v_pk_fma_f32 v[20:21], v[10:11], 0.5, v[22:23] op_sel_hi:[1,0,1]
	v_cvt_pk_bf16_f32 v10, v14, v15
	v_cvt_pk_bf16_f32 v11, v16, v17
	s_nop 0
	v_lshlrev_b32_e32 v12, 16, v10
	v_and_b32_e32 v13, 0xffff0000, v10
	v_lshlrev_b32_e32 v22, 16, v11
	v_and_b32_e32 v23, 0xffff0000, v11
	v_sub_f32_e32 v16, v16, v22
	v_sub_f32_e32 v17, v17, v23
	v_sub_f32_e32 v14, v14, v12
	v_sub_f32_e32 v15, v15, v13
	v_cvt_pk_bf16_f32 v14, v14, v15
	v_cvt_pk_bf16_f32 v15, v16, v17
	s_nop 0
	v_lshlrev_b32_e32 v16, 16, v14
	v_and_b32_e32 v17, 0xffff0000, v14
	v_lshlrev_b32_e32 v24, 16, v15
	v_and_b32_e32 v25, 0xffff0000, v15
	v_pk_add_f32 v[22:23], v[22:23], v[24:25]
	v_pk_add_f32 v[24:25], v[12:13], v[16:17]
	v_cvt_pk_bf16_f32 v12, v20, v21
	v_cvt_pk_bf16_f32 v13, v18, v19
	s_nop 0
	v_lshlrev_b32_e32 v32, 16, v12
	v_and_b32_e32 v33, 0xffff0000, v12
	v_lshlrev_b32_e32 v36, 16, v13
	v_and_b32_e32 v37, 0xffff0000, v13
	v_sub_f32_e32 v17, v18, v36
	v_sub_f32_e32 v18, v19, v37
	v_sub_f32_e32 v16, v20, v32
	v_sub_f32_e32 v19, v21, v33
	v_cvt_pk_bf16_f32 v16, v16, v19
	v_cvt_pk_bf16_f32 v17, v17, v18
	global_store_dwordx4 v[26:27], v[10:13], off
	global_store_dwordx4 v[28:29], v[14:17], off
	v_lshlrev_b32_e32 v18, 16, v16
	v_and_b32_e32 v19, 0xffff0000, v16
	v_mul_f32_e32 v10, v25, v25
	v_mul_f32_e32 v11, v23, v23
	v_pk_add_f32 v[18:19], v[32:33], v[18:19]
	v_fmac_f32_e32 v10, v24, v24
	v_fmac_f32_e32 v11, v22, v22
	v_lshlrev_b32_e32 v20, 16, v17
	v_and_b32_e32 v21, 0xffff0000, v17
	v_add_f32_e32 v10, v10, v11
	v_mul_f32_e32 v11, v19, v19
	v_pk_add_f32 v[20:21], v[36:37], v[20:21]
	v_fmac_f32_e32 v11, v18, v18
	v_add_f32_e32 v10, v10, v11
	v_mul_f32_e32 v11, v21, v21
	v_fmac_f32_e32 v11, v20, v20
	v_add_f32_e32 v18, v11, v10
	s_waitcnt vmcnt(10)
	v_lshlrev_b32_e32 v20, 16, v170
	v_and_b32_e32 v21, 0xffff0000, v170
	v_lshlrev_b32_e32 v22, 16, v174
	v_and_b32_e32 v23, 0xffff0000, v174
	v_lshlrev_b32_e32 v10, 16, v171
	v_and_b32_e32 v11, 0xffff0000, v171
	v_lshlrev_b32_e32 v14, 16, v175
	v_and_b32_e32 v15, 0xffff0000, v175
	v_pk_add_f32 v[20:21], v[20:21], v[22:23]
	v_pk_add_f32 v[10:11], v[10:11], v[14:15]
	v_lshlrev_b32_e32 v14, 16, v172
	v_and_b32_e32 v15, 0xffff0000, v172
	v_lshlrev_b32_e32 v22, 16, v176
	v_and_b32_e32 v23, 0xffff0000, v176
	v_lshlrev_b32_e32 v12, 16, v173
	v_and_b32_e32 v13, 0xffff0000, v173
	v_lshlrev_b32_e32 v16, 16, v177
	v_and_b32_e32 v17, 0xffff0000, v177
	v_pk_add_f32 v[14:15], v[14:15], v[22:23]
	v_pk_add_f32 v[12:13], v[12:13], v[16:17]
	v_pk_fma_f32 v[8:9], v[8:9], 0.5, v[10:11] op_sel_hi:[1,0,1]
	v_pk_fma_f32 v[6:7], v[6:7], 0.5, v[20:21] op_sel_hi:[1,0,1]
	v_pk_fma_f32 v[10:11], v[4:5], 0.5, v[12:13] op_sel_hi:[1,0,1]
	v_pk_fma_f32 v[12:13], v[2:3], 0.5, v[14:15] op_sel_hi:[1,0,1]
	v_cvt_pk_bf16_f32 v2, v6, v7
	v_cvt_pk_bf16_f32 v3, v8, v9
	s_nop 0
	v_lshlrev_b32_e32 v4, 16, v2
	v_and_b32_e32 v5, 0xffff0000, v2
	v_lshlrev_b32_e32 v14, 16, v3
	v_and_b32_e32 v15, 0xffff0000, v3
	v_sub_f32_e32 v8, v8, v14
	v_sub_f32_e32 v9, v9, v15
	v_sub_f32_e32 v6, v6, v4
	v_sub_f32_e32 v7, v7, v5
	v_cvt_pk_bf16_f32 v6, v6, v7
	v_cvt_pk_bf16_f32 v7, v8, v9
	s_nop 0
	v_lshlrev_b32_e32 v8, 16, v6
	v_and_b32_e32 v9, 0xffff0000, v6
	v_lshlrev_b32_e32 v16, 16, v7
	v_and_b32_e32 v17, 0xffff0000, v7
	v_pk_add_f32 v[14:15], v[14:15], v[16:17]
	v_pk_add_f32 v[16:17], v[4:5], v[8:9]
	v_cvt_pk_bf16_f32 v4, v12, v13
	v_cvt_pk_bf16_f32 v5, v10, v11
	s_nop 0
	v_lshlrev_b32_e32 v20, 16, v4
	v_and_b32_e32 v21, 0xffff0000, v4
	v_lshlrev_b32_e32 v22, 16, v5
	v_and_b32_e32 v23, 0xffff0000, v5
	v_sub_f32_e32 v9, v10, v22
	v_sub_f32_e32 v10, v11, v23
	v_sub_f32_e32 v8, v12, v20
	v_sub_f32_e32 v11, v13, v21
	v_cvt_pk_bf16_f32 v8, v8, v11
	v_cvt_pk_bf16_f32 v9, v9, v10
	global_store_dwordx4 v[26:27], v[2:5], off offset:256
	global_store_dwordx4 v[28:29], v[6:9], off offset:256
	v_lshlrev_b32_e32 v10, 16, v8
	v_and_b32_e32 v11, 0xffff0000, v8
	v_mul_f32_e32 v2, v17, v17
	v_mul_f32_e32 v3, v15, v15
	v_pk_add_f32 v[10:11], v[20:21], v[10:11]
	v_fmac_f32_e32 v2, v16, v16
	v_fmac_f32_e32 v3, v14, v14
	v_lshlrev_b32_e32 v12, 16, v9
	v_and_b32_e32 v13, 0xffff0000, v9
	v_add_f32_e32 v2, v2, v3
	v_mul_f32_e32 v3, v11, v11
	v_pk_add_f32 v[12:13], v[22:23], v[12:13]
	v_fmac_f32_e32 v3, v10, v10
	v_add_f32_e32 v2, v2, v3
	v_mul_f32_e32 v3, v13, v13
	v_fmac_f32_e32 v3, v12, v12
	v_add_f32_e32 v2, v3, v2
	v_add_f32_e32 v2, v18, v2
	ds_bpermute_b32 v3, v204, v2
	s_waitcnt lgkmcnt(0)
	v_add_f32_e32 v2, v2, v3
	ds_bpermute_b32 v3, v205, v2
	s_and_saveexec_b64 s[24:25], s[10:11]
	s_cbranch_execz .LBB11_2775
	s_ashr_i32 s23, s22, 31
	s_lshl_b64 s[0:1], s[22:23], 2
	s_add_u32 s0, s36, s0
	v_ashrrev_i32_e32 v141, 31, v140
	s_addc_u32 s1, s37, s1
	s_waitcnt lgkmcnt(0)
	v_add_f32_e32 v4, v2, v3
	v_add_f32_e32 v11, v118, v119
	v_lshl_add_u64 v[2:3], v[140:141], 2, s[0:1]
	v_add_f32_e32 v5, v30, v31
	v_add_f32_e32 v6, v34, v35
	v_add_f32_e32 v7, v54, v55
	v_add_f32_e32 v8, v70, v71
	v_add_f32_e32 v9, v86, v87
	v_add_f32_e32 v10, v102, v103
	global_atomic_add_f32 v[2:3], v11, off
	global_atomic_add_f32 v[2:3], v10, off offset:64
	global_atomic_add_f32 v[2:3], v9, off offset:128
	global_atomic_add_f32 v[2:3], v8, off offset:192
	global_atomic_add_f32 v[2:3], v7, off offset:512
	global_atomic_add_f32 v[2:3], v6, off offset:576
	global_atomic_add_f32 v[2:3], v5, off offset:640
	global_atomic_add_f32 v[2:3], v4, off offset:704

	.amdhsa_kernel _ZN2mk8mega_fwdENS_6ParamsE
		.amdhsa_group_segment_fixed_size 0
		.amdhsa_private_segment_fixed_size 0
		.amdhsa_kernarg_size 592
		.amdhsa_user_sgpr_count 2
		.amdhsa_user_sgpr_dispatch_ptr 0
		.amdhsa_user_sgpr_queue_ptr 0
		.amdhsa_user_sgpr_kernarg_segment_ptr 1
		.amdhsa_user_sgpr_dispatch_id 0
		.amdhsa_user_sgpr_kernarg_preload_length 0
		.amdhsa_user_sgpr_kernarg_preload_offset 0
		.amdhsa_user_sgpr_private_segment_size 0
		.amdhsa_uses_dynamic_stack 0
		.amdhsa_enable_private_segment 0
		.amdhsa_system_sgpr_workgroup_id_x 1
		.amdhsa_system_sgpr_workgroup_id_y 0
		.amdhsa_system_sgpr_workgroup_id_z 0
		.amdhsa_system_sgpr_workgroup_info 0
		.amdhsa_system_vgpr_workitem_id 0
		.amdhsa_next_free_vgpr 256
		.amdhsa_next_free_sgpr 100
		.amdhsa_accum_offset 256
		.amdhsa_reserve_vcc 1
		.amdhsa_float_round_mode_32 0
		.amdhsa_float_round_mode_16_64 0
		.amdhsa_float_denorm_mode_32 3
		.amdhsa_float_denorm_mode_16_64 3
		.amdhsa_dx10_clamp 1
		.amdhsa_ieee_mode 1
		.amdhsa_fp16_overflow 0
		.amdhsa_tg_split 0
		.amdhsa_exception_fp_ieee_invalid_op 0
		.amdhsa_exception_fp_denorm_src 0
		.amdhsa_exception_fp_ieee_div_zero 0
		.amdhsa_exception_fp_ieee_overflow 0
		.amdhsa_exception_fp_ieee_underflow 0
		.amdhsa_exception_fp_ieee_inexact 0
		.amdhsa_exception_int_div_zero 0
	.end_amdhsa_kernel

.Lfunc_end11:
	.size	_ZN2mk8mega_fwdENS_6ParamsE, .Lfunc_end11-_ZN2mk8mega_fwdENS_6ParamsE
	.set _ZN2mk8mega_fwdENS_6ParamsE.num_vgpr, 256
	.set _ZN2mk8mega_fwdENS_6ParamsE.num_agpr, 0
	.set _ZN2mk8mega_fwdENS_6ParamsE.numbered_sgpr, 100
	.set _ZN2mk8mega_fwdENS_6ParamsE.num_named_barrier, 0
	.set _ZN2mk8mega_fwdENS_6ParamsE.private_seg_size, 0
	.set _ZN2mk8mega_fwdENS_6ParamsE.uses_vcc, 1
	.set _ZN2mk8mega_fwdENS_6ParamsE.uses_flat_scratch, 0
	.set _ZN2mk8mega_fwdENS_6ParamsE.has_dyn_sized_stack, 0
	.set _ZN2mk8mega_fwdENS_6ParamsE.has_recursion, 0
	.set _ZN2mk8mega_fwdENS_6ParamsE.has_indirect_call, 0

amdhsa.kernels:
  - .agpr_count:     0
    .args:
      - .offset:         0
        .size:           128
        .value_kind:     by_value
    .group_segment_fixed_size: 8704
    .kernarg_segment_align: 8
    .kernarg_segment_size: 128
    .language:       OpenCL C
    .language_version:
      - 2
      - 0
    .max_flat_workgroup_size: 256
    .name:           _ZN2nv6k_gemmENS_5GemmPE
    .private_segment_fixed_size: 0
    .sgpr_count:     53
    .sgpr_spill_count: 0
    .symbol:         _ZN2nv6k_gemmENS_5GemmPE.kd
    .uniform_work_group_size: 1
    .uses_dynamic_stack: false
    .vgpr_count:     88
    .vgpr_spill_count: 0
    .wavefront_size: 64
  - .agpr_count:     0
    .args:
      - .address_space:  global
        .offset:         0
        .size:           8
        .value_kind:     global_buffer
      - .address_space:  global
        .offset:         8
        .size:           8
        .value_kind:     global_buffer
      - .address_space:  global
        .offset:         16
        .size:           8
        .value_kind:     global_buffer
      - .offset:         24
        .size:           4
        .value_kind:     by_value
    .group_segment_fixed_size: 0
    .kernarg_segment_align: 8
    .kernarg_segment_size: 28
    .language:       OpenCL C
    .language_version:
      - 2
      - 0
    .max_flat_workgroup_size: 256
    .name:           _ZN2nv9k_rmsnormEPKfS1_Pfi
    .private_segment_fixed_size: 0
    .sgpr_count:     14
    .sgpr_spill_count: 0
    .symbol:         _ZN2nv9k_rmsnormEPKfS1_Pfi.kd
    .uniform_work_group_size: 1
    .uses_dynamic_stack: false
    .vgpr_count:     31
    .vgpr_spill_count: 0
    .wavefront_size: 64
  - .agpr_count:     0
    .args:
      - .address_space:  global
        .offset:         0
        .size:           8
        .value_kind:     global_buffer
      - .address_space:  global
        .offset:         8
        .size:           8
        .value_kind:     global_buffer
      - .offset:         16
        .size:           8
        .value_kind:     by_value
      - .offset:         24
        .size:           4
        .value_kind:     hidden_block_count_x
      - .offset:         28
        .size:           4
        .value_kind:     hidden_block_count_y
      - .offset:         32
        .size:           4
        .value_kind:     hidden_block_count_z
      - .offset:         36
        .size:           2
        .value_kind:     hidden_group_size_x
      - .offset:         38
        .size:           2
        .value_kind:     hidden_group_size_y
      - .offset:         40
        .size:           2
        .value_kind:     hidden_group_size_z
      - .offset:         42
        .size:           2
        .value_kind:     hidden_remainder_x
      - .offset:         44
        .size:           2
        .value_kind:     hidden_remainder_y
      - .offset:         46
        .size:           2
        .value_kind:     hidden_remainder_z
      - .offset:         64
        .size:           8
        .value_kind:     hidden_global_offset_x
      - .offset:         72
        .size:           8
        .value_kind:     hidden_global_offset_y
      - .offset:         80
        .size:           8
        .value_kind:     hidden_global_offset_z
      - .offset:         88
        .size:           2
        .value_kind:     hidden_grid_dims
    .group_segment_fixed_size: 0
    .kernarg_segment_align: 8
    .kernarg_segment_size: 280
    .language:       OpenCL C
    .language_version:
      - 2
      - 0
    .max_flat_workgroup_size: 1024
    .name:           _ZN2nv6k_copyEPKfPfm
    .private_segment_fixed_size: 0
    .sgpr_count:     18
    .sgpr_spill_count: 0
    .symbol:         _ZN2nv6k_copyEPKfPfm.kd
    .uniform_work_group_size: 1
    .uses_dynamic_stack: false
    .vgpr_count:     7
    .vgpr_spill_count: 0
    .wavefront_size: 64
  - .agpr_count:     0
    .args:
      - .address_space:  global
        .offset:         0
        .size:           8
        .value_kind:     global_buffer
      - .address_space:  global
        .offset:         8
        .size:           8
        .value_kind:     global_buffer
      - .offset:         16
        .size:           8
        .value_kind:     by_value
      - .offset:         24
        .size:           4
        .value_kind:     hidden_block_count_x
      - .offset:         28
        .size:           4
        .value_kind:     hidden_block_count_y
      - .offset:         32
        .size:           4
        .value_kind:     hidden_block_count_z
      - .offset:         36
        .size:           2
        .value_kind:     hidden_group_size_x
      - .offset:         38
        .size:           2
        .value_kind:     hidden_group_size_y
      - .offset:         40
        .size:           2
        .value_kind:     hidden_group_size_z
      - .offset:         42
        .size:           2
        .value_kind:     hidden_remainder_x
      - .offset:         44
        .size:           2
        .value_kind:     hidden_remainder_y
      - .offset:         46
        .size:           2
        .value_kind:     hidden_remainder_z
      - .offset:         64
        .size:           8
        .value_kind:     hidden_global_offset_x
      - .offset:         72
        .size:           8
        .value_kind:     hidden_global_offset_y
      - .offset:         80
        .size:           8
        .value_kind:     hidden_global_offset_z
      - .offset:         88
        .size:           2
        .value_kind:     hidden_grid_dims
    .group_segment_fixed_size: 0
    .kernarg_segment_align: 8
    .kernarg_segment_size: 280
    .language:       OpenCL C
    .language_version:
      - 2
      - 0
    .max_flat_workgroup_size: 1024
    .name:           _ZN2nv8k_swigluEPfPKfm
    .private_segment_fixed_size: 0
    .sgpr_count:     24
    .sgpr_spill_count: 0
    .symbol:         _ZN2nv8k_swigluEPfPKfm.kd
    .uniform_work_group_size: 1
    .uses_dynamic_stack: false
    .vgpr_count:     15
    .vgpr_spill_count: 0
    .wavefront_size: 64
  - .agpr_count:     0
    .args:
      - .address_space:  global
        .offset:         0
        .size:           8
        .value_kind:     global_buffer
      - .offset:         8
        .size:           8
        .value_kind:     by_value
      - .offset:         16
        .size:           4
        .value_kind:     hidden_block_count_x
      - .offset:         20
        .size:           4
        .value_kind:     hidden_block_count_y
      - .offset:         24
        .size:           4
        .value_kind:     hidden_block_count_z
      - .offset:         28
        .size:           2
        .value_kind:     hidden_group_size_x
      - .offset:         30
        .size:           2
        .value_kind:     hidden_group_size_y
      - .offset:         32
        .size:           2
        .value_kind:     hidden_group_size_z
      - .offset:         34
        .size:           2
        .value_kind:     hidden_remainder_x
      - .offset:         36
        .size:           2
        .value_kind:     hidden_remainder_y
      - .offset:         38
        .size:           2
        .value_kind:     hidden_remainder_z
      - .offset:         56
        .size:           8
        .value_kind:     hidden_global_offset_x
      - .offset:         64
        .size:           8
        .value_kind:     hidden_global_offset_y
      - .offset:         72
        .size:           8
        .value_kind:     hidden_global_offset_z
      - .offset:         80
        .size:           2
        .value_kind:     hidden_grid_dims
    .group_segment_fixed_size: 0
    .kernarg_segment_align: 8
    .kernarg_segment_size: 272
    .language:       OpenCL C
    .language_version:
      - 2
      - 0
    .max_flat_workgroup_size: 1024
    .name:           _ZN2nv6k_geluEPfm
    .private_segment_fixed_size: 0
    .sgpr_count:     24
    .sgpr_spill_count: 0
    .symbol:         _ZN2nv6k_geluEPfm.kd
    .uniform_work_group_size: 1
    .uses_dynamic_stack: false
    .vgpr_count:     12
    .vgpr_spill_count: 0
    .wavefront_size: 64
  - .agpr_count:     0
    .args:
      - .address_space:  global
        .offset:         0
        .size:           8
        .value_kind:     global_buffer
      - .address_space:  global
        .offset:         8
        .size:           8
        .value_kind:     global_buffer
      - .address_space:  global
        .offset:         16
        .size:           8
        .value_kind:     global_buffer
      - .address_space:  global
        .offset:         24
        .size:           8
        .value_kind:     global_buffer
      - .offset:         32
        .size:           4
        .value_kind:     by_value
    .group_segment_fixed_size: 0
    .kernarg_segment_align: 8
    .kernarg_segment_size: 36
    .language:       OpenCL C
    .language_version:
      - 2
      - 0
    .max_flat_workgroup_size: 256
    .name:           _ZN2nv13k_layernorm_vEPKfS1_S1_Pfi
    .private_segment_fixed_size: 0
    .sgpr_count:     18
    .sgpr_spill_count: 0
    .symbol:         _ZN2nv13k_layernorm_vEPKfS1_S1_Pfi.kd
    .uniform_work_group_size: 1
    .uses_dynamic_stack: false
    .vgpr_count:     65
    .vgpr_spill_count: 0
    .wavefront_size: 64
  - .agpr_count:     0
    .args:
      - .address_space:  global
        .offset:         0
        .size:           8
        .value_kind:     global_buffer
      - .address_space:  global
        .offset:         8
        .size:           8
        .value_kind:     global_buffer
      - .address_space:  global
        .offset:         16
        .size:           8
        .value_kind:     global_buffer
      - .address_space:  global
        .offset:         24
        .size:           8
        .value_kind:     global_buffer
      - .address_space:  global
        .offset:         32
        .size:           8
        .value_kind:     global_buffer
    .group_segment_fixed_size: 0
    .kernarg_segment_align: 8
    .kernarg_segment_size: 40
    .language:       OpenCL C
    .language_version:
      - 2
      - 0
    .max_flat_workgroup_size: 256
    .name:           _ZN2nv5k_mixEPKfS1_S1_S1_Pf
    .private_segment_fixed_size: 0
    .sgpr_count:     22
    .sgpr_spill_count: 0
    .symbol:         _ZN2nv5k_mixEPKfS1_S1_S1_Pf.kd
    .uniform_work_group_size: 1
    .uses_dynamic_stack: false
    .vgpr_count:     10
    .vgpr_spill_count: 0
    .wavefront_size: 64
  - .agpr_count:     0
    .args:
      - .address_space:  global
        .offset:         0
        .size:           8
        .value_kind:     global_buffer
      - .address_space:  global
        .offset:         8
        .size:           8
        .value_kind:     global_buffer
      - .offset:         16
        .size:           4
        .value_kind:     by_value
      - .offset:         20
        .size:           4
        .value_kind:     by_value
      - .offset:         24
        .size:           4
        .value_kind:     by_value
      - .address_space:  global
        .offset:         32
        .size:           8
        .value_kind:     global_buffer
      - .address_space:  global
        .offset:         40
        .size:           8
        .value_kind:     global_buffer
      - .address_space:  global
        .offset:         48
        .size:           8
        .value_kind:     global_buffer
      - .address_space:  global
        .offset:         56
        .size:           8
        .value_kind:     global_buffer
      - .address_space:  global
        .offset:         64
        .size:           8
        .value_kind:     global_buffer
      - .address_space:  global
        .offset:         72
        .size:           8
        .value_kind:     global_buffer
      - .address_space:  global
        .offset:         80
        .size:           8
        .value_kind:     global_buffer
      - .address_space:  global
        .offset:         88
        .size:           8
        .value_kind:     global_buffer
      - .address_space:  global
        .offset:         96
        .size:           8
        .value_kind:     global_buffer
      - .address_space:  global
        .offset:         104
        .size:           8
        .value_kind:     global_buffer
      - .address_space:  global
        .offset:         112
        .size:           8
        .value_kind:     global_buffer
      - .address_space:  global
        .offset:         120
        .size:           8
        .value_kind:     global_buffer
    .group_segment_fixed_size: 576
    .kernarg_segment_align: 8
    .kernarg_segment_size: 128
    .language:       OpenCL C
    .language_version:
      - 2
      - 0
    .max_flat_workgroup_size: 64
    .name:           _ZN2nv5k_ssmEPKfPfiiiS1_S1_S2_S2_S1_S1_S1_S1_S1_S1_S1_S1_
    .private_segment_fixed_size: 0
    .sgpr_count:     36
    .sgpr_spill_count: 0
    .symbol:         _ZN2nv5k_ssmEPKfPfiiiS1_S1_S2_S2_S1_S1_S1_S1_S1_S1_S1_S1_.kd
    .uniform_work_group_size: 1
    .uses_dynamic_stack: false
    .vgpr_count:     127
    .vgpr_spill_count: 0
    .wavefront_size: 64
  - .agpr_count:     0
    .args:
      - .address_space:  global
        .offset:         0
        .size:           8
        .value_kind:     global_buffer
      - .address_space:  global
        .offset:         8
        .size:           8
        .value_kind:     global_buffer
      - .offset:         16
        .size:           8
        .value_kind:     by_value
      - .offset:         24
        .size:           4
        .value_kind:     hidden_block_count_x
      - .offset:         28
        .size:           4
        .value_kind:     hidden_block_count_y
      - .offset:         32
        .size:           4
        .value_kind:     hidden_block_count_z
      - .offset:         36
        .size:           2
        .value_kind:     hidden_group_size_x
      - .offset:         38
        .size:           2
        .value_kind:     hidden_group_size_y
      - .offset:         40
        .size:           2
        .value_kind:     hidden_group_size_z
      - .offset:         42
        .size:           2
        .value_kind:     hidden_remainder_x
      - .offset:         44
        .size:           2
        .value_kind:     hidden_remainder_y
      - .offset:         46
        .size:           2
        .value_kind:     hidden_remainder_z
      - .offset:         64
        .size:           8
        .value_kind:     hidden_global_offset_x
      - .offset:         72
        .size:           8
        .value_kind:     hidden_global_offset_y
      - .offset:         80
        .size:           8
        .value_kind:     hidden_global_offset_z
      - .offset:         88
        .size:           2
        .value_kind:     hidden_grid_dims
    .group_segment_fixed_size: 0
    .kernarg_segment_align: 8
    .kernarg_segment_size: 280
    .language:       OpenCL C
    .language_version:
      - 2
      - 0
    .max_flat_workgroup_size: 1024
    .name:           _ZN2nv9k_glu_addEPfPKfm
    .private_segment_fixed_size: 0
    .sgpr_count:     24
    .sgpr_spill_count: 0
    .symbol:         _ZN2nv9k_glu_addEPfPKfm.kd
    .uniform_work_group_size: 1
    .uses_dynamic_stack: false
    .vgpr_count:     16
    .vgpr_spill_count: 0
    .wavefront_size: 64
  - .agpr_count:     0
    .args:
      - .address_space:  global
        .offset:         0
        .size:           8
        .value_kind:     global_buffer
      - .offset:         8
        .size:           8
        .value_kind:     by_value
      - .offset:         16
        .size:           4
        .value_kind:     by_value
    .group_segment_fixed_size: 0
    .kernarg_segment_align: 8
    .kernarg_segment_size: 20
    .language:       OpenCL C
    .language_version:
      - 2
      - 0
    .max_flat_workgroup_size: 256
    .name:           _ZN2nv9k_softmaxEPfmf
    .private_segment_fixed_size: 0
    .sgpr_count:     14
    .sgpr_spill_count: 0
    .symbol:         _ZN2nv9k_softmaxEPfmf.kd
    .uniform_work_group_size: 1
    .uses_dynamic_stack: false
    .vgpr_count:     25
    .vgpr_spill_count: 0
    .wavefront_size: 64
  - .agpr_count:     0
    .args:
      - .address_space:  global
        .offset:         0
        .size:           8
        .value_kind:     global_buffer
      - .address_space:  global
        .offset:         8
        .size:           8
        .value_kind:     global_buffer
      - .offset:         16
        .size:           4
        .value_kind:     hidden_block_count_x
      - .offset:         20
        .size:           4
        .value_kind:     hidden_block_count_y
      - .offset:         24
        .size:           4
        .value_kind:     hidden_block_count_z
      - .offset:         28
        .size:           2
        .value_kind:     hidden_group_size_x
      - .offset:         30
        .size:           2
        .value_kind:     hidden_group_size_y
      - .offset:         32
        .size:           2
        .value_kind:     hidden_group_size_z
      - .offset:         34
        .size:           2
        .value_kind:     hidden_remainder_x
      - .offset:         36
        .size:           2
        .value_kind:     hidden_remainder_y
      - .offset:         38
        .size:           2
        .value_kind:     hidden_remainder_z
      - .offset:         56
        .size:           8
        .value_kind:     hidden_global_offset_x
      - .offset:         64
        .size:           8
        .value_kind:     hidden_global_offset_y
      - .offset:         72
        .size:           8
        .value_kind:     hidden_global_offset_z
      - .offset:         80
        .size:           2
        .value_kind:     hidden_grid_dims
    .group_segment_fixed_size: 0
    .kernarg_segment_align: 8
    .kernarg_segment_size: 272
    .language:       OpenCL C
    .language_version:
      - 2
      - 0
    .max_flat_workgroup_size: 1024
    .name:           _ZN2nv6k_snapEPKfPf
    .private_segment_fixed_size: 0
    .sgpr_count:     16
    .sgpr_spill_count: 0
    .symbol:         _ZN2nv6k_snapEPKfPf.kd
    .uniform_work_group_size: 1
    .uses_dynamic_stack: false
    .vgpr_count:     6
    .vgpr_spill_count: 0
    .wavefront_size: 64
  - .agpr_count:     0
    .args:
      - .offset:         0
        .size:           336
        .value_kind:     by_value
      - .offset:         336
        .size:           4
        .value_kind:     hidden_block_count_x
      - .offset:         340
        .size:           4
        .value_kind:     hidden_block_count_y
      - .offset:         344
        .size:           4
        .value_kind:     hidden_block_count_z
      - .offset:         348
        .size:           2
        .value_kind:     hidden_group_size_x
      - .offset:         350
        .size:           2
        .value_kind:     hidden_group_size_y
      - .offset:         352
        .size:           2
        .value_kind:     hidden_group_size_z
      - .offset:         354
        .size:           2
        .value_kind:     hidden_remainder_x
      - .offset:         356
        .size:           2
        .value_kind:     hidden_remainder_y
      - .offset:         358
        .size:           2
        .value_kind:     hidden_remainder_z
      - .offset:         376
        .size:           8
        .value_kind:     hidden_global_offset_x
      - .offset:         384
        .size:           8
        .value_kind:     hidden_global_offset_y
      - .offset:         392
        .size:           8
        .value_kind:     hidden_global_offset_z
      - .offset:         400
        .size:           2
        .value_kind:     hidden_grid_dims
      - .offset:         456
        .size:           4
        .value_kind:     hidden_dynamic_lds_size
    .group_segment_fixed_size: 0
    .kernarg_segment_align: 8
    .kernarg_segment_size: 592
    .language:       OpenCL C
    .language_version:
      - 2
      - 0
    .max_flat_workgroup_size: 512
    .name:           _ZN2mk8mega_fwdENS_6ParamsE
    .private_segment_fixed_size: 0
    .sgpr_count:     106
    .sgpr_spill_count: 453
    .symbol:         _ZN2mk8mega_fwdENS_6ParamsE.kd
    .uniform_work_group_size: 1
    .uses_dynamic_stack: false
    .vgpr_count:     256
    .vgpr_spill_count: 0
    .wavefront_size: 64
  - .agpr_count:     0
    .args:
      - .offset:         0
        .size:           1032
        .value_kind:     by_value
      - .address_space:  global
        .offset:         1032
        .size:           8
        .value_kind:     global_buffer
      - .offset:         1040
        .size:           4
        .value_kind:     hidden_block_count_x
      - .offset:         1044
        .size:           4
        .value_kind:     hidden_block_count_y
      - .offset:         1048
        .size:           4
        .value_kind:     hidden_block_count_z
      - .offset:         1052
        .size:           2
        .value_kind:     hidden_group_size_x
      - .offset:         1054
        .size:           2
        .value_kind:     hidden_group_size_y
      - .offset:         1056
        .size:           2
        .value_kind:     hidden_group_size_z
      - .offset:         1058
        .size:           2
        .value_kind:     hidden_remainder_x
      - .offset:         1060
        .size:           2
        .value_kind:     hidden_remainder_y
      - .offset:         1062
        .size:           2
        .value_kind:     hidden_remainder_z
      - .offset:         1080
        .size:           8
        .value_kind:     hidden_global_offset_x
      - .offset:         1088
        .size:           8
        .value_kind:     hidden_global_offset_y
      - .offset:         1096
        .size:           8
        .value_kind:     hidden_global_offset_z
      - .offset:         1104
        .size:           2
        .value_kind:     hidden_grid_dims
    .group_segment_fixed_size: 5120
    .kernarg_segment_align: 8
    .kernarg_segment_size: 1296
    .language:       OpenCL C
    .language_version:
      - 2
      - 0
    .max_flat_workgroup_size: 256
    .name:           _ZN3dbg5k_cmpENS_6ChkAllEPd
    .private_segment_fixed_size: 0
    .sgpr_count:     24
    .sgpr_spill_count: 0
    .symbol:         _ZN3dbg5k_cmpENS_6ChkAllEPd.kd
    .uniform_work_group_size: 1
    .uses_dynamic_stack: false
    .vgpr_count:     17
    .vgpr_spill_count: 0
    .wavefront_size: 64
  - .agpr_count:     0
    .args:
      - .address_space:  global
        .offset:         0
        .size:           8
        .value_kind:     global_buffer
      - .address_space:  global
        .offset:         8
        .size:           8
        .value_kind:     global_buffer
      - .offset:         16
        .size:           4
        .value_kind:     by_value
    .group_segment_fixed_size: 0
    .kernarg_segment_align: 8
    .kernarg_segment_size: 20
    .language:       OpenCL C
    .language_version:
      - 2
      - 0
    .max_flat_workgroup_size: 1024
    .name:           _ZN3dbg8k_encodeEPKdPii
    .private_segment_fixed_size: 0
    .sgpr_count:     46
    .sgpr_spill_count: 0
    .symbol:         _ZN3dbg8k_encodeEPKdPii.kd
    .uniform_work_group_size: 1
    .uses_dynamic_stack: false
    .vgpr_count:     30
    .vgpr_spill_count: 0
    .wavefront_size: 64
  - .agpr_count:     0
    .args:
      - .address_space:  global
        .offset:         0
        .size:           8
        .value_kind:     global_buffer
      - .address_space:  global
        .offset:         8
        .size:           8
        .value_kind:     global_buffer
      - .offset:         16
        .size:           8
        .value_kind:     by_value
      - .address_space:  global
        .offset:         24
        .size:           8
        .value_kind:     global_buffer
      - .offset:         32
        .size:           4
        .value_kind:     hidden_block_count_x
      - .offset:         36
        .size:           4
        .value_kind:     hidden_block_count_y
      - .offset:         40
        .size:           4
        .value_kind:     hidden_block_count_z
      - .offset:         44
        .size:           2
        .value_kind:     hidden_group_size_x
      - .offset:         46
        .size:           2
        .value_kind:     hidden_group_size_y
      - .offset:         48
        .size:           2
        .value_kind:     hidden_group_size_z
      - .offset:         50
        .size:           2
        .value_kind:     hidden_remainder_x
      - .offset:         52
        .size:           2
        .value_kind:     hidden_remainder_y
      - .offset:         54
        .size:           2
        .value_kind:     hidden_remainder_z
      - .offset:         72
        .size:           8
        .value_kind:     hidden_global_offset_x
      - .offset:         80
        .size:           8
        .value_kind:     hidden_global_offset_y
      - .offset:         88
        .size:           8
        .value_kind:     hidden_global_offset_z
      - .offset:         96
        .size:           2
        .value_kind:     hidden_grid_dims
    .group_segment_fixed_size: 0
    .kernarg_segment_align: 8
    .kernarg_segment_size: 288
    .language:       OpenCL C
    .language_version:
      - 2
      - 0
    .max_flat_workgroup_size: 1024
    .name:           _ZN3dbg7k_applyEPfPKfmPKi
    .private_segment_fixed_size: 0
    .sgpr_count:     23
    .sgpr_spill_count: 0
    .symbol:         _ZN3dbg7k_applyEPfPKfmPKi.kd
    .uniform_work_group_size: 1
    .uses_dynamic_stack: false
    .vgpr_count:     10
    .vgpr_spill_count: 0
    .wavefront_size: 64
